# speedup vs baseline: 1.0095x; 1.0095x over previous
; DI int my_tid() { int t = threadIdx.x; asm volatile("" : "+v"(t)); return t; }
; DI unsigned fkey(float f) { const unsigned u = __float_as_uint(f); return (u & 0x80000000u) ? ~u : (u | 0x80000000u); }
; #define TK_PREFETCH(t_, p_) do { const int tk0_ = ((t_) >> 3) * 64, hp_ = ((t_) & 7) * 2 + (p_); \
;         _Pragma("unroll") for (int i_ = 0; i_ < 4; ++i_) { const int c_ = tid + 256 * i_; pre[i_] = *(const u32x4*)(qp + (size_t)(tk0_ + (c_ >> 4)) * 2048 + hp_ * 128 + (c_ & 15) * 8); } } while (0)
; DI void topk_phase(unsigned char* smem_, const bf16_t* __restrict__ qp, const bf16_t* __restrict__ keys, int* __restrict__ eidx, float* __restrict__ gate) {
;     const int tid5 = my_tid(), half = __builtin_amdgcn_readfirstlane(tid5 >> 8), tid = tid5 & 255, lane = tid & 63, wid = __builtin_amdgcn_readfirstlane((tid5 >> 6) & 3), l31 = lane & 31, hi = lane >> 5;
;     unsigned char* smem = smem_ + half * 69632;
;     const int G = gridDim.x * 2, bx = blockIdx.x * 2 + half;
;     constexpr int LDA = 136, LDS_ = 132, NT = 512 * 8;
;     bf16_t* As = (bf16_t*)smem;
;     float* S = (float*)(smem + 17408);
;     float* SV = (float*)(smem + 53248);
;     int* SI = (int*)(smem + 53248 + 8192);
;     const int row = tid >> 2, q = tid & 3;
;     int cur_h = -1;
;     bf16x8 kf[2][8];
;     u32x4 pre[4];
;     ...
;     TK_PREFETCH(bx, 0);
;     for (int t = bx; t < NT; t += G) {
;     ...
;     constexpr unsigned KT[13] = {0x03020100u, 0x07060504u, 0x0b0a0908u, 0x0f0e0d0cu, 0x13121110u, 0x17161514u, 0x23222120u, 0x32313024u, 0x42414033u, 0x61605150u, 0x90807170u, 0xd0c0b0a0u, 0x0000f0e0u};
;     unsigned c16[16];
; #pragma unroll
;     for (int i = 0; i < 13; ++i) {
;         const unsigned ab = (KT[i] >> (8 * q)) & 255u;
;         const float c = SV[row * 32 + (ab >> 4)] + SV[row * 32 + 16 + (ab & 15u)];
;         c16[i] = (fkey(c) & ~255u) | (255u - ab);
.LBB0_51:
	s_andn2_b64 vcc, exec, s[0:1]
	s_cbranch_vccnz .LBB0_84
	v_mov_b32_e32 v0, v192
	v_readlane_b32 s2, v251, 57
	v_readfirstlane_b32 s1, v0
	s_ashr_i32 s0, s1, 8
	s_add_i32 s18, s0, s2
	s_cmpk_gt_i32 s18, 0xfff
	s_cbranch_scc1 .LBB0_83
	s_mul_i32 s2, s0, 0x11000
	s_add_i32 s19, s2, 0
	s_lshl_b32 s2, s18, 9
	v_lshlrev_b32_e32 v1, 3, v0
	s_and_b32 s2, s2, 0xe00
	v_and_b32_e32 v2, 0x78, v1
	s_add_u32 s2, s86, s2
	s_addc_u32 s3, s87, 0
	v_lshlrev_b32_e32 v128, 1, v2
	v_bfe_u32 v165, v0, 4, 4
	v_lshl_add_u64 v[4:5], s[2:3], 0, v[128:129]
	s_lshl_b32 s2, s18, 3
	v_or_b32_e32 v168, 48, v165
	s_andn2_b32 s2, s2, 63
	v_or_b32_e32 v167, 32, v165
	v_or_b32_e32 v6, s2, v168
	v_ashrrev_i32_e32 v7, 31, v6
	v_or_b32_e32 v8, s2, v167
	v_lshlrev_b64 v[6:7], 12, v[6:7]
	v_ashrrev_i32_e32 v9, 31, v8
	v_or_b32_e32 v166, 16, v165
	v_lshl_add_u64 v[6:7], v[4:5], 0, v[6:7]
	v_lshlrev_b64 v[8:9], 12, v[8:9]
	v_lshl_add_u64 v[8:9], v[4:5], 0, v[8:9]
	global_load_dwordx4 v[108:111], v[6:7], off
	global_load_dwordx4 v[104:107], v[8:9], off
	v_or_b32_e32 v6, s2, v166
	v_ashrrev_i32_e32 v7, 31, v6
	v_or_b32_e32 v8, s2, v165
	v_lshlrev_b64 v[6:7], 12, v[6:7]
	v_ashrrev_i32_e32 v9, 31, v8
	v_lshl_add_u64 v[6:7], v[4:5], 0, v[6:7]
	v_lshlrev_b64 v[8:9], 12, v[8:9]
	v_lshl_add_u64 v[4:5], v[4:5], 0, v[8:9]
	global_load_dwordx4 v[100:103], v[6:7], off
	global_load_dwordx4 v[96:99], v[4:5], off
	v_bfe_u32 v164, v0, 2, 6
	v_and_b32_e32 v3, 3, v0
	v_and_b32_e32 v10, 31, v0
	v_lshrrev_b32_e32 v0, 1, v0
	v_readlane_b32 s2, v252, 41
	s_bfe_u32 s1, s1, 0x20006
	v_and_b32_e32 v0, 16, v0
	v_mov_b32_e32 v1, v129
	v_readlane_b32 s3, v252, 42
	v_add_u32_e32 v4, s19, v0
	v_mov_b32_e32 v5, s19
	v_lshl_add_u64 v[112:113], s[2:3], 0, v[0:1]
	s_lshl_b32 s2, s1, 7
	s_add_i32 s2, s19, s2
	v_add_u32_e32 v0, s2, v0
	s_movk_i32 s2, 0x210
	v_cmp_lt_i32_e32 vcc, v204, v200
	v_mad_u32_u24 v169, v164, s2, v5
	v_lshl_or_b32 v176, s1, 5, v10
	v_cndmask_b32_e32 v5, v197, v204, vcc
	v_cmp_lt_i32_e32 vcc, v203, v200
	v_lshlrev_b32_e32 v172, 2, v5
	s_mov_b32 s1, 0x3020100
	v_cndmask_b32_e32 v5, v197, v203, vcc
	v_lshlrev_b32_e32 v173, 2, v5
	v_lshlrev_b32_e32 v5, 3, v3
	v_bfe_u32 v185, s1, v5, 2
	s_mov_b32 s1, 0x7060504
	s_movk_i32 s2, 0xfe70
	v_bfe_u32 v187, s1, v5, 3
	s_mov_b32 s1, 0xb0a0908
	v_lshlrev_b32_e32 v170, 5, v3
	v_lshl_add_u32 v171, v3, 7, v169
	v_mad_i32_i24 v175, v164, s2, v169
	v_cmp_lt_u32_e64 s[2:3], 1, v3
	v_cmp_eq_u32_e64 s[4:5], 0, v3
	v_cmp_eq_u32_e64 s[6:7], 1, v3
	v_cmp_eq_u32_e64 s[8:9], 2, v3
	v_cmp_eq_u32_e64 s[10:11], 3, v3
	v_lshlrev_b32_e32 v253, 4, v3
	v_lshrrev_b32_e64 v3, v5, s1
	s_mov_b32 s1, 0xf0e0d0c
	v_bfe_u32 v191, s1, v5, 4
	s_mov_b32 s1, 0x13121110
	v_and_b32_e32 v189, 11, v3
	v_lshrrev_b32_e64 v3, v5, s1
	v_and_b32_e32 v212, 19, v3
	v_bfe_u32 v3, s1, v5, 2
	s_mov_b32 s1, 0x17161514
	v_lshl_add_u32 v213, v3, 2, v175
	v_lshrrev_b32_e64 v3, v5, s1
	v_and_b32_e32 v214, 23, v3
	v_bfe_u32 v3, s1, v5, 3
	s_mov_b32 s1, 0x23222120
	v_lshl_add_u32 v215, v3, 2, v175
	v_lshrrev_b32_e64 v3, v5, s1
	v_and_b32_e32 v216, 35, v3
	v_bfe_u32 v3, s1, v5, 2
	s_mov_b32 s1, 0x32313024
	v_lshl_add_u32 v217, v3, 2, v175
	v_lshrrev_b32_e64 v3, v5, s1
	v_and_b32_e32 v218, 55, v3
	v_lshrrev_b32_e32 v3, 2, v3
	v_and_b32_e32 v3, 12, v3
	v_add_u32_e32 v219, v175, v3
	v_bfe_u32 v3, s1, v5, 3
	s_mov_b32 s1, 0x42414033
	v_lshl_add_u32 v220, v3, 2, v175
	v_lshrrev_b32_e64 v3, v5, s1
	v_and_b32_e32 v221, 0x73, v3
	v_lshrrev_b32_e32 v3, 2, v221
	v_add_u32_e32 v222, v175, v3
	v_bfe_u32 v3, s1, v5, 2
	s_mov_b32 s1, 0x61605150
	v_lshl_add_u32 v223, v3, 2, v175
	v_lshrrev_b32_e64 v3, v5, s1
	v_and_b32_e32 v224, 0x71, v3
	v_lshrrev_b32_e32 v3, 2, v224
	v_add_u32_e32 v225, v175, v3
	v_bfe_u32 v3, s1, v5, 1
	s_mov_b32 s1, 0x90807170
	v_lshl_add_u32 v226, v3, 2, v175
	v_lshrrev_b32_e64 v3, v5, s1
	v_and_b32_e32 v227, 0xf1, v3
	v_lshrrev_b32_e32 v3, 2, v227
	v_add_u32_e32 v228, v175, v3
	v_bfe_u32 v3, s1, v5, 1
	s_mov_b32 s1, 0xd0c0b0a0
	v_lshl_add_u32 v229, v3, 2, v175
	v_lshrrev_b32_e64 v3, v5, s1
	s_mov_b32 s1, 0xf0e0
	v_lshrrev_b32_e64 v5, v5, s1
	v_readlane_b32 s1, v251, 49
	v_and_b32_e32 v230, 0xf0, v3
	v_and_b32_e32 v231, 0xf0, v5
	s_add_i32 s1, s1, s0
	v_add_u32_e32 v1, s19, v128
	v_mul_u32_u24_e32 v6, 0x110, v165
	v_mul_u32_u24_e32 v7, 0x110, v10
	v_mul_u32_u24_e32 v8, 0x210, v10
	v_lshrrev_b32_e32 v3, 2, v230
	v_lshrrev_b32_e32 v5, 2, v231
	s_lshl_b32 s21, s1, 8
	s_lshl_b32 s0, s0, 3
	v_readlane_b32 s1, v251, 52
	s_mov_b32 s20, -1
	v_lshlrev_b32_e32 v174, 5, v164
	v_lshl_add_u64 v[114:115], s[86:87], 0, v[128:129]
	v_or_b32_e32 v177, 4, v170
	v_or_b32_e32 v178, 8, v170
	v_or_b32_e32 v179, 12, v170
	v_or_b32_e32 v180, 16, v170
	v_or_b32_e32 v181, 20, v170
	v_or_b32_e32 v182, 24, v170
	v_or_b32_e32 v183, 28, v170
	v_lshl_add_u32 v184, v164, 7, s19
	v_add_u32_e32 v253, v253, v184
	v_lshl_add_u32 v186, v185, 2, v175
	v_lshl_add_u32 v188, v187, 2, v175
	v_lshl_add_u32 v190, v189, 2, v175
	v_lshl_add_u32 v211, v191, 2, v175
	s_add_i32 s22, s1, s0
	v_lshlrev_b32_e32 v128, 1, v2
	v_add_u32_e32 v232, v175, v3
	v_add_u32_e32 v233, v175, v5
	v_add_u32_e32 v234, v1, v6
	v_add_u32_e32 v235, v4, v7
	v_add_u32_e32 v236, v0, v8
	s_branch .LBB0_55

; #define MFMA32(a, b, c) __builtin_amdgcn_mfma_f32_32x32x16_bf16((a), (b), (c), 0, 0, 0)
; #define TK_PREFETCH(t_, p_) do { const int tk0_ = ((t_) >> 3) * 64, hp_ = ((t_) & 7) * 2 + (p_); \
;         _Pragma("unroll") for (int i_ = 0; i_ < 4; ++i_) { const int c_ = tid + 256 * i_; pre[i_] = *(const u32x4*)(qp + (size_t)(tk0_ + (c_ >> 4)) * 2048 + hp_ * 128 + (c_ & 15) * 8); } } while (0)
; DI void topk_phase(unsigned char* smem_, const bf16_t* __restrict__ qp, const bf16_t* __restrict__ keys, int* __restrict__ eidx, float* __restrict__ gate) {
;     ...
;         for (int i = 0; i < 4; ++i) { const int c = tid + 256 * i; *(u32x4*)(As + (c >> 4) * LDA + (c & 15) * 8) = pre[i]; }
;         __syncthreads();
;         f32x16 acc[2];
; #pragma unroll
;         for (int i = 0; i < 16; ++i) { acc[0][i] = 0.f; acc[1][i] = 0.f; }
; #pragma unroll
;         for (int ks = 0; ks < 8; ++ks) {
; #pragma unroll
;             for (int th = 0; th < 2; ++th) { const bf16x8 qf = *(const bf16x8*)(As + (32 * th + l31) * LDA + ks * 16 + hi * 8); acc[th] = MFMA32(kf[p][ks], qf, acc[th]); }
;         }
; #pragma unroll
;         for (int th = 0; th < 2; ++th)
; #pragma unroll
;             for (int g = 0; g < 4; ++g) { f32x4 o; o.x = acc[th][4 * g]; o.y = acc[th][4 * g + 1]; o.z = acc[th][4 * g + 2]; o.w = acc[th][4 * g + 3]; *(f32x4*)(S + (32 * th + l31) * LDS_ + 32 * wid + 8 * g + 4 * hi) = o; }
;         __syncthreads();
;         if (p == 0) TK_PREFETCH(t, 1); else if (t + G < NT) TK_PREFETCH(t + G, 0);
;         unsigned v[32];
; #pragma unroll
;         for (int i = 0; i < 8; ++i) {
;             const f32x4 sv4 = *(const f32x4*)(S + row * LDS_ + 32 * q + 4 * i);
.LBB0_57:
	s_waitcnt vmcnt(0)
	ds_write_b128 v234, v[96:99]
	ds_write_b128 v234, v[100:103] offset:4352
	ds_write_b128 v234, v[104:107] offset:8704
	ds_write_b128 v234, v[108:111] offset:13056
	s_waitcnt lgkmcnt(0)
	s_barrier
	ds_read_b128 v[0:3], v235
	ds_read_b128 v[96:99], v235 offset:32
	s_waitcnt lgkmcnt(1)
	v_mfma_f32_32x32x16_bf16 v[16:31], v[32:35], v[0:3], 0
	ds_read_b128 v[0:3], v235 offset:8704
	s_and_b32 s24, s22, 0xffffffc0
	s_lshl_b32 s0, s0, 1
	s_add_u32 s0, s86, s0
	s_addc_u32 s1, s87, 0
	s_waitcnt lgkmcnt(1)
	v_mfma_f32_32x32x16_bf16 v[16:31], v[36:39], v[96:99], v[16:31]
	ds_read_b128 v[96:99], v235 offset:8736
	s_waitcnt lgkmcnt(1)
	v_mfma_f32_32x32x16_bf16 v[0:15], v[32:35], v[0:3], 0
	s_waitcnt lgkmcnt(0)
	v_mfma_f32_32x32x16_bf16 v[0:15], v[36:39], v[96:99], v[0:15]
	ds_read_b128 v[96:99], v235 offset:64
	s_waitcnt lgkmcnt(0)
	v_mfma_f32_32x32x16_bf16 v[16:31], v[40:43], v[96:99], v[16:31]
	ds_read_b128 v[96:99], v235 offset:8768
	s_waitcnt lgkmcnt(0)
	v_mfma_f32_32x32x16_bf16 v[0:15], v[40:43], v[96:99], v[0:15]
	ds_read_b128 v[96:99], v235 offset:96
	s_waitcnt lgkmcnt(0)
	v_mfma_f32_32x32x16_bf16 v[16:31], v[44:47], v[96:99], v[16:31]
	ds_read_b128 v[96:99], v235 offset:8800
	s_waitcnt lgkmcnt(0)
	v_mfma_f32_32x32x16_bf16 v[0:15], v[44:47], v[96:99], v[0:15]
	ds_read_b128 v[96:99], v235 offset:128
	s_waitcnt lgkmcnt(0)
	v_mfma_f32_32x32x16_bf16 v[16:31], v[48:51], v[96:99], v[16:31]
	ds_read_b128 v[96:99], v235 offset:8832
	s_waitcnt lgkmcnt(0)
	v_mfma_f32_32x32x16_bf16 v[0:15], v[48:51], v[96:99], v[0:15]
	ds_read_b128 v[96:99], v235 offset:160
	s_waitcnt lgkmcnt(0)
	v_mfma_f32_32x32x16_bf16 v[16:31], v[52:55], v[96:99], v[16:31]
	ds_read_b128 v[96:99], v235 offset:8864
	s_waitcnt lgkmcnt(0)
	v_mfma_f32_32x32x16_bf16 v[0:15], v[52:55], v[96:99], v[0:15]
	ds_read_b128 v[96:99], v235 offset:192
	s_waitcnt lgkmcnt(0)
	v_mfma_f32_32x32x16_bf16 v[16:31], v[56:59], v[96:99], v[16:31]
	ds_read_b128 v[96:99], v235 offset:8896
	s_waitcnt lgkmcnt(0)
	v_mfma_f32_32x32x16_bf16 v[0:15], v[56:59], v[96:99], v[0:15]
	ds_read_b128 v[96:99], v235 offset:224
	s_waitcnt lgkmcnt(0)
	v_mfma_f32_32x32x16_bf16 v[16:31], v[60:63], v[96:99], v[16:31]
	ds_read_b128 v[96:99], v235 offset:8928
	s_nop 10
	ds_write_b128 v236, v[16:19] offset:17408
	ds_write_b128 v236, v[20:23] offset:17440
	ds_write_b128 v236, v[24:27] offset:17472
	ds_write_b128 v236, v[28:31] offset:17504
	s_waitcnt lgkmcnt(4)
	v_mfma_f32_32x32x16_bf16 v[0:15], v[60:63], v[96:99], v[0:15]
	s_nop 11
	ds_write_b128 v236, v[0:3] offset:34304
	ds_write_b128 v236, v[4:7] offset:34336
	ds_write_b128 v236, v[8:11] offset:34368
	ds_write_b128 v236, v[12:15] offset:34400
	v_or_b32_e32 v0, s24, v165
	v_ashrrev_i32_e32 v1, 31, v0
	v_lshlrev_b64 v[0:1], 12, v[0:1]
	v_lshl_add_u64 v[0:1], s[0:1], 0, v[0:1]
	v_lshl_add_u64 v[0:1], v[0:1], 0, v[128:129]
	s_waitcnt lgkmcnt(0)
	s_barrier
	global_load_dwordx4 v[96:99], v[0:1], off offset:256
	v_or_b32_e32 v0, s24, v166
	v_ashrrev_i32_e32 v1, 31, v0
	v_lshlrev_b64 v[0:1], 12, v[0:1]
	v_lshl_add_u64 v[0:1], s[0:1], 0, v[0:1]
	v_lshl_add_u64 v[0:1], v[0:1], 0, v[128:129]
	global_load_dwordx4 v[100:103], v[0:1], off offset:256
	v_or_b32_e32 v0, s24, v167
	v_ashrrev_i32_e32 v1, 31, v0
	v_lshlrev_b64 v[0:1], 12, v[0:1]
	v_lshl_add_u64 v[0:1], s[0:1], 0, v[0:1]
	v_lshl_add_u64 v[0:1], v[0:1], 0, v[128:129]
	global_load_dwordx4 v[104:107], v[0:1], off offset:256
	v_or_b32_e32 v0, s24, v168
	v_ashrrev_i32_e32 v1, 31, v0
	v_lshlrev_b64 v[0:1], 12, v[0:1]
	v_lshl_add_u64 v[0:1], s[0:1], 0, v[0:1]
	v_lshl_add_u64 v[4:5], v[0:1], 0, v[128:129]
	ds_read_b128 v[0:3], v171 offset:17408
	global_load_dwordx4 v[108:111], v[4:5], off offset:256
	ds_read_b128 v[4:7], v171 offset:17424
	ds_read_b128 v[8:11], v171 offset:17440
	ds_read_b128 v[12:15], v171 offset:17456
	s_waitcnt lgkmcnt(3)
	v_ashrrev_i32_e32 v16, 31, v0


; DI unsigned fkey(float f) { const unsigned u = __float_as_uint(f); return (u & 0x80000000u) ? ~u : (u | 0x80000000u); }
; DI void topk_phase(unsigned char* smem_, const bf16_t* __restrict__ qp, const bf16_t* __restrict__ keys, int* __restrict__ eidx, float* __restrict__ gate) {
;     ...
;             const f32x4 sv4 = *(const f32x4*)(S + row * LDS_ + 32 * q + 4 * i);
;             const int ib = 127 - (32 * q + 4 * i);
;             v[4 * i] = (fkey(sv4.x) & ~127u) | (unsigned)ib; v[4 * i + 1] = (fkey(sv4.y) & ~127u) | (unsigned)(ib - 1);
	s_waitcnt lgkmcnt(0)
	v_not_b32_e32 v20, v15
	v_or_b32_e32 v21, 0x80000000, v15
	v_bitop3_b32 v0, v16, s98, v0 bitop3:0x56
	v_ashrrev_i32_e32 v16, 31, v1


; DI unsigned fkey(float f) { const unsigned u = __float_as_uint(f); return (u & 0x80000000u) ? ~u : (u | 0x80000000u); }
; DI void topk_phase(unsigned char* smem_, const bf16_t* __restrict__ qp, const bf16_t* __restrict__ keys, int* __restrict__ eidx, float* __restrict__ gate) {
;     ...
;             v[4 * i] = (fkey(sv4.x) & ~127u) | (unsigned)ib; v[4 * i + 1] = (fkey(sv4.y) & ~127u) | (unsigned)(ib - 1);
	v_and_b32_e32 v0, 0xffffff80, v0
	v_sub_u32_e32 v0, v0, v170
	v_bitop3_b32 v1, v16, s98, v1 bitop3:0x56
	v_ashrrev_i32_e32 v16, 31, v2


; DI unsigned fkey(float f) { const unsigned u = __float_as_uint(f); return (u & 0x80000000u) ? ~u : (u | 0x80000000u); }
; DI void topk_phase(unsigned char* smem_, const bf16_t* __restrict__ qp, const bf16_t* __restrict__ keys, int* __restrict__ eidx, float* __restrict__ gate) {
;     ...
;             v[4 * i] = (fkey(sv4.x) & ~127u) | (unsigned)ib; v[4 * i + 1] = (fkey(sv4.y) & ~127u) | (unsigned)(ib - 1);
	v_and_b32_e32 v1, 0xffffff80, v1
	v_sub_u32_e32 v1, v1, v170
	v_bitop3_b32 v2, v16, s98, v2 bitop3:0x56
	v_ashrrev_i32_e32 v16, 31, v3


; DI unsigned fkey(float f) { const unsigned u = __float_as_uint(f); return (u & 0x80000000u) ? ~u : (u | 0x80000000u); }
; DI void topk_phase(unsigned char* smem_, const bf16_t* __restrict__ qp, const bf16_t* __restrict__ keys, int* __restrict__ eidx, float* __restrict__ gate) {
;     ...
;             v[4 * i + 2] = (fkey(sv4.z) & ~127u) | (unsigned)(ib - 2); v[4 * i + 3] = (fkey(sv4.w) & ~127u) | (unsigned)(ib - 3);
	v_and_b32_e32 v2, 0xffffff80, v2
	v_sub_u32_e32 v2, v2, v170
	v_bitop3_b32 v3, v16, s98, v3 bitop3:0x56
	v_ashrrev_i32_e32 v16, 31, v4


; DI unsigned fkey(float f) { const unsigned u = __float_as_uint(f); return (u & 0x80000000u) ? ~u : (u | 0x80000000u); }
; DI void topk_phase(unsigned char* smem_, const bf16_t* __restrict__ qp, const bf16_t* __restrict__ keys, int* __restrict__ eidx, float* __restrict__ gate) {
;     ...
;             v[4 * i + 2] = (fkey(sv4.z) & ~127u) | (unsigned)(ib - 2); v[4 * i + 3] = (fkey(sv4.w) & ~127u) | (unsigned)(ib - 3);
	v_and_b32_e32 v3, 0xffffff80, v3
	v_sub_u32_e32 v3, v3, v170
	v_bitop3_b32 v4, v16, s98, v4 bitop3:0x56
	v_ashrrev_i32_e32 v16, 31, v5


; DI unsigned fkey(float f) { const unsigned u = __float_as_uint(f); return (u & 0x80000000u) ? ~u : (u | 0x80000000u); }
; DI void topk_phase(unsigned char* smem_, const bf16_t* __restrict__ qp, const bf16_t* __restrict__ keys, int* __restrict__ eidx, float* __restrict__ gate) {
;     ...
;             v[4 * i] = (fkey(sv4.x) & ~127u) | (unsigned)ib; v[4 * i + 1] = (fkey(sv4.y) & ~127u) | (unsigned)(ib - 1);
	v_and_b32_e32 v4, 0xffffff80, v4
	v_sub_u32_e32 v4, v4, v177
	v_bitop3_b32 v5, v16, s98, v5 bitop3:0x56
	v_ashrrev_i32_e32 v16, 31, v6


; DI unsigned fkey(float f) { const unsigned u = __float_as_uint(f); return (u & 0x80000000u) ? ~u : (u | 0x80000000u); }
; DI void topk_phase(unsigned char* smem_, const bf16_t* __restrict__ qp, const bf16_t* __restrict__ keys, int* __restrict__ eidx, float* __restrict__ gate) {
;     ...
;             v[4 * i] = (fkey(sv4.x) & ~127u) | (unsigned)ib; v[4 * i + 1] = (fkey(sv4.y) & ~127u) | (unsigned)(ib - 1);
	v_and_b32_e32 v5, 0xffffff80, v5
	v_sub_u32_e32 v5, v5, v177
	v_bitop3_b32 v6, v16, s98, v6 bitop3:0x56
	v_ashrrev_i32_e32 v16, 31, v7


; DI unsigned fkey(float f) { const unsigned u = __float_as_uint(f); return (u & 0x80000000u) ? ~u : (u | 0x80000000u); }
; DI void topk_phase(unsigned char* smem_, const bf16_t* __restrict__ qp, const bf16_t* __restrict__ keys, int* __restrict__ eidx, float* __restrict__ gate) {
;     ...
;             v[4 * i + 2] = (fkey(sv4.z) & ~127u) | (unsigned)(ib - 2); v[4 * i + 3] = (fkey(sv4.w) & ~127u) | (unsigned)(ib - 3);
	v_and_b32_e32 v6, 0xffffff80, v6
	v_sub_u32_e32 v6, v6, v177
	v_bitop3_b32 v7, v16, s98, v7 bitop3:0x56
	v_ashrrev_i32_e32 v16, 31, v8


; DI unsigned fkey(float f) { const unsigned u = __float_as_uint(f); return (u & 0x80000000u) ? ~u : (u | 0x80000000u); }
; DI void topk_phase(unsigned char* smem_, const bf16_t* __restrict__ qp, const bf16_t* __restrict__ keys, int* __restrict__ eidx, float* __restrict__ gate) {
;     ...
;             v[4 * i + 2] = (fkey(sv4.z) & ~127u) | (unsigned)(ib - 2); v[4 * i + 3] = (fkey(sv4.w) & ~127u) | (unsigned)(ib - 3);
	v_and_b32_e32 v7, 0xffffff80, v7
	v_sub_u32_e32 v7, v7, v177
	v_bitop3_b32 v8, v16, s98, v8 bitop3:0x56
	v_ashrrev_i32_e32 v16, 31, v9


; DI unsigned fkey(float f) { const unsigned u = __float_as_uint(f); return (u & 0x80000000u) ? ~u : (u | 0x80000000u); }
; DI void topk_phase(unsigned char* smem_, const bf16_t* __restrict__ qp, const bf16_t* __restrict__ keys, int* __restrict__ eidx, float* __restrict__ gate) {
;     ...
;             v[4 * i] = (fkey(sv4.x) & ~127u) | (unsigned)ib; v[4 * i + 1] = (fkey(sv4.y) & ~127u) | (unsigned)(ib - 1);
	v_and_b32_e32 v8, 0xffffff80, v8
	v_sub_u32_e32 v8, v8, v178
	v_bitop3_b32 v9, v16, s98, v9 bitop3:0x56
	v_ashrrev_i32_e32 v16, 31, v10


; DI unsigned fkey(float f) { const unsigned u = __float_as_uint(f); return (u & 0x80000000u) ? ~u : (u | 0x80000000u); }
; DI void topk_phase(unsigned char* smem_, const bf16_t* __restrict__ qp, const bf16_t* __restrict__ keys, int* __restrict__ eidx, float* __restrict__ gate) {
;     ...
;         for (int i = 0; i < 8; ++i) {
;             const f32x4 sv4 = *(const f32x4*)(S + row * LDS_ + 32 * q + 4 * i);
;             const int ib = 127 - (32 * q + 4 * i);
;             v[4 * i] = (fkey(sv4.x) & ~127u) | (unsigned)ib; v[4 * i + 1] = (fkey(sv4.y) & ~127u) | (unsigned)(ib - 1);
;             v[4 * i + 2] = (fkey(sv4.z) & ~127u) | (unsigned)(ib - 2); v[4 * i + 3] = (fkey(sv4.w) & ~127u) | (unsigned)(ib - 3);
;         }
	v_and_b32_e32 v9, 0xffffff80, v9
	v_sub_u32_e32 v9, v9, v178
	v_bitop3_b32 v10, v16, s98, v10 bitop3:0x56
	v_and_b32_e32 v10, 0xffffff80, v10
	v_sub_u32_e32 v10, v10, v178
	v_add_u32_e32 v16, 0x7d, v10
	v_not_b32_e32 v10, v11
	v_or_b32_e32 v17, 0x80000000, v11
	v_cmp_gt_i32_e32 vcc, 0, v11
	v_ashrrev_i32_e32 v11, 31, v12
	v_add_u32_e32 v0, 0x7f, v0
	v_cndmask_b32_e32 v10, v17, v10, vcc
	v_and_b32_e32 v10, 0xffffff80, v10
	v_sub_u32_e32 v10, v10, v178
	v_add_u32_e32 v17, 0x7c, v10


; DI unsigned fkey(float f) { const unsigned u = __float_as_uint(f); return (u & 0x80000000u) ? ~u : (u | 0x80000000u); }
; DI void topk_phase(unsigned char* smem_, const bf16_t* __restrict__ qp, const bf16_t* __restrict__ keys, int* __restrict__ eidx, float* __restrict__ gate) {
;     ...
;             v[4 * i] = (fkey(sv4.x) & ~127u) | (unsigned)ib; v[4 * i + 1] = (fkey(sv4.y) & ~127u) | (unsigned)(ib - 1);
;             v[4 * i + 2] = (fkey(sv4.z) & ~127u) | (unsigned)(ib - 2); v[4 * i + 3] = (fkey(sv4.w) & ~127u) | (unsigned)(ib - 3);
	v_add_u32_e32 v1, 0x7e, v1
	v_add_u32_e32 v2, 0x7d, v2
	v_bitop3_b32 v10, v11, s98, v12 bitop3:0x56
	v_and_b32_e32 v10, 0xffffff80, v10
	v_sub_u32_e32 v10, v10, v179
	v_add_u32_e32 v18, 0x7f, v10
	v_ashrrev_i32_e32 v10, 31, v13


; DI unsigned fkey(float f) { const unsigned u = __float_as_uint(f); return (u & 0x80000000u) ? ~u : (u | 0x80000000u); }
; DI void topk_phase(unsigned char* smem_, const bf16_t* __restrict__ qp, const bf16_t* __restrict__ keys, int* __restrict__ eidx, float* __restrict__ gate) {
;     ...
;             v[4 * i] = (fkey(sv4.x) & ~127u) | (unsigned)ib; v[4 * i + 1] = (fkey(sv4.y) & ~127u) | (unsigned)(ib - 1);
;             v[4 * i + 2] = (fkey(sv4.z) & ~127u) | (unsigned)(ib - 2); v[4 * i + 3] = (fkey(sv4.w) & ~127u) | (unsigned)(ib - 3);
	v_add_u32_e32 v3, 0x7c, v3
	v_add_u32_e32 v4, 0x7f, v4
	v_bitop3_b32 v10, v10, s98, v13 bitop3:0x56
	v_and_b32_e32 v10, 0xffffff80, v10
	v_sub_u32_e32 v10, v10, v179
	v_add_u32_e32 v19, 0x7e, v10
	v_ashrrev_i32_e32 v10, 31, v14


; DI unsigned fkey(float f) { const unsigned u = __float_as_uint(f); return (u & 0x80000000u) ? ~u : (u | 0x80000000u); }
; DI void topk_phase(unsigned char* smem_, const bf16_t* __restrict__ qp, const bf16_t* __restrict__ keys, int* __restrict__ eidx, float* __restrict__ gate) {
;     ...
;         for (int i = 0; i < 8; ++i) {
;             const f32x4 sv4 = *(const f32x4*)(S + row * LDS_ + 32 * q + 4 * i);
;             const int ib = 127 - (32 * q + 4 * i);
;             v[4 * i] = (fkey(sv4.x) & ~127u) | (unsigned)ib; v[4 * i + 1] = (fkey(sv4.y) & ~127u) | (unsigned)(ib - 1);
;             v[4 * i + 2] = (fkey(sv4.z) & ~127u) | (unsigned)(ib - 2); v[4 * i + 3] = (fkey(sv4.w) & ~127u) | (unsigned)(ib - 3);
;         }
	v_add_u32_e32 v5, 0x7e, v5
	v_add_u32_e32 v6, 0x7d, v6
	v_bitop3_b32 v10, v10, s98, v14 bitop3:0x56
	v_and_b32_e32 v10, 0xffffff80, v10
	v_sub_u32_e32 v10, v10, v179
	v_add_u32_e32 v14, 0x7d, v10
	ds_read_b128 v[10:13], v171 offset:17472
	v_cmp_gt_i32_e32 vcc, 0, v15
	v_add_u32_e32 v7, 0x7c, v7
	v_add_u32_e32 v8, 0x7f, v8
	v_cndmask_b32_e32 v15, v21, v20, vcc
	s_waitcnt lgkmcnt(0)
	v_ashrrev_i32_e32 v20, 31, v10


; DI unsigned fkey(float f) { const unsigned u = __float_as_uint(f); return (u & 0x80000000u) ? ~u : (u | 0x80000000u); }
; DI void topk_phase(unsigned char* smem_, const bf16_t* __restrict__ qp, const bf16_t* __restrict__ keys, int* __restrict__ eidx, float* __restrict__ gate) {
;     ...
;         for (int i = 0; i < 8; ++i) {
;             const f32x4 sv4 = *(const f32x4*)(S + row * LDS_ + 32 * q + 4 * i);
;             const int ib = 127 - (32 * q + 4 * i);
;             v[4 * i] = (fkey(sv4.x) & ~127u) | (unsigned)ib; v[4 * i + 1] = (fkey(sv4.y) & ~127u) | (unsigned)(ib - 1);
;             v[4 * i + 2] = (fkey(sv4.z) & ~127u) | (unsigned)(ib - 2); v[4 * i + 3] = (fkey(sv4.w) & ~127u) | (unsigned)(ib - 3);
;         }
	v_not_b32_e32 v23, v13
	v_or_b32_e32 v24, 0x80000000, v13
	v_bitop3_b32 v10, v20, s98, v10 bitop3:0x56
	v_and_b32_e32 v10, 0xffffff80, v10
	v_sub_u32_e32 v10, v10, v180
	v_add_u32_e32 v20, 0x7f, v10
	v_not_b32_e32 v10, v11
	v_or_b32_e32 v21, 0x80000000, v11
	v_cmp_gt_i32_e32 vcc, 0, v11
	v_ashrrev_i32_e32 v11, 31, v12
	v_and_b32_e32 v15, 0xffffff80, v15
	v_cndmask_b32_e32 v10, v21, v10, vcc
	v_and_b32_e32 v10, 0xffffff80, v10
	v_sub_u32_e32 v10, v10, v180
	v_add_u32_e32 v21, 0x7e, v10


; DI unsigned fkey(float f) { const unsigned u = __float_as_uint(f); return (u & 0x80000000u) ? ~u : (u | 0x80000000u); }
; DI void topk_phase(unsigned char* smem_, const bf16_t* __restrict__ qp, const bf16_t* __restrict__ keys, int* __restrict__ eidx, float* __restrict__ gate) {
;     ...
;         for (int i = 0; i < 8; ++i) {
;             const f32x4 sv4 = *(const f32x4*)(S + row * LDS_ + 32 * q + 4 * i);
;             const int ib = 127 - (32 * q + 4 * i);
;             v[4 * i] = (fkey(sv4.x) & ~127u) | (unsigned)ib; v[4 * i + 1] = (fkey(sv4.y) & ~127u) | (unsigned)(ib - 1);
;             v[4 * i + 2] = (fkey(sv4.z) & ~127u) | (unsigned)(ib - 2); v[4 * i + 3] = (fkey(sv4.w) & ~127u) | (unsigned)(ib - 3);
;         }
	v_sub_u32_e32 v15, v15, v179
	v_add_u32_e32 v9, 0x7e, v9
	v_bitop3_b32 v10, v11, s98, v12 bitop3:0x56
	v_and_b32_e32 v10, 0xffffff80, v10
	v_sub_u32_e32 v10, v10, v180
	v_add_u32_e32 v22, 0x7d, v10
	v_cmp_gt_i32_e32 vcc, 0, v13
	ds_read_b128 v[10:13], v171 offset:17488
	v_add_u32_e32 v15, 0x7c, v15
	v_cndmask_b32_e32 v23, v24, v23, vcc
	v_and_b32_e32 v23, 0xffffff80, v23
	v_sub_u32_e32 v23, v23, v180
	s_waitcnt lgkmcnt(0)
	v_ashrrev_i32_e32 v24, 31, v10


; DI unsigned fkey(float f) { const unsigned u = __float_as_uint(f); return (u & 0x80000000u) ? ~u : (u | 0x80000000u); }
; DI void topk_phase(unsigned char* smem_, const bf16_t* __restrict__ qp, const bf16_t* __restrict__ keys, int* __restrict__ eidx, float* __restrict__ gate) {
;     ...
;         for (int i = 0; i < 8; ++i) {
;             const f32x4 sv4 = *(const f32x4*)(S + row * LDS_ + 32 * q + 4 * i);
;             const int ib = 127 - (32 * q + 4 * i);
;             v[4 * i] = (fkey(sv4.x) & ~127u) | (unsigned)ib; v[4 * i + 1] = (fkey(sv4.y) & ~127u) | (unsigned)(ib - 1);
;             v[4 * i + 2] = (fkey(sv4.z) & ~127u) | (unsigned)(ib - 2); v[4 * i + 3] = (fkey(sv4.w) & ~127u) | (unsigned)(ib - 3);
;         }
	v_not_b32_e32 v27, v13
	v_or_b32_e32 v28, 0x80000000, v13
	v_bitop3_b32 v10, v24, s98, v10 bitop3:0x56
	v_and_b32_e32 v10, 0xffffff80, v10
	v_sub_u32_e32 v10, v10, v181
	v_add_u32_e32 v24, 0x7f, v10
	v_not_b32_e32 v10, v11
	v_or_b32_e32 v25, 0x80000000, v11
	v_cmp_gt_i32_e32 vcc, 0, v11
	v_ashrrev_i32_e32 v11, 31, v12
	v_add_u32_e32 v23, 0x7c, v23
	v_cndmask_b32_e32 v10, v25, v10, vcc
	v_and_b32_e32 v10, 0xffffff80, v10
	v_sub_u32_e32 v10, v10, v181
	v_add_u32_e32 v25, 0x7e, v10


; DI unsigned fkey(float f) { const unsigned u = __float_as_uint(f); return (u & 0x80000000u) ? ~u : (u | 0x80000000u); }
; DI void topk_phase(unsigned char* smem_, const bf16_t* __restrict__ qp, const bf16_t* __restrict__ keys, int* __restrict__ eidx, float* __restrict__ gate) {
;     ...
;         for (int i = 0; i < 8; ++i) {
;             const f32x4 sv4 = *(const f32x4*)(S + row * LDS_ + 32 * q + 4 * i);
;             const int ib = 127 - (32 * q + 4 * i);
;             v[4 * i] = (fkey(sv4.x) & ~127u) | (unsigned)ib; v[4 * i + 1] = (fkey(sv4.y) & ~127u) | (unsigned)(ib - 1);
;             v[4 * i + 2] = (fkey(sv4.z) & ~127u) | (unsigned)(ib - 2); v[4 * i + 3] = (fkey(sv4.w) & ~127u) | (unsigned)(ib - 3);
;         }
	s_nop 1
	v_bitop3_b32 v10, v11, s98, v12 bitop3:0x56
	v_and_b32_e32 v10, 0xffffff80, v10
	v_sub_u32_e32 v10, v10, v181
	v_add_u32_e32 v26, 0x7d, v10
	v_cmp_gt_i32_e32 vcc, 0, v13
	ds_read_b128 v[10:13], v171 offset:17504
	s_waitcnt lgkmcnt(0)
	v_ashrrev_i32_e32 v29, 31, v10
	v_cndmask_b32_e32 v27, v28, v27, vcc


; DI unsigned fkey(float f) { const unsigned u = __float_as_uint(f); return (u & 0x80000000u) ? ~u : (u | 0x80000000u); }
; DI void topk_phase(unsigned char* smem_, const bf16_t* __restrict__ qp, const bf16_t* __restrict__ keys, int* __restrict__ eidx, float* __restrict__ gate) {
;     ...
;         for (int i = 0; i < 8; ++i) {
;             const f32x4 sv4 = *(const f32x4*)(S + row * LDS_ + 32 * q + 4 * i);
;             const int ib = 127 - (32 * q + 4 * i);
;             v[4 * i] = (fkey(sv4.x) & ~127u) | (unsigned)ib; v[4 * i + 1] = (fkey(sv4.y) & ~127u) | (unsigned)(ib - 1);
;             v[4 * i + 2] = (fkey(sv4.z) & ~127u) | (unsigned)(ib - 2); v[4 * i + 3] = (fkey(sv4.w) & ~127u) | (unsigned)(ib - 3);
;         }
	v_not_b32_e32 v31, v13
	v_or_b32_e32 v116, 0x80000000, v13
	v_bitop3_b32 v10, v29, s98, v10 bitop3:0x56
	v_and_b32_e32 v10, 0xffffff80, v10
	v_sub_u32_e32 v10, v10, v182
	v_add_u32_e32 v28, 0x7f, v10
	v_not_b32_e32 v10, v11
	v_or_b32_e32 v29, 0x80000000, v11
	v_cmp_gt_i32_e32 vcc, 0, v11
	v_ashrrev_i32_e32 v11, 31, v12
	v_and_b32_e32 v27, 0xffffff80, v27
	v_cndmask_b32_e32 v10, v29, v10, vcc
	v_and_b32_e32 v10, 0xffffff80, v10
	v_sub_u32_e32 v10, v10, v182
	v_add_u32_e32 v29, 0x7e, v10


; DI unsigned fkey(float f) { const unsigned u = __float_as_uint(f); return (u & 0x80000000u) ? ~u : (u | 0x80000000u); }
; DI void topk_phase(unsigned char* smem_, const bf16_t* __restrict__ qp, const bf16_t* __restrict__ keys, int* __restrict__ eidx, float* __restrict__ gate) {
;     ...
;         for (int i = 0; i < 8; ++i) {
;             const f32x4 sv4 = *(const f32x4*)(S + row * LDS_ + 32 * q + 4 * i);
;             const int ib = 127 - (32 * q + 4 * i);
;             v[4 * i] = (fkey(sv4.x) & ~127u) | (unsigned)ib; v[4 * i + 1] = (fkey(sv4.y) & ~127u) | (unsigned)(ib - 1);
;             v[4 * i + 2] = (fkey(sv4.z) & ~127u) | (unsigned)(ib - 2); v[4 * i + 3] = (fkey(sv4.w) & ~127u) | (unsigned)(ib - 3);
;         }
	v_sub_u32_e32 v27, v27, v181
	v_add_u32_e32 v27, 0x7c, v27
	v_bitop3_b32 v10, v11, s98, v12 bitop3:0x56
	v_and_b32_e32 v10, 0xffffff80, v10
	v_sub_u32_e32 v10, v10, v182
	v_add_u32_e32 v30, 0x7d, v10
	v_cmp_gt_i32_e32 vcc, 0, v13
	ds_read_b128 v[10:13], v171 offset:17520
	s_waitcnt lgkmcnt(0)
	v_ashrrev_i32_e32 v117, 31, v10
	v_cndmask_b32_e32 v31, v116, v31, vcc


; DI unsigned fkey(float f) { const unsigned u = __float_as_uint(f); return (u & 0x80000000u) ? ~u : (u | 0x80000000u); }
; DI void topk_phase(unsigned char* smem_, const bf16_t* __restrict__ qp, const bf16_t* __restrict__ keys, int* __restrict__ eidx, float* __restrict__ gate) {
;     ...
;         for (int i = 0; i < 8; ++i) {
;             const f32x4 sv4 = *(const f32x4*)(S + row * LDS_ + 32 * q + 4 * i);
;             const int ib = 127 - (32 * q + 4 * i);
;             v[4 * i] = (fkey(sv4.x) & ~127u) | (unsigned)ib; v[4 * i + 1] = (fkey(sv4.y) & ~127u) | (unsigned)(ib - 1);
;             v[4 * i + 2] = (fkey(sv4.z) & ~127u) | (unsigned)(ib - 2); v[4 * i + 3] = (fkey(sv4.w) & ~127u) | (unsigned)(ib - 3);
;         }
	v_and_b32_e32 v31, 0xffffff80, v31
	v_sub_u32_e32 v31, v31, v182
	v_bitop3_b32 v10, v117, s98, v10 bitop3:0x56
	v_ashrrev_i32_e32 v116, 31, v11


; DI unsigned fkey(float f) { const unsigned u = __float_as_uint(f); return (u & 0x80000000u) ? ~u : (u | 0x80000000u); }
; DI void topk_phase(unsigned char* smem_, const bf16_t* __restrict__ qp, const bf16_t* __restrict__ keys, int* __restrict__ eidx, float* __restrict__ gate) {
;     ...
;         for (int i = 0; i < 8; ++i) {
;             const f32x4 sv4 = *(const f32x4*)(S + row * LDS_ + 32 * q + 4 * i);
;             const int ib = 127 - (32 * q + 4 * i);
;             v[4 * i] = (fkey(sv4.x) & ~127u) | (unsigned)ib; v[4 * i + 1] = (fkey(sv4.y) & ~127u) | (unsigned)(ib - 1);
;             v[4 * i + 2] = (fkey(sv4.z) & ~127u) | (unsigned)(ib - 2); v[4 * i + 3] = (fkey(sv4.w) & ~127u) | (unsigned)(ib - 3);
;         }
	v_and_b32_e32 v10, 0xffffff80, v10
	v_sub_u32_e32 v10, v10, v183
	v_bitop3_b32 v11, v116, s98, v11 bitop3:0x56
	v_ashrrev_i32_e32 v116, 31, v12


; DI unsigned fkey(float f) { const unsigned u = __float_as_uint(f); return (u & 0x80000000u) ? ~u : (u | 0x80000000u); }
; DI void topk_phase(unsigned char* smem_, const bf16_t* __restrict__ qp, const bf16_t* __restrict__ keys, int* __restrict__ eidx, float* __restrict__ gate) {
;     ...
;         for (int i = 0; i < 8; ++i) {
;             const f32x4 sv4 = *(const f32x4*)(S + row * LDS_ + 32 * q + 4 * i);
;             const int ib = 127 - (32 * q + 4 * i);
;             v[4 * i] = (fkey(sv4.x) & ~127u) | (unsigned)ib; v[4 * i + 1] = (fkey(sv4.y) & ~127u) | (unsigned)(ib - 1);
;             v[4 * i + 2] = (fkey(sv4.z) & ~127u) | (unsigned)(ib - 2); v[4 * i + 3] = (fkey(sv4.w) & ~127u) | (unsigned)(ib - 3);
;         }
	v_and_b32_e32 v11, 0xffffff80, v11
	v_sub_u32_e32 v11, v11, v183
	v_bitop3_b32 v12, v116, s98, v12 bitop3:0x56
	v_ashrrev_i32_e32 v116, 31, v13


; DI unsigned fkey(float f) { const unsigned u = __float_as_uint(f); return (u & 0x80000000u) ? ~u : (u | 0x80000000u); }
; template <int N> DI void bitonic_sort_desc(unsigned (&v)[N]) {
; #pragma unroll
;     for (int k = 2; k <= N; k <<= 1)
; #pragma unroll
;         for (int j = k >> 1; j > 0; j >>= 1)
; #pragma unroll
;             for (int i = 0; i < N; ++i) { const int l = i ^ j; if (l > i) { if ((i & k) == 0) cswap(v[i], v[l]); else cswap(v[l], v[i]); } }
; DI void topk_phase(unsigned char* smem_, const bf16_t* __restrict__ qp, const bf16_t* __restrict__ keys, int* __restrict__ eidx, float* __restrict__ gate) {
;     ...
;         for (int i = 0; i < 8; ++i) {
;             const f32x4 sv4 = *(const f32x4*)(S + row * LDS_ + 32 * q + 4 * i);
;             const int ib = 127 - (32 * q + 4 * i);
;             v[4 * i] = (fkey(sv4.x) & ~127u) | (unsigned)ib; v[4 * i + 1] = (fkey(sv4.y) & ~127u) | (unsigned)(ib - 1);
;             v[4 * i + 2] = (fkey(sv4.z) & ~127u) | (unsigned)(ib - 2); v[4 * i + 3] = (fkey(sv4.w) & ~127u) | (unsigned)(ib - 3);
;         }
;         bitonic_sort_desc<32>(v);
	v_and_b32_e32 v12, 0xffffff80, v12
	v_sub_u32_e32 v12, v12, v183
	v_bitop3_b32 v13, v116, s98, v13 bitop3:0x56
	v_and_b32_e32 v13, 0xffffff80, v13
	v_sub_u32_e32 v13, v13, v183
	v_add_u32_e32 v31, 0x7c, v31
	v_add_u32_e32 v10, 0x7f, v10
	v_add_u32_e32 v11, 0x7e, v11
	v_add_u32_e32 v12, 0x7d, v12
	v_add_u32_e32 v13, 0x7c, v13
	v_max_u32_e32 v116, v0, v1
	v_min_u32_e32 v0, v0, v1
	v_max_u32_e32 v1, v3, v2
	v_min_u32_e32 v2, v3, v2
	v_max_u32_e32 v3, v4, v5
	v_min_u32_e32 v4, v4, v5
	v_max_u32_e32 v5, v7, v6
	v_min_u32_e32 v6, v7, v6
	v_max_u32_e32 v7, v8, v9
	v_min_u32_e32 v8, v8, v9
	v_max_u32_e32 v9, v17, v16
	v_min_u32_e32 v16, v17, v16
	v_max_u32_e32 v17, v18, v19
	v_min_u32_e32 v18, v18, v19
	v_max_u32_e32 v19, v15, v14
	v_min_u32_e32 v14, v15, v14
	v_max_u32_e32 v15, v20, v21
	v_min_u32_e32 v20, v20, v21
	v_max_u32_e32 v21, v23, v22
	v_min_u32_e32 v22, v23, v22
	v_max_u32_e32 v23, v24, v25
	v_min_u32_e32 v24, v24, v25
	v_max_u32_e32 v25, v27, v26
	v_min_u32_e32 v26, v27, v26
	v_max_u32_e32 v27, v28, v29
	v_min_u32_e32 v28, v28, v29
	v_max_u32_e32 v29, v31, v30
	v_min_u32_e32 v30, v31, v30
	v_max_u32_e32 v31, v10, v11
	v_min_u32_e32 v10, v10, v11
	v_max_u32_e32 v11, v13, v12
	v_min_u32_e32 v12, v13, v12
	v_max_u32_e32 v13, v116, v2
	v_min_u32_e32 v2, v116, v2
	v_max_u32_e32 v116, v0, v1
	v_min_u32_e32 v0, v0, v1
	v_max_u32_e32 v1, v6, v3
	v_min_u32_e32 v3, v6, v3
	v_max_u32_e32 v6, v5, v4
	v_min_u32_e32 v4, v5, v4
	v_max_u32_e32 v5, v7, v16
	v_min_u32_e32 v7, v7, v16
	v_max_u32_e32 v16, v8, v9
	v_min_u32_e32 v8, v8, v9
	v_max_u32_e32 v9, v14, v17
	v_min_u32_e32 v14, v14, v17
	v_max_u32_e32 v17, v19, v18
	v_min_u32_e32 v18, v19, v18
	v_max_u32_e32 v19, v15, v22
	v_min_u32_e32 v15, v15, v22
	v_max_u32_e32 v22, v20, v21
	v_min_u32_e32 v20, v20, v21
	v_max_u32_e32 v21, v26, v23
	v_min_u32_e32 v23, v26, v23
	v_max_u32_e32 v26, v25, v24
	v_min_u32_e32 v24, v25, v24
	v_max_u32_e32 v25, v27, v30
	v_min_u32_e32 v27, v27, v30
	v_max_u32_e32 v30, v28, v29
	v_min_u32_e32 v28, v28, v29
	v_max_u32_e32 v29, v12, v31
	v_min_u32_e32 v12, v12, v31
	v_max_u32_e32 v31, v11, v10
	v_min_u32_e32 v10, v11, v10
	v_max_u32_e32 v11, v13, v116
	v_min_u32_e32 v13, v13, v116
	v_max_u32_e32 v116, v2, v0
	v_min_u32_e32 v0, v2, v0
	v_max_u32_e32 v2, v4, v3
	v_min_u32_e32 v3, v4, v3
	v_max_u32_e32 v4, v6, v1
	v_min_u32_e32 v1, v6, v1
	v_max_u32_e32 v6, v5, v16
	v_min_u32_e32 v5, v5, v16
	v_max_u32_e32 v16, v7, v8
	v_min_u32_e32 v7, v7, v8
	v_max_u32_e32 v8, v18, v14
	v_min_u32_e32 v14, v18, v14
	v_max_u32_e32 v18, v17, v9
	v_min_u32_e32 v9, v17, v9
	v_max_u32_e32 v17, v19, v22
	v_min_u32_e32 v19, v19, v22
	v_max_u32_e32 v22, v15, v20
	v_min_u32_e32 v15, v15, v20
	v_max_u32_e32 v20, v24, v23
	v_min_u32_e32 v23, v24, v23
	v_max_u32_e32 v24, v26, v21
	v_min_u32_e32 v21, v26, v21
	v_max_u32_e32 v26, v25, v30
	v_min_u32_e32 v25, v25, v30
	v_max_u32_e32 v30, v27, v28
	v_min_u32_e32 v27, v27, v28
	v_max_u32_e32 v28, v10, v12
	v_min_u32_e32 v10, v10, v12
	v_max_u32_e32 v12, v31, v29
	v_min_u32_e32 v29, v31, v29
	v_max_u32_e32 v31, v11, v3
	v_min_u32_e32 v3, v11, v3
	v_max_u32_e32 v11, v13, v2
	v_min_u32_e32 v2, v13, v2
	v_max_u32_e32 v13, v116, v1
	v_min_u32_e32 v1, v116, v1
	v_max_u32_e32 v116, v0, v4
	v_min_u32_e32 v0, v0, v4
	v_max_u32_e32 v4, v14, v6
	v_min_u32_e32 v6, v14, v6
	v_max_u32_e32 v14, v8, v5
	v_min_u32_e32 v5, v8, v5
	v_max_u32_e32 v8, v9, v16
	v_min_u32_e32 v9, v9, v16
	v_max_u32_e32 v16, v18, v7
	v_min_u32_e32 v7, v18, v7
	v_max_u32_e32 v18, v17, v23
	v_min_u32_e32 v17, v17, v23
	v_max_u32_e32 v23, v19, v20
	v_min_u32_e32 v19, v19, v20
	v_max_u32_e32 v20, v22, v21
	v_min_u32_e32 v21, v22, v21
	v_max_u32_e32 v22, v15, v24
	v_min_u32_e32 v15, v15, v24
	v_max_u32_e32 v24, v10, v26
	v_min_u32_e32 v10, v10, v26
	v_max_u32_e32 v26, v28, v25
	v_min_u32_e32 v25, v28, v25
	v_max_u32_e32 v28, v29, v30
	v_min_u32_e32 v29, v29, v30
	v_max_u32_e32 v30, v12, v27
	v_min_u32_e32 v12, v12, v27
	v_max_u32_e32 v27, v31, v13
	v_min_u32_e32 v13, v31, v13
	v_max_u32_e32 v31, v11, v116
	v_min_u32_e32 v11, v11, v116
	v_max_u32_e32 v116, v3, v1
	v_min_u32_e32 v1, v3, v1
	v_max_u32_e32 v3, v2, v0
	v_min_u32_e32 v0, v2, v0
	v_max_u32_e32 v2, v9, v6
	v_min_u32_e32 v6, v9, v6
	v_max_u32_e32 v9, v7, v5
	v_min_u32_e32 v5, v7, v5
	v_max_u32_e32 v7, v8, v4
	v_min_u32_e32 v4, v8, v4
	v_max_u32_e32 v8, v16, v14
	v_min_u32_e32 v14, v16, v14
	v_max_u32_e32 v16, v18, v20
	v_min_u32_e32 v18, v18, v20
	v_max_u32_e32 v20, v23, v22
	v_min_u32_e32 v22, v23, v22
	v_max_u32_e32 v23, v17, v21
	v_min_u32_e32 v17, v17, v21
	v_max_u32_e32 v21, v19, v15
	v_min_u32_e32 v15, v19, v15
	v_max_u32_e32 v19, v29, v10
	v_min_u32_e32 v10, v29, v10
	v_max_u32_e32 v29, v12, v25
	v_min_u32_e32 v12, v12, v25
	v_max_u32_e32 v25, v28, v24
	v_min_u32_e32 v24, v28, v24
	v_max_u32_e32 v28, v30, v26
	v_min_u32_e32 v26, v30, v26
	v_max_u32_e32 v30, v27, v31
	v_min_u32_e32 v27, v27, v31
	v_max_u32_e32 v31, v13, v11
	v_min_u32_e32 v11, v13, v11
	v_max_u32_e32 v13, v116, v3
	v_min_u32_e32 v3, v116, v3
	v_max_u32_e32 v116, v1, v0
	v_min_u32_e32 v0, v1, v0
	v_max_u32_e32 v1, v5, v6
	v_min_u32_e32 v5, v5, v6
	v_max_u32_e32 v6, v9, v2
	v_min_u32_e32 v2, v9, v2
	v_max_u32_e32 v9, v14, v4
	v_min_u32_e32 v4, v14, v4
	v_max_u32_e32 v14, v8, v7
	v_min_u32_e32 v7, v8, v7
	v_max_u32_e32 v8, v16, v20
	v_min_u32_e32 v16, v16, v20
	v_max_u32_e32 v20, v18, v22
	v_min_u32_e32 v18, v18, v22
	v_max_u32_e32 v22, v23, v21
	v_min_u32_e32 v21, v23, v21
	v_max_u32_e32 v23, v17, v15
	v_min_u32_e32 v15, v17, v15
	v_max_u32_e32 v17, v12, v10
	v_min_u32_e32 v10, v12, v10
	v_max_u32_e32 v12, v29, v19
	v_min_u32_e32 v19, v29, v19
	v_max_u32_e32 v29, v26, v24
; DI void merge_top16(unsigned (&v)[16], int st) {
;     unsigned x[16];
; #pragma unroll
;     for (int i = 0; i < 16; ++i) x[i] = (unsigned)__shfl_xor((int)v[15 - i], st);
; #pragma unroll
;     for (int i = 0; i < 16; ++i) v[i] = max(v[i], x[i]);
; #pragma unroll
;     for (int j = 8; j > 0; j >>= 1)
; #pragma unroll
;         for (int i = 0; i < 16; ++i) { const int l = i ^ j; if (l > i) cswap(v[i], v[l]); }
; }
; DI void topk_phase(unsigned char* smem_, const bf16_t* __restrict__ qp, const bf16_t* __restrict__ keys, int* __restrict__ eidx, float* __restrict__ gate) {
;     ...
;         bitonic_sort_desc<32>(v);
;         unsigned t16[16];
; #pragma unroll
;         for (int i = 0; i < 16; ++i) t16[i] = v[i];
;         merge_top16(t16, 1);
	v_min_u32_e32 v24, v26, v24
	v_max_u32_e32 v26, v28, v25
	v_min_u32_e32 v25, v28, v25
	v_max_u32_e32 v28, v30, v5
	v_min_u32_e32 v5, v30, v5
	v_max_u32_e32 v30, v27, v1
	v_min_u32_e32 v1, v27, v1
	v_max_u32_e32 v27, v31, v2
	v_min_u32_e32 v2, v31, v2
	v_max_u32_e32 v31, v11, v6
	v_min_u32_e32 v6, v11, v6
	v_max_u32_e32 v11, v13, v4
	v_min_u32_e32 v4, v13, v4
	v_max_u32_e32 v13, v3, v9
	v_min_u32_e32 v3, v3, v9
	v_max_u32_e32 v9, v116, v7
	v_min_u32_e32 v7, v116, v7
	v_max_u32_e32 v116, v0, v14
	v_min_u32_e32 v0, v0, v14
	v_max_u32_e32 v14, v10, v8
	v_min_u32_e32 v8, v10, v8
	v_max_u32_e32 v10, v17, v16
	v_min_u32_e32 v16, v17, v16
	v_max_u32_e32 v17, v19, v20
	v_min_u32_e32 v19, v19, v20
	v_max_u32_e32 v20, v12, v18
	v_min_u32_e32 v12, v12, v18
	v_max_u32_e32 v18, v24, v22
	v_min_u32_e32 v22, v24, v22
	v_max_u32_e32 v24, v29, v21
	v_min_u32_e32 v21, v29, v21
	v_max_u32_e32 v29, v25, v23
	v_min_u32_e32 v23, v25, v23
	v_max_u32_e32 v25, v26, v15
	v_min_u32_e32 v15, v26, v15
	v_max_u32_e32 v26, v28, v11
	v_min_u32_e32 v11, v28, v11
	v_max_u32_e32 v28, v30, v13
	v_min_u32_e32 v13, v30, v13
	v_max_u32_e32 v30, v27, v9
	v_min_u32_e32 v9, v27, v9
	v_max_u32_e32 v27, v31, v116
	v_min_u32_e32 v31, v31, v116
	v_max_u32_e32 v116, v5, v4
	v_min_u32_e32 v4, v5, v4
	v_max_u32_e32 v5, v1, v3
	v_min_u32_e32 v1, v1, v3
	v_max_u32_e32 v3, v2, v7
	v_min_u32_e32 v2, v2, v7
	v_max_u32_e32 v7, v6, v0
	v_min_u32_e32 v0, v6, v0
	v_max_u32_e32 v6, v22, v8
	v_min_u32_e32 v8, v22, v8
	v_max_u32_e32 v22, v21, v16
	v_min_u32_e32 v16, v21, v16
	v_max_u32_e32 v21, v23, v19
	v_min_u32_e32 v19, v23, v19
	v_max_u32_e32 v23, v15, v12
	v_min_u32_e32 v12, v15, v12
	v_max_u32_e32 v15, v18, v14
	v_min_u32_e32 v14, v18, v14
	v_max_u32_e32 v18, v24, v10
	v_min_u32_e32 v10, v24, v10
	v_max_u32_e32 v24, v29, v17
	v_min_u32_e32 v17, v29, v17
	v_max_u32_e32 v29, v25, v20
	v_min_u32_e32 v20, v25, v20
	v_max_u32_e32 v25, v26, v30
	v_min_u32_e32 v26, v26, v30
	v_max_u32_e32 v30, v28, v27
	v_min_u32_e32 v27, v28, v27
	v_max_u32_e32 v28, v11, v9
	v_min_u32_e32 v9, v11, v9
	v_max_u32_e32 v11, v13, v31
	v_min_u32_e32 v13, v13, v31
	v_max_u32_e32 v31, v116, v3
	v_min_u32_e32 v3, v116, v3
	v_max_u32_e32 v116, v5, v7
	v_min_u32_e32 v5, v5, v7
	v_max_u32_e32 v7, v4, v2
	v_min_u32_e32 v2, v4, v2
	v_max_u32_e32 v4, v1, v0
	v_min_u32_e32 v0, v1, v0
	v_max_u32_e32 v1, v19, v8
	v_min_u32_e32 v8, v19, v8
	v_max_u32_e32 v19, v12, v16
	v_min_u32_e32 v12, v12, v16
	v_max_u32_e32 v16, v21, v6
	v_min_u32_e32 v6, v21, v6
	v_max_u32_e32 v21, v23, v22
	v_min_u32_e32 v22, v23, v22
	v_max_u32_e32 v23, v17, v14
	v_min_u32_e32 v14, v17, v14
	v_max_u32_e32 v17, v20, v10
	v_min_u32_e32 v10, v20, v10
	v_max_u32_e32 v20, v24, v15
	v_min_u32_e32 v15, v24, v15
	v_max_u32_e32 v24, v29, v18
	v_min_u32_e32 v18, v29, v18
	v_min_u32_e32 v29, v25, v30
	v_min_u32_e32 v117, v26, v27
	v_min_u32_e32 v118, v28, v11
	v_min_u32_e32 v119, v9, v13
	v_min_u32_e32 v120, v31, v116
	v_min_u32_e32 v121, v3, v5
	v_min_u32_e32 v122, v7, v4
	v_min_u32_e32 v123, v2, v0
	v_min_u32_e32 v124, v12, v8
	v_min_u32_e32 v125, v19, v1
	v_min_u32_e32 v126, v22, v6
	v_min_u32_e32 v127, v21, v16
	v_min_u32_e32 v142, v10, v14
	v_min_u32_e32 v143, v17, v23
	v_min_u32_e32 v144, v18, v15
	v_min_u32_e32 v145, v24, v20
	v_max3_u32 v25, v25, v30, v124
	v_max3_u32 v8, v29, v12, v8
	v_max3_u32 v12, v26, v27, v125
	v_max3_u32 v1, v117, v19, v1
	v_max3_u32 v11, v28, v11, v126
	v_max3_u32 v6, v118, v22, v6
	v_max3_u32 v9, v9, v13, v127
	v_max3_u32 v13, v119, v21, v16
	v_max3_u32 v16, v31, v116, v142
	v_max3_u32 v10, v120, v10, v14
	v_max3_u32 v3, v3, v5, v143
	v_max3_u32 v5, v121, v17, v23
	v_max3_u32 v4, v7, v4, v144
	v_max3_u32 v7, v122, v18, v15
	v_max3_u32 v0, v2, v0, v145
	v_max3_u32 v2, v123, v24, v20
	v_max_u32_e32 v14, v25, v16
	v_min_u32_e32 v15, v25, v16
	v_max_u32_e32 v16, v8, v10
	v_min_u32_e32 v8, v8, v10
	v_max_u32_e32 v10, v12, v3
	v_min_u32_e32 v3, v12, v3
	v_max_u32_e32 v12, v1, v5
	v_min_u32_e32 v1, v1, v5
	v_max_u32_e32 v5, v11, v4
	v_min_u32_e32 v4, v11, v4
	v_max_u32_e32 v11, v6, v7
	v_min_u32_e32 v6, v6, v7
	v_max_u32_e32 v7, v9, v0
	v_min_u32_e32 v0, v9, v0
	v_max_u32_e32 v9, v13, v2
	v_min_u32_e32 v2, v13, v2
	v_max_u32_e32 v13, v14, v5
	v_min_u32_e32 v5, v14, v5
	v_max_u32_e32 v14, v16, v11
	v_min_u32_e32 v11, v16, v11
	v_max_u32_e32 v16, v10, v7
	v_min_u32_e32 v7, v10, v7
	v_max_u32_e32 v10, v12, v9
	v_min_u32_e32 v9, v12, v9
	v_max_u32_e32 v12, v15, v4
	v_min_u32_e32 v4, v15, v4
	v_max_u32_e32 v15, v8, v6
	v_min_u32_e32 v6, v8, v6
	v_max_u32_e32 v8, v3, v0
	v_min_u32_e32 v0, v3, v0
	v_max_u32_e32 v3, v1, v2
	v_min_u32_e32 v1, v1, v2
	v_max_u32_e32 v2, v13, v16
	v_min_u32_e32 v13, v13, v16
	v_max_u32_e32 v16, v14, v10
	v_min_u32_e32 v10, v14, v10
	v_max_u32_e32 v14, v5, v7
	v_min_u32_e32 v5, v5, v7
	v_max_u32_e32 v7, v11, v9
	v_min_u32_e32 v9, v11, v9
	v_max_u32_e32 v11, v12, v8
	v_min_u32_e32 v8, v12, v8
	v_max_u32_e32 v12, v15, v3
	v_min_u32_e32 v3, v15, v3
	v_max_u32_e32 v15, v4, v0
	v_min_u32_e32 v0, v4, v0
	v_max_u32_e32 v4, v6, v1
	v_min_u32_e32 v1, v6, v1
	v_max_u32_e32 v6, v2, v16
	v_min_u32_e32 v2, v2, v16
	v_max_u32_e32 v16, v13, v10
	v_min_u32_e32 v10, v13, v10
	v_max_u32_e32 v13, v14, v7
	v_min_u32_e32 v7, v14, v7
	v_max_u32_e32 v14, v5, v9
	v_min_u32_e32 v5, v5, v9
	v_max_u32_e32 v9, v11, v12
	v_min_u32_e32 v11, v11, v12
	v_max_u32_e32 v12, v8, v3
	v_min_u32_e32 v3, v8, v3
	v_max_u32_e32 v8, v15, v4
	v_min_u32_e32 v4, v15, v4
	v_max_u32_e32 v15, v0, v1
	v_min_u32_e32 v0, v0, v1
	s_nop 1
	v_mov_b32_dpp v1, v0 quad_perm:[1,0,3,2] row_mask:0xf bank_mask:0xf
	v_mov_b32_dpp v17, v15 quad_perm:[1,0,3,2] row_mask:0xf bank_mask:0xf
	v_mov_b32_dpp v18, v4 quad_perm:[1,0,3,2] row_mask:0xf bank_mask:0xf
	v_mov_b32_dpp v19, v8 quad_perm:[1,0,3,2] row_mask:0xf bank_mask:0xf
	v_mov_b32_dpp v20, v3 quad_perm:[1,0,3,2] row_mask:0xf bank_mask:0xf
	v_mov_b32_dpp v21, v12 quad_perm:[1,0,3,2] row_mask:0xf bank_mask:0xf
	v_mov_b32_dpp v22, v11 quad_perm:[1,0,3,2] row_mask:0xf bank_mask:0xf
	v_mov_b32_dpp v23, v9 quad_perm:[1,0,3,2] row_mask:0xf bank_mask:0xf
	v_mov_b32_dpp v24, v5 quad_perm:[1,0,3,2] row_mask:0xf bank_mask:0xf
	v_mov_b32_dpp v25, v14 quad_perm:[1,0,3,2] row_mask:0xf bank_mask:0xf
	v_mov_b32_dpp v26, v7 quad_perm:[1,0,3,2] row_mask:0xf bank_mask:0xf
	v_mov_b32_dpp v27, v13 quad_perm:[1,0,3,2] row_mask:0xf bank_mask:0xf
	v_mov_b32_dpp v28, v10 quad_perm:[1,0,3,2] row_mask:0xf bank_mask:0xf
	v_mov_b32_dpp v29, v16 quad_perm:[1,0,3,2] row_mask:0xf bank_mask:0xf
	v_mov_b32_dpp v30, v2 quad_perm:[1,0,3,2] row_mask:0xf bank_mask:0xf
	v_mov_b32_dpp v31, v6 quad_perm:[1,0,3,2] row_mask:0xf bank_mask:0xf
	s_waitcnt lgkmcnt(0)
; DI void topk_phase(unsigned char* smem_, const bf16_t* __restrict__ qp, const bf16_t* __restrict__ keys, int* __restrict__ eidx, float* __restrict__ gate) {
;     ...
;         for (int i = 0; i < 4; ++i) { const int c = tid + 256 * i; *(u32x4*)(As + (c >> 4) * LDA + (c & 15) * 8) = pre[i]; }
;         __syncthreads();
;     ...
;         merge_top16(t16, 1);
;         merge_top16(t16, 2);
; #pragma unroll
;         for (int i = 0; i < 16; ++i) if ((i >> 2) == q) { const int idx = 127 - (int)(t16[i] & 127u); SI[row * 32 + 16 * p + i] = idx; SV[row * 32 + 16 * p + i] = S[row * LDS_ + idx]; }
	v_max_u32_e32 v1, v6, v1
	v_max_u32_e32 v2, v2, v17
	v_max_u32_e32 v6, v16, v18
	v_max_u32_e32 v10, v10, v19
	v_max_u32_e32 v13, v13, v20
	v_max_u32_e32 v7, v7, v21
	v_max_u32_e32 v14, v14, v22
	v_max_u32_e32 v5, v5, v23
	v_max_u32_e32 v9, v9, v24
	v_max_u32_e32 v11, v11, v25
	v_max_u32_e32 v12, v12, v26
	v_max_u32_e32 v3, v3, v27
	v_max_u32_e32 v8, v8, v28
	v_max_u32_e32 v4, v4, v29
	v_max_u32_e32 v15, v15, v30
	v_max_u32_e32 v0, v0, v31
	v_max_u32_e32 v16, v1, v9
	v_min_u32_e32 v1, v1, v9
	v_max_u32_e32 v9, v2, v11
	v_min_u32_e32 v2, v2, v11
	v_max_u32_e32 v11, v6, v12
	v_min_u32_e32 v6, v6, v12
	v_max_u32_e32 v12, v10, v3
	v_min_u32_e32 v3, v10, v3
	v_max_u32_e32 v10, v13, v8
	v_min_u32_e32 v8, v13, v8
	v_max_u32_e32 v13, v7, v4
	v_min_u32_e32 v4, v7, v4
	v_max_u32_e32 v7, v14, v15
	v_min_u32_e32 v14, v14, v15
	v_max_u32_e32 v15, v5, v0
	v_min_u32_e32 v0, v5, v0
	v_max_u32_e32 v5, v16, v10
	v_min_u32_e32 v10, v16, v10
	v_max_u32_e32 v16, v9, v13
	v_min_u32_e32 v9, v9, v13
	v_max_u32_e32 v13, v11, v7
	v_min_u32_e32 v7, v11, v7
	v_max_u32_e32 v11, v12, v15
	v_min_u32_e32 v12, v12, v15
	v_max_u32_e32 v15, v1, v8
	v_min_u32_e32 v1, v1, v8
	v_max_u32_e32 v8, v2, v4
	v_min_u32_e32 v2, v2, v4
	v_max_u32_e32 v4, v6, v14
	v_min_u32_e32 v6, v6, v14
	v_max_u32_e32 v14, v3, v0
	v_min_u32_e32 v0, v3, v0
	v_max_u32_e32 v3, v5, v13
	v_min_u32_e32 v5, v5, v13
	v_max_u32_e32 v13, v16, v11
	v_min_u32_e32 v11, v16, v11
	v_max_u32_e32 v16, v10, v7
	v_min_u32_e32 v7, v10, v7
	v_max_u32_e32 v10, v9, v12
	v_min_u32_e32 v9, v9, v12
	v_max_u32_e32 v12, v15, v4
	v_min_u32_e32 v4, v15, v4
	v_max_u32_e32 v15, v8, v14
	v_min_u32_e32 v8, v8, v14
	v_max_u32_e32 v14, v1, v6
	v_min_u32_e32 v1, v1, v6
	v_max_u32_e32 v6, v2, v0
	v_min_u32_e32 v0, v2, v0
	v_max_u32_e32 v2, v3, v13
	v_min_u32_e32 v3, v3, v13
	v_max_u32_e32 v13, v5, v11
	v_min_u32_e32 v5, v5, v11
	v_max_u32_e32 v11, v16, v10
	v_min_u32_e32 v10, v16, v10
	v_max_u32_e32 v16, v7, v9
	v_min_u32_e32 v7, v7, v9
	v_max_u32_e32 v9, v12, v15
	v_min_u32_e32 v12, v12, v15
	v_max_u32_e32 v15, v4, v8
	v_min_u32_e32 v17, v4, v8
	v_max_u32_e32 v18, v14, v6
	v_min_u32_e32 v14, v14, v6
	v_max_u32_e32 v19, v1, v0
	v_min_u32_e32 v20, v1, v0
	s_nop 1
	v_mov_b32_dpp v0, v20 quad_perm:[2,3,0,1] row_mask:0xf bank_mask:0xf
	v_mov_b32_dpp v1, v19 quad_perm:[2,3,0,1] row_mask:0xf bank_mask:0xf
	v_mov_b32_dpp v4, v14 quad_perm:[2,3,0,1] row_mask:0xf bank_mask:0xf
	v_mov_b32_dpp v6, v18 quad_perm:[2,3,0,1] row_mask:0xf bank_mask:0xf
	v_mov_b32_dpp v8, v17 quad_perm:[2,3,0,1] row_mask:0xf bank_mask:0xf
	v_mov_b32_dpp v21, v15 quad_perm:[2,3,0,1] row_mask:0xf bank_mask:0xf
	v_mov_b32_dpp v22, v12 quad_perm:[2,3,0,1] row_mask:0xf bank_mask:0xf
	v_mov_b32_dpp v23, v9 quad_perm:[2,3,0,1] row_mask:0xf bank_mask:0xf
	v_mov_b32_dpp v24, v7 quad_perm:[2,3,0,1] row_mask:0xf bank_mask:0xf
	v_mov_b32_dpp v25, v16 quad_perm:[2,3,0,1] row_mask:0xf bank_mask:0xf
	v_mov_b32_dpp v26, v10 quad_perm:[2,3,0,1] row_mask:0xf bank_mask:0xf
	v_mov_b32_dpp v27, v11 quad_perm:[2,3,0,1] row_mask:0xf bank_mask:0xf
	v_mov_b32_dpp v28, v5 quad_perm:[2,3,0,1] row_mask:0xf bank_mask:0xf
	v_mov_b32_dpp v29, v13 quad_perm:[2,3,0,1] row_mask:0xf bank_mask:0xf
	v_mov_b32_dpp v30, v3 quad_perm:[2,3,0,1] row_mask:0xf bank_mask:0xf
	v_mov_b32_dpp v31, v2 quad_perm:[2,3,0,1] row_mask:0xf bank_mask:0xf
	s_waitcnt lgkmcnt(0)
	v_max_u32_e32 v0, v2, v0
	v_max_u32_e32 v1, v3, v1
	v_max_u32_e32 v2, v13, v4
	v_max_u32_e32 v3, v5, v6
	v_max_u32_e32 v4, v11, v8
	v_max_u32_e32 v5, v10, v21
	v_max_u32_e32 v6, v16, v22
	v_max_u32_e32 v7, v7, v23
	v_max_u32_e32 v8, v9, v24
	v_max_u32_e32 v9, v12, v25
	v_max_u32_e32 v10, v15, v26
	v_max_u32_e32 v11, v17, v27
	v_max_u32_e32 v12, v18, v28
	v_max_u32_e32 v13, v14, v29
	v_max_u32_e32 v14, v19, v30
	v_max_u32_e32 v15, v20, v31
	v_max_u32_e32 v16, v0, v8
	v_max_u32_e32 v17, v1, v9
	v_max_u32_e32 v18, v2, v10
	v_max_u32_e32 v19, v3, v11
	v_max_u32_e32 v20, v4, v12
	v_max_u32_e32 v21, v5, v13
	v_max_u32_e32 v22, v6, v14
	v_max_u32_e32 v23, v7, v15
	s_or_b64 s[0:1], s[4:5], s[6:7]
	s_or_b64 vcc, s[6:7], s[10:11]
	v_min_u32_e32 v0, v0, v8
	v_min_u32_e32 v1, v1, v9
	v_min_u32_e32 v2, v2, v10
	v_min_u32_e32 v3, v3, v11
	v_min_u32_e32 v4, v4, v12
	v_min_u32_e32 v5, v5, v13
	v_min_u32_e32 v6, v6, v14
	v_min_u32_e32 v7, v7, v15
	v_add_u32_e32 v116, 0xf000, v184
	v_cndmask_b32_e64 v0, v0, v16, s[0:1]
	v_cndmask_b32_e64 v1, v1, v17, s[0:1]
	v_cndmask_b32_e64 v2, v2, v18, s[0:1]
	v_cndmask_b32_e64 v3, v3, v19, s[0:1]
	v_cndmask_b32_e64 v4, v4, v20, s[0:1]
	v_cndmask_b32_e64 v5, v5, v21, s[0:1]
	v_cndmask_b32_e64 v6, v6, v22, s[0:1]
	v_cndmask_b32_e64 v7, v7, v23, s[0:1]
	v_max_u32_e32 v8, v0, v4
	v_max_u32_e32 v9, v1, v5
	v_max_u32_e32 v10, v2, v6
	v_max_u32_e32 v11, v3, v7
	v_min_u32_e32 v12, v0, v4
	v_min_u32_e32 v13, v1, v5
	v_min_u32_e32 v14, v2, v6
	v_min_u32_e32 v15, v3, v7
	v_cndmask_b32_e32 v0, v8, v12, vcc
	v_cndmask_b32_e32 v1, v9, v13, vcc
	v_cndmask_b32_e32 v2, v10, v14, vcc
	v_cndmask_b32_e32 v3, v11, v15, vcc
	v_max_u32_e32 v4, v0, v2
	v_min_u32_e32 v5, v0, v2
	v_max_u32_e32 v6, v1, v3
	v_min_u32_e32 v7, v1, v3
	v_max_u32_e32 v0, v4, v6
	v_min_u32_e32 v1, v4, v6
	v_max_u32_e32 v2, v5, v7
	v_min_u32_e32 v3, v5, v7
	v_xor_b32_e32 v0, -1, v0
	v_xor_b32_e32 v1, -1, v1
	v_xor_b32_e32 v2, -1, v2
	v_xor_b32_e32 v3, -1, v3
	v_and_b32_e32 v0, 0x7f, v0
	v_and_b32_e32 v1, 0x7f, v1
	v_and_b32_e32 v2, 0x7f, v2
	v_and_b32_e32 v3, 0x7f, v3
	v_lshl_add_u32 v4, v0, 2, v169
	v_lshl_add_u32 v5, v1, 2, v169
	v_lshl_add_u32 v6, v2, 2, v169
	v_lshl_add_u32 v7, v3, 2, v169
	ds_read_b32 v4, v4 offset:17408
	ds_read_b32 v5, v5 offset:17408
	ds_read_b32 v6, v6 offset:17408
	ds_read_b32 v7, v7 offset:17408
	ds_write_b128 v253, v[0:3] offset:61440
	s_waitcnt lgkmcnt(1)
	ds_write_b128 v253, v[4:7] offset:53248
	s_waitcnt vmcnt(3)
	ds_write_b128 v234, v[96:99]
	s_waitcnt vmcnt(2)
	ds_write_b128 v234, v[100:103] offset:4352
	s_waitcnt vmcnt(1)
	ds_write_b128 v234, v[104:107] offset:8704
	s_waitcnt vmcnt(0)
	ds_write_b128 v234, v[108:111] offset:13056
	s_waitcnt lgkmcnt(0)
	s_barrier
; #define MFMA32(a, b, c) __builtin_amdgcn_mfma_f32_32x32x16_bf16((a), (b), (c), 0, 0, 0)
; #define TK_PREFETCH(t_, p_) do { const int tk0_ = ((t_) >> 3) * 64, hp_ = ((t_) & 7) * 2 + (p_); \
;         _Pragma("unroll") for (int i_ = 0; i_ < 4; ++i_) { const int c_ = tid + 256 * i_; pre[i_] = *(const u32x4*)(qp + (size_t)(tk0_ + (c_ >> 4)) * 2048 + hp_ * 128 + (c_ & 15) * 8); } } while (0)
; DI void topk_phase(unsigned char* smem_, const bf16_t* __restrict__ qp, const bf16_t* __restrict__ keys, int* __restrict__ eidx, float* __restrict__ gate) {
;     ...
;         f32x16 acc[2];
; #pragma unroll
;         for (int i = 0; i < 16; ++i) { acc[0][i] = 0.f; acc[1][i] = 0.f; }
; #pragma unroll
;         for (int ks = 0; ks < 8; ++ks) {
; #pragma unroll
;             for (int th = 0; th < 2; ++th) { const bf16x8 qf = *(const bf16x8*)(As + (32 * th + l31) * LDA + ks * 16 + hi * 8); acc[th] = MFMA32(kf[p][ks], qf, acc[th]); }
;         }
; #pragma unroll
;         for (int th = 0; th < 2; ++th)
; #pragma unroll
;             for (int g = 0; g < 4; ++g) { f32x4 o; o.x = acc[th][4 * g]; o.y = acc[th][4 * g + 1]; o.z = acc[th][4 * g + 2]; o.w = acc[th][4 * g + 3]; *(f32x4*)(S + (32 * th + l31) * LDS_ + 32 * wid + 8 * g + 4 * hi) = o; }
;         __syncthreads();
;         if (p == 0) TK_PREFETCH(t, 1); else if (t + G < NT) TK_PREFETCH(t + G, 0);
;         unsigned v[32];
; #pragma unroll
;         for (int i = 0; i < 8; ++i) {
;             const f32x4 sv4 = *(const f32x4*)(S + row * LDS_ + 32 * q + 4 * i);
	ds_read_b128 v[0:3], v235
	ds_read_b128 v[118:121], v235 offset:32
	s_waitcnt lgkmcnt(1)
	v_mfma_f32_32x32x16_bf16 v[16:31], v[64:67], v[0:3], 0
	ds_read_b128 v[0:3], v235 offset:8704
	s_add_i32 s18, s18, s82
	s_cmpk_gt_i32 s18, 0xfff
	s_cselect_b64 s[0:1], -1, 0
	v_readlane_b32 s16, v251, 51
	s_add_i32 s22, s16, s22
	s_and_b64 vcc, exec, s[0:1]
	s_waitcnt lgkmcnt(1)
	v_mfma_f32_32x32x16_bf16 v[16:31], v[68:71], v[118:121], v[16:31]
	ds_read_b128 v[118:121], v235 offset:8736
	s_waitcnt lgkmcnt(1)
	v_mfma_f32_32x32x16_bf16 v[0:15], v[64:67], v[0:3], 0
	s_waitcnt lgkmcnt(0)
	v_mfma_f32_32x32x16_bf16 v[0:15], v[68:71], v[118:121], v[0:15]
	ds_read_b128 v[118:121], v235 offset:64
	s_waitcnt lgkmcnt(0)
	v_mfma_f32_32x32x16_bf16 v[16:31], v[72:75], v[118:121], v[16:31]
	ds_read_b128 v[118:121], v235 offset:8768
	s_waitcnt lgkmcnt(0)
	v_mfma_f32_32x32x16_bf16 v[0:15], v[72:75], v[118:121], v[0:15]
	ds_read_b128 v[118:121], v235 offset:96
	s_waitcnt lgkmcnt(0)
	v_mfma_f32_32x32x16_bf16 v[16:31], v[76:79], v[118:121], v[16:31]
	ds_read_b128 v[118:121], v235 offset:8800
	s_waitcnt lgkmcnt(0)
	v_mfma_f32_32x32x16_bf16 v[0:15], v[76:79], v[118:121], v[0:15]
	ds_read_b128 v[118:121], v235 offset:128
	s_waitcnt lgkmcnt(0)
	v_mfma_f32_32x32x16_bf16 v[16:31], v[80:83], v[118:121], v[16:31]
	ds_read_b128 v[118:121], v235 offset:8832
	s_waitcnt lgkmcnt(0)
	v_mfma_f32_32x32x16_bf16 v[0:15], v[80:83], v[118:121], v[0:15]
	ds_read_b128 v[118:121], v235 offset:160
	s_waitcnt lgkmcnt(0)
	v_mfma_f32_32x32x16_bf16 v[16:31], v[84:87], v[118:121], v[16:31]
	ds_read_b128 v[118:121], v235 offset:8864
	s_waitcnt lgkmcnt(0)
	v_mfma_f32_32x32x16_bf16 v[0:15], v[84:87], v[118:121], v[0:15]
	ds_read_b128 v[118:121], v235 offset:192
	s_waitcnt lgkmcnt(0)
	v_mfma_f32_32x32x16_bf16 v[16:31], v[88:91], v[118:121], v[16:31]
	ds_read_b128 v[118:121], v235 offset:8896
	s_waitcnt lgkmcnt(0)
	v_mfma_f32_32x32x16_bf16 v[0:15], v[88:91], v[118:121], v[0:15]
	ds_read_b128 v[118:121], v235 offset:224
	s_waitcnt lgkmcnt(0)
	v_mfma_f32_32x32x16_bf16 v[16:31], v[92:95], v[118:121], v[16:31]
	ds_read_b128 v[118:121], v235 offset:8928
	s_nop 10
	ds_write_b128 v236, v[16:19] offset:17408
	ds_write_b128 v236, v[20:23] offset:17440
	ds_write_b128 v236, v[24:27] offset:17472
	ds_write_b128 v236, v[28:31] offset:17504
	s_waitcnt lgkmcnt(4)
	v_mfma_f32_32x32x16_bf16 v[0:15], v[92:95], v[118:121], v[0:15]
	s_nop 11
	ds_write_b128 v236, v[0:3] offset:34304
	ds_write_b128 v236, v[4:7] offset:34336
	ds_write_b128 v236, v[8:11] offset:34368
	ds_write_b128 v236, v[12:15] offset:34400
	s_waitcnt lgkmcnt(0)
	s_barrier
	s_cbranch_vccnz .LBB0_67
	s_and_b32 s16, s22, 0xffffffc0
	s_and_b32 s17, s21, 0x700
	v_or_b32_e32 v2, s16, v165
	s_lshl_b32 s60, s17, 1
	v_ashrrev_i32_e32 v3, 31, v2
	v_or_b32_e32 v4, s16, v166
	v_lshl_add_u64 v[0:1], v[114:115], 0, s[60:61]
	v_lshlrev_b64 v[2:3], 12, v[2:3]
	v_ashrrev_i32_e32 v5, 31, v4
	v_lshl_add_u64 v[2:3], v[0:1], 0, v[2:3]
	v_lshlrev_b64 v[4:5], 12, v[4:5]
	v_lshl_add_u64 v[4:5], v[0:1], 0, v[4:5]
	global_load_dwordx4 v[96:99], v[2:3], off
	global_load_dwordx4 v[100:103], v[4:5], off
	v_or_b32_e32 v2, s16, v167
	v_ashrrev_i32_e32 v3, 31, v2
	v_or_b32_e32 v4, s16, v168
	v_lshlrev_b64 v[2:3], 12, v[2:3]
	v_ashrrev_i32_e32 v5, 31, v4
	v_lshl_add_u64 v[2:3], v[0:1], 0, v[2:3]
	v_lshlrev_b64 v[4:5], 12, v[4:5]
	v_lshl_add_u64 v[0:1], v[0:1], 0, v[4:5]
	global_load_dwordx4 v[104:107], v[2:3], off
	global_load_dwordx4 v[108:111], v[0:1], off
.LBB0_67:
	ds_read_b128 v[0:3], v171 offset:17408
	ds_read_b128 v[4:7], v171 offset:17424
	ds_read_b128 v[8:11], v171 offset:17440
	ds_read_b128 v[12:15], v171 offset:17456
	s_waitcnt lgkmcnt(3)
	v_ashrrev_i32_e32 v16, 31, v0


; DI unsigned fkey(float f) { const unsigned u = __float_as_uint(f); return (u & 0x80000000u) ? ~u : (u | 0x80000000u); }
; DI void topk_phase(unsigned char* smem_, const bf16_t* __restrict__ qp, const bf16_t* __restrict__ keys, int* __restrict__ eidx, float* __restrict__ gate) {
;     ...
;         for (int i = 0; i < 8; ++i) {
;             const f32x4 sv4 = *(const f32x4*)(S + row * LDS_ + 32 * q + 4 * i);
;             const int ib = 127 - (32 * q + 4 * i);
;             v[4 * i] = (fkey(sv4.x) & ~127u) | (unsigned)ib; v[4 * i + 1] = (fkey(sv4.y) & ~127u) | (unsigned)(ib - 1);
;             v[4 * i + 2] = (fkey(sv4.z) & ~127u) | (unsigned)(ib - 2); v[4 * i + 3] = (fkey(sv4.w) & ~127u) | (unsigned)(ib - 3);
;         }
	s_nop 1
	v_bitop3_b32 v0, v16, s98, v0 bitop3:0x56
	v_and_b32_e32 v0, 0xffffff80, v0
	v_sub_u32_e32 v0, v0, v170
	v_add_u32_e32 v16, 0x7f, v0
	v_not_b32_e32 v0, v1
	v_or_b32_e32 v17, 0x80000000, v1
	v_cmp_gt_i32_e32 vcc, 0, v1
	v_ashrrev_i32_e32 v1, 31, v2
	s_nop 0
	v_cndmask_b32_e32 v0, v17, v0, vcc
	v_and_b32_e32 v0, 0xffffff80, v0
	v_sub_u32_e32 v0, v0, v170
	v_add_u32_e32 v17, 0x7e, v0


; DI unsigned fkey(float f) { const unsigned u = __float_as_uint(f); return (u & 0x80000000u) ? ~u : (u | 0x80000000u); }
; DI void topk_phase(unsigned char* smem_, const bf16_t* __restrict__ qp, const bf16_t* __restrict__ keys, int* __restrict__ eidx, float* __restrict__ gate) {
;     ...
;         for (int i = 0; i < 8; ++i) {
;             const f32x4 sv4 = *(const f32x4*)(S + row * LDS_ + 32 * q + 4 * i);
;             const int ib = 127 - (32 * q + 4 * i);
;             v[4 * i] = (fkey(sv4.x) & ~127u) | (unsigned)ib; v[4 * i + 1] = (fkey(sv4.y) & ~127u) | (unsigned)(ib - 1);
;             v[4 * i + 2] = (fkey(sv4.z) & ~127u) | (unsigned)(ib - 2); v[4 * i + 3] = (fkey(sv4.w) & ~127u) | (unsigned)(ib - 3);
;         }
	s_nop 1
	v_bitop3_b32 v0, v1, s98, v2 bitop3:0x56
	v_and_b32_e32 v0, 0xffffff80, v0
	v_sub_u32_e32 v0, v0, v170
	v_add_u32_e32 v18, 0x7d, v0
	v_ashrrev_i32_e32 v0, 31, v3


; DI unsigned fkey(float f) { const unsigned u = __float_as_uint(f); return (u & 0x80000000u) ? ~u : (u | 0x80000000u); }
; DI void topk_phase(unsigned char* smem_, const bf16_t* __restrict__ qp, const bf16_t* __restrict__ keys, int* __restrict__ eidx, float* __restrict__ gate) {
;     ...
;         for (int i = 0; i < 8; ++i) {
;             const f32x4 sv4 = *(const f32x4*)(S + row * LDS_ + 32 * q + 4 * i);
;             const int ib = 127 - (32 * q + 4 * i);
;             v[4 * i] = (fkey(sv4.x) & ~127u) | (unsigned)ib; v[4 * i + 1] = (fkey(sv4.y) & ~127u) | (unsigned)(ib - 1);
;             v[4 * i + 2] = (fkey(sv4.z) & ~127u) | (unsigned)(ib - 2); v[4 * i + 3] = (fkey(sv4.w) & ~127u) | (unsigned)(ib - 3);
;         }
	s_nop 1
	v_bitop3_b32 v0, v0, s98, v3 bitop3:0x56
	v_and_b32_e32 v0, 0xffffff80, v0
	v_sub_u32_e32 v0, v0, v170
	v_add_u32_e32 v19, 0x7c, v0
	s_waitcnt lgkmcnt(2)
	v_ashrrev_i32_e32 v0, 31, v4


; DI unsigned fkey(float f) { const unsigned u = __float_as_uint(f); return (u & 0x80000000u) ? ~u : (u | 0x80000000u); }
; DI void topk_phase(unsigned char* smem_, const bf16_t* __restrict__ qp, const bf16_t* __restrict__ keys, int* __restrict__ eidx, float* __restrict__ gate) {
;     ...
;         for (int i = 0; i < 8; ++i) {
;             const f32x4 sv4 = *(const f32x4*)(S + row * LDS_ + 32 * q + 4 * i);
;             const int ib = 127 - (32 * q + 4 * i);
;             v[4 * i] = (fkey(sv4.x) & ~127u) | (unsigned)ib; v[4 * i + 1] = (fkey(sv4.y) & ~127u) | (unsigned)(ib - 1);
;             v[4 * i + 2] = (fkey(sv4.z) & ~127u) | (unsigned)(ib - 2); v[4 * i + 3] = (fkey(sv4.w) & ~127u) | (unsigned)(ib - 3);
;         }
	s_nop 1
	v_bitop3_b32 v0, v0, s98, v4 bitop3:0x56
	v_and_b32_e32 v0, 0xffffff80, v0
	v_sub_u32_e32 v0, v0, v177
	v_add_u32_e32 v20, 0x7f, v0
	v_ashrrev_i32_e32 v0, 31, v5


; DI unsigned fkey(float f) { const unsigned u = __float_as_uint(f); return (u & 0x80000000u) ? ~u : (u | 0x80000000u); }
; DI void topk_phase(unsigned char* smem_, const bf16_t* __restrict__ qp, const bf16_t* __restrict__ keys, int* __restrict__ eidx, float* __restrict__ gate) {
;     ...
;         for (int i = 0; i < 8; ++i) {
;             const f32x4 sv4 = *(const f32x4*)(S + row * LDS_ + 32 * q + 4 * i);
;             const int ib = 127 - (32 * q + 4 * i);
;             v[4 * i] = (fkey(sv4.x) & ~127u) | (unsigned)ib; v[4 * i + 1] = (fkey(sv4.y) & ~127u) | (unsigned)(ib - 1);
;             v[4 * i + 2] = (fkey(sv4.z) & ~127u) | (unsigned)(ib - 2); v[4 * i + 3] = (fkey(sv4.w) & ~127u) | (unsigned)(ib - 3);
;         }
	s_nop 1
	v_bitop3_b32 v0, v0, s98, v5 bitop3:0x56
	v_and_b32_e32 v0, 0xffffff80, v0
	v_sub_u32_e32 v0, v0, v177
	v_add_u32_e32 v21, 0x7e, v0
	v_ashrrev_i32_e32 v0, 31, v6


; DI unsigned fkey(float f) { const unsigned u = __float_as_uint(f); return (u & 0x80000000u) ? ~u : (u | 0x80000000u); }
; DI void topk_phase(unsigned char* smem_, const bf16_t* __restrict__ qp, const bf16_t* __restrict__ keys, int* __restrict__ eidx, float* __restrict__ gate) {
;     ...
;         for (int i = 0; i < 8; ++i) {
;             const f32x4 sv4 = *(const f32x4*)(S + row * LDS_ + 32 * q + 4 * i);
;             const int ib = 127 - (32 * q + 4 * i);
;             v[4 * i] = (fkey(sv4.x) & ~127u) | (unsigned)ib; v[4 * i + 1] = (fkey(sv4.y) & ~127u) | (unsigned)(ib - 1);
;             v[4 * i + 2] = (fkey(sv4.z) & ~127u) | (unsigned)(ib - 2); v[4 * i + 3] = (fkey(sv4.w) & ~127u) | (unsigned)(ib - 3);
;         }
	s_nop 1
	v_bitop3_b32 v0, v0, s98, v6 bitop3:0x56
	v_and_b32_e32 v0, 0xffffff80, v0
	v_sub_u32_e32 v0, v0, v177
	v_add_u32_e32 v22, 0x7d, v0
	v_ashrrev_i32_e32 v0, 31, v7


; DI unsigned fkey(float f) { const unsigned u = __float_as_uint(f); return (u & 0x80000000u) ? ~u : (u | 0x80000000u); }
; DI void topk_phase(unsigned char* smem_, const bf16_t* __restrict__ qp, const bf16_t* __restrict__ keys, int* __restrict__ eidx, float* __restrict__ gate) {
;     ...
;         for (int i = 0; i < 8; ++i) {
;             const f32x4 sv4 = *(const f32x4*)(S + row * LDS_ + 32 * q + 4 * i);
;             const int ib = 127 - (32 * q + 4 * i);
;             v[4 * i] = (fkey(sv4.x) & ~127u) | (unsigned)ib; v[4 * i + 1] = (fkey(sv4.y) & ~127u) | (unsigned)(ib - 1);
;             v[4 * i + 2] = (fkey(sv4.z) & ~127u) | (unsigned)(ib - 2); v[4 * i + 3] = (fkey(sv4.w) & ~127u) | (unsigned)(ib - 3);
;         }
	s_nop 1
	v_bitop3_b32 v0, v0, s98, v7 bitop3:0x56
	v_and_b32_e32 v0, 0xffffff80, v0
	v_sub_u32_e32 v0, v0, v177
	v_add_u32_e32 v23, 0x7c, v0
	s_waitcnt lgkmcnt(1)
	v_ashrrev_i32_e32 v0, 31, v8


; DI unsigned fkey(float f) { const unsigned u = __float_as_uint(f); return (u & 0x80000000u) ? ~u : (u | 0x80000000u); }
; DI void topk_phase(unsigned char* smem_, const bf16_t* __restrict__ qp, const bf16_t* __restrict__ keys, int* __restrict__ eidx, float* __restrict__ gate) {
;     ...
;         for (int i = 0; i < 8; ++i) {
;             const f32x4 sv4 = *(const f32x4*)(S + row * LDS_ + 32 * q + 4 * i);
;             const int ib = 127 - (32 * q + 4 * i);
;             v[4 * i] = (fkey(sv4.x) & ~127u) | (unsigned)ib; v[4 * i + 1] = (fkey(sv4.y) & ~127u) | (unsigned)(ib - 1);
;             v[4 * i + 2] = (fkey(sv4.z) & ~127u) | (unsigned)(ib - 2); v[4 * i + 3] = (fkey(sv4.w) & ~127u) | (unsigned)(ib - 3);
;         }
	s_nop 1
	v_bitop3_b32 v0, v0, s98, v8 bitop3:0x56
	v_and_b32_e32 v0, 0xffffff80, v0
	v_sub_u32_e32 v0, v0, v178
	v_add_u32_e32 v8, 0x7f, v0
	v_ashrrev_i32_e32 v0, 31, v9


; DI unsigned fkey(float f) { const unsigned u = __float_as_uint(f); return (u & 0x80000000u) ? ~u : (u | 0x80000000u); }
; DI void topk_phase(unsigned char* smem_, const bf16_t* __restrict__ qp, const bf16_t* __restrict__ keys, int* __restrict__ eidx, float* __restrict__ gate) {
;     ...
;         for (int i = 0; i < 8; ++i) {
;             const f32x4 sv4 = *(const f32x4*)(S + row * LDS_ + 32 * q + 4 * i);
;             const int ib = 127 - (32 * q + 4 * i);
;             v[4 * i] = (fkey(sv4.x) & ~127u) | (unsigned)ib; v[4 * i + 1] = (fkey(sv4.y) & ~127u) | (unsigned)(ib - 1);
;             v[4 * i + 2] = (fkey(sv4.z) & ~127u) | (unsigned)(ib - 2); v[4 * i + 3] = (fkey(sv4.w) & ~127u) | (unsigned)(ib - 3);
;         }
	s_nop 1
	v_bitop3_b32 v0, v0, s98, v9 bitop3:0x56
	v_and_b32_e32 v0, 0xffffff80, v0
	v_sub_u32_e32 v0, v0, v178
	v_add_u32_e32 v9, 0x7e, v0
	v_ashrrev_i32_e32 v0, 31, v10


; DI unsigned fkey(float f) { const unsigned u = __float_as_uint(f); return (u & 0x80000000u) ? ~u : (u | 0x80000000u); }
; DI void topk_phase(unsigned char* smem_, const bf16_t* __restrict__ qp, const bf16_t* __restrict__ keys, int* __restrict__ eidx, float* __restrict__ gate) {
;     ...
;         for (int i = 0; i < 8; ++i) {
;             const f32x4 sv4 = *(const f32x4*)(S + row * LDS_ + 32 * q + 4 * i);
;             const int ib = 127 - (32 * q + 4 * i);
;             v[4 * i] = (fkey(sv4.x) & ~127u) | (unsigned)ib; v[4 * i + 1] = (fkey(sv4.y) & ~127u) | (unsigned)(ib - 1);
;             v[4 * i + 2] = (fkey(sv4.z) & ~127u) | (unsigned)(ib - 2); v[4 * i + 3] = (fkey(sv4.w) & ~127u) | (unsigned)(ib - 3);
;         }
	s_nop 1
	v_bitop3_b32 v0, v0, s98, v10 bitop3:0x56
	v_and_b32_e32 v0, 0xffffff80, v0
	v_sub_u32_e32 v0, v0, v178
	v_add_u32_e32 v10, 0x7d, v0
	v_ashrrev_i32_e32 v0, 31, v11


; DI unsigned fkey(float f) { const unsigned u = __float_as_uint(f); return (u & 0x80000000u) ? ~u : (u | 0x80000000u); }
; DI void topk_phase(unsigned char* smem_, const bf16_t* __restrict__ qp, const bf16_t* __restrict__ keys, int* __restrict__ eidx, float* __restrict__ gate) {
;     ...
;         for (int i = 0; i < 8; ++i) {
;             const f32x4 sv4 = *(const f32x4*)(S + row * LDS_ + 32 * q + 4 * i);
;             const int ib = 127 - (32 * q + 4 * i);
;             v[4 * i] = (fkey(sv4.x) & ~127u) | (unsigned)ib; v[4 * i + 1] = (fkey(sv4.y) & ~127u) | (unsigned)(ib - 1);
;             v[4 * i + 2] = (fkey(sv4.z) & ~127u) | (unsigned)(ib - 2); v[4 * i + 3] = (fkey(sv4.w) & ~127u) | (unsigned)(ib - 3);
;         }
	s_nop 1
	v_bitop3_b32 v0, v0, s98, v11 bitop3:0x56
	v_and_b32_e32 v0, 0xffffff80, v0
	v_sub_u32_e32 v0, v0, v178
	v_add_u32_e32 v11, 0x7c, v0
	s_waitcnt lgkmcnt(0)
	v_ashrrev_i32_e32 v0, 31, v12


; DI unsigned fkey(float f) { const unsigned u = __float_as_uint(f); return (u & 0x80000000u) ? ~u : (u | 0x80000000u); }
; DI void topk_phase(unsigned char* smem_, const bf16_t* __restrict__ qp, const bf16_t* __restrict__ keys, int* __restrict__ eidx, float* __restrict__ gate) {
;     ...
;         for (int i = 0; i < 8; ++i) {
;             const f32x4 sv4 = *(const f32x4*)(S + row * LDS_ + 32 * q + 4 * i);
;             const int ib = 127 - (32 * q + 4 * i);
;             v[4 * i] = (fkey(sv4.x) & ~127u) | (unsigned)ib; v[4 * i + 1] = (fkey(sv4.y) & ~127u) | (unsigned)(ib - 1);
;             v[4 * i + 2] = (fkey(sv4.z) & ~127u) | (unsigned)(ib - 2); v[4 * i + 3] = (fkey(sv4.w) & ~127u) | (unsigned)(ib - 3);
;         }
	s_nop 1
	v_bitop3_b32 v0, v0, s98, v12 bitop3:0x56
	v_and_b32_e32 v0, 0xffffff80, v0
	v_sub_u32_e32 v0, v0, v179
	v_add_u32_e32 v12, 0x7f, v0
	v_ashrrev_i32_e32 v0, 31, v13


; DI unsigned fkey(float f) { const unsigned u = __float_as_uint(f); return (u & 0x80000000u) ? ~u : (u | 0x80000000u); }
; DI void topk_phase(unsigned char* smem_, const bf16_t* __restrict__ qp, const bf16_t* __restrict__ keys, int* __restrict__ eidx, float* __restrict__ gate) {
;     ...
;         for (int i = 0; i < 8; ++i) {
;             const f32x4 sv4 = *(const f32x4*)(S + row * LDS_ + 32 * q + 4 * i);
;             const int ib = 127 - (32 * q + 4 * i);
;             v[4 * i] = (fkey(sv4.x) & ~127u) | (unsigned)ib; v[4 * i + 1] = (fkey(sv4.y) & ~127u) | (unsigned)(ib - 1);
;             v[4 * i + 2] = (fkey(sv4.z) & ~127u) | (unsigned)(ib - 2); v[4 * i + 3] = (fkey(sv4.w) & ~127u) | (unsigned)(ib - 3);
;         }
	s_nop 1
	v_bitop3_b32 v0, v0, s98, v13 bitop3:0x56
	v_and_b32_e32 v0, 0xffffff80, v0
	v_sub_u32_e32 v0, v0, v179
	v_add_u32_e32 v13, 0x7e, v0
	v_ashrrev_i32_e32 v0, 31, v14


; DI unsigned fkey(float f) { const unsigned u = __float_as_uint(f); return (u & 0x80000000u) ? ~u : (u | 0x80000000u); }
; DI void topk_phase(unsigned char* smem_, const bf16_t* __restrict__ qp, const bf16_t* __restrict__ keys, int* __restrict__ eidx, float* __restrict__ gate) {
;     ...
;         for (int i = 0; i < 8; ++i) {
;             const f32x4 sv4 = *(const f32x4*)(S + row * LDS_ + 32 * q + 4 * i);
;             const int ib = 127 - (32 * q + 4 * i);
;             v[4 * i] = (fkey(sv4.x) & ~127u) | (unsigned)ib; v[4 * i + 1] = (fkey(sv4.y) & ~127u) | (unsigned)(ib - 1);
;             v[4 * i + 2] = (fkey(sv4.z) & ~127u) | (unsigned)(ib - 2); v[4 * i + 3] = (fkey(sv4.w) & ~127u) | (unsigned)(ib - 3);
;         }
	s_nop 1
	v_bitop3_b32 v0, v0, s98, v14 bitop3:0x56
	v_and_b32_e32 v0, 0xffffff80, v0
	v_sub_u32_e32 v0, v0, v179
	v_add_u32_e32 v14, 0x7d, v0
	v_ashrrev_i32_e32 v0, 31, v15


; DI unsigned fkey(float f) { const unsigned u = __float_as_uint(f); return (u & 0x80000000u) ? ~u : (u | 0x80000000u); }
; DI void topk_phase(unsigned char* smem_, const bf16_t* __restrict__ qp, const bf16_t* __restrict__ keys, int* __restrict__ eidx, float* __restrict__ gate) {
;     ...
;         for (int i = 0; i < 8; ++i) {
;             const f32x4 sv4 = *(const f32x4*)(S + row * LDS_ + 32 * q + 4 * i);
;             const int ib = 127 - (32 * q + 4 * i);
;             v[4 * i] = (fkey(sv4.x) & ~127u) | (unsigned)ib; v[4 * i + 1] = (fkey(sv4.y) & ~127u) | (unsigned)(ib - 1);
;             v[4 * i + 2] = (fkey(sv4.z) & ~127u) | (unsigned)(ib - 2); v[4 * i + 3] = (fkey(sv4.w) & ~127u) | (unsigned)(ib - 3);
;         }
	s_nop 1
	v_bitop3_b32 v4, v0, s98, v15 bitop3:0x56
	ds_read_b128 v[0:3], v171 offset:17472
	v_and_b32_e32 v4, 0xffffff80, v4
	v_sub_u32_e32 v4, v4, v179
	v_add_u32_e32 v15, 0x7c, v4
	ds_read_b128 v[4:7], v171 offset:17488
	s_waitcnt lgkmcnt(1)
	v_ashrrev_i32_e32 v24, 31, v0


; DI unsigned fkey(float f) { const unsigned u = __float_as_uint(f); return (u & 0x80000000u) ? ~u : (u | 0x80000000u); }
; DI void topk_phase(unsigned char* smem_, const bf16_t* __restrict__ qp, const bf16_t* __restrict__ keys, int* __restrict__ eidx, float* __restrict__ gate) {
;     ...
;         for (int i = 0; i < 8; ++i) {
;             const f32x4 sv4 = *(const f32x4*)(S + row * LDS_ + 32 * q + 4 * i);
;             const int ib = 127 - (32 * q + 4 * i);
;             v[4 * i] = (fkey(sv4.x) & ~127u) | (unsigned)ib; v[4 * i + 1] = (fkey(sv4.y) & ~127u) | (unsigned)(ib - 1);
;             v[4 * i + 2] = (fkey(sv4.z) & ~127u) | (unsigned)(ib - 2); v[4 * i + 3] = (fkey(sv4.w) & ~127u) | (unsigned)(ib - 3);
;         }
	s_nop 1
	v_bitop3_b32 v0, v24, s98, v0 bitop3:0x56
	v_and_b32_e32 v0, 0xffffff80, v0
	v_sub_u32_e32 v0, v0, v180
	v_add_u32_e32 v24, 0x7f, v0
	v_not_b32_e32 v0, v1
	v_or_b32_e32 v25, 0x80000000, v1
	v_cmp_gt_i32_e32 vcc, 0, v1
	v_ashrrev_i32_e32 v1, 31, v2
	s_nop 0
	v_cndmask_b32_e32 v0, v25, v0, vcc
	v_and_b32_e32 v0, 0xffffff80, v0
	v_sub_u32_e32 v0, v0, v180
	v_add_u32_e32 v25, 0x7e, v0


; DI unsigned fkey(float f) { const unsigned u = __float_as_uint(f); return (u & 0x80000000u) ? ~u : (u | 0x80000000u); }
; DI void topk_phase(unsigned char* smem_, const bf16_t* __restrict__ qp, const bf16_t* __restrict__ keys, int* __restrict__ eidx, float* __restrict__ gate) {
;     ...
;         for (int i = 0; i < 8; ++i) {
;             const f32x4 sv4 = *(const f32x4*)(S + row * LDS_ + 32 * q + 4 * i);
;             const int ib = 127 - (32 * q + 4 * i);
;             v[4 * i] = (fkey(sv4.x) & ~127u) | (unsigned)ib; v[4 * i + 1] = (fkey(sv4.y) & ~127u) | (unsigned)(ib - 1);
;             v[4 * i + 2] = (fkey(sv4.z) & ~127u) | (unsigned)(ib - 2); v[4 * i + 3] = (fkey(sv4.w) & ~127u) | (unsigned)(ib - 3);
;         }
	s_nop 1
	v_bitop3_b32 v0, v1, s98, v2 bitop3:0x56
	v_and_b32_e32 v0, 0xffffff80, v0
	v_sub_u32_e32 v0, v0, v180
	v_add_u32_e32 v26, 0x7d, v0
	v_ashrrev_i32_e32 v0, 31, v3


; DI unsigned fkey(float f) { const unsigned u = __float_as_uint(f); return (u & 0x80000000u) ? ~u : (u | 0x80000000u); }
; DI void topk_phase(unsigned char* smem_, const bf16_t* __restrict__ qp, const bf16_t* __restrict__ keys, int* __restrict__ eidx, float* __restrict__ gate) {
;     ...
;         for (int i = 0; i < 8; ++i) {
;             const f32x4 sv4 = *(const f32x4*)(S + row * LDS_ + 32 * q + 4 * i);
;             const int ib = 127 - (32 * q + 4 * i);
;             v[4 * i] = (fkey(sv4.x) & ~127u) | (unsigned)ib; v[4 * i + 1] = (fkey(sv4.y) & ~127u) | (unsigned)(ib - 1);
;             v[4 * i + 2] = (fkey(sv4.z) & ~127u) | (unsigned)(ib - 2); v[4 * i + 3] = (fkey(sv4.w) & ~127u) | (unsigned)(ib - 3);
;         }
	s_nop 1
	v_bitop3_b32 v0, v0, s98, v3 bitop3:0x56
	v_and_b32_e32 v0, 0xffffff80, v0
	v_sub_u32_e32 v0, v0, v180
	v_add_u32_e32 v27, 0x7c, v0
	s_waitcnt lgkmcnt(0)
	v_ashrrev_i32_e32 v0, 31, v4


; DI unsigned fkey(float f) { const unsigned u = __float_as_uint(f); return (u & 0x80000000u) ? ~u : (u | 0x80000000u); }
; DI void topk_phase(unsigned char* smem_, const bf16_t* __restrict__ qp, const bf16_t* __restrict__ keys, int* __restrict__ eidx, float* __restrict__ gate) {
;     ...
;         for (int i = 0; i < 8; ++i) {
;             const f32x4 sv4 = *(const f32x4*)(S + row * LDS_ + 32 * q + 4 * i);
;             const int ib = 127 - (32 * q + 4 * i);
;             v[4 * i] = (fkey(sv4.x) & ~127u) | (unsigned)ib; v[4 * i + 1] = (fkey(sv4.y) & ~127u) | (unsigned)(ib - 1);
;             v[4 * i + 2] = (fkey(sv4.z) & ~127u) | (unsigned)(ib - 2); v[4 * i + 3] = (fkey(sv4.w) & ~127u) | (unsigned)(ib - 3);
;         }
	s_nop 1
	v_bitop3_b32 v0, v0, s98, v4 bitop3:0x56
	v_and_b32_e32 v0, 0xffffff80, v0
	v_sub_u32_e32 v0, v0, v181
	v_add_u32_e32 v28, 0x7f, v0
	v_ashrrev_i32_e32 v0, 31, v5


; DI unsigned fkey(float f) { const unsigned u = __float_as_uint(f); return (u & 0x80000000u) ? ~u : (u | 0x80000000u); }
; DI void topk_phase(unsigned char* smem_, const bf16_t* __restrict__ qp, const bf16_t* __restrict__ keys, int* __restrict__ eidx, float* __restrict__ gate) {
;     ...
;         for (int i = 0; i < 8; ++i) {
;             const f32x4 sv4 = *(const f32x4*)(S + row * LDS_ + 32 * q + 4 * i);
;             const int ib = 127 - (32 * q + 4 * i);
;             v[4 * i] = (fkey(sv4.x) & ~127u) | (unsigned)ib; v[4 * i + 1] = (fkey(sv4.y) & ~127u) | (unsigned)(ib - 1);
;             v[4 * i + 2] = (fkey(sv4.z) & ~127u) | (unsigned)(ib - 2); v[4 * i + 3] = (fkey(sv4.w) & ~127u) | (unsigned)(ib - 3);
;         }
	s_nop 1
	v_bitop3_b32 v0, v0, s98, v5 bitop3:0x56
	v_and_b32_e32 v0, 0xffffff80, v0
	v_sub_u32_e32 v0, v0, v181
	v_add_u32_e32 v29, 0x7e, v0
	v_ashrrev_i32_e32 v0, 31, v6


; DI unsigned fkey(float f) { const unsigned u = __float_as_uint(f); return (u & 0x80000000u) ? ~u : (u | 0x80000000u); }
; DI void topk_phase(unsigned char* smem_, const bf16_t* __restrict__ qp, const bf16_t* __restrict__ keys, int* __restrict__ eidx, float* __restrict__ gate) {
;     ...
;         for (int i = 0; i < 8; ++i) {
;             const f32x4 sv4 = *(const f32x4*)(S + row * LDS_ + 32 * q + 4 * i);
;             const int ib = 127 - (32 * q + 4 * i);
;             v[4 * i] = (fkey(sv4.x) & ~127u) | (unsigned)ib; v[4 * i + 1] = (fkey(sv4.y) & ~127u) | (unsigned)(ib - 1);
;             v[4 * i + 2] = (fkey(sv4.z) & ~127u) | (unsigned)(ib - 2); v[4 * i + 3] = (fkey(sv4.w) & ~127u) | (unsigned)(ib - 3);
;         }
	s_nop 1
	v_bitop3_b32 v0, v0, s98, v6 bitop3:0x56
	v_and_b32_e32 v0, 0xffffff80, v0
	v_sub_u32_e32 v0, v0, v181
	v_add_u32_e32 v30, 0x7d, v0
	v_ashrrev_i32_e32 v0, 31, v7


; DI unsigned fkey(float f) { const unsigned u = __float_as_uint(f); return (u & 0x80000000u) ? ~u : (u | 0x80000000u); }
; DI void topk_phase(unsigned char* smem_, const bf16_t* __restrict__ qp, const bf16_t* __restrict__ keys, int* __restrict__ eidx, float* __restrict__ gate) {
;     ...
;         for (int i = 0; i < 8; ++i) {
;             const f32x4 sv4 = *(const f32x4*)(S + row * LDS_ + 32 * q + 4 * i);
;             const int ib = 127 - (32 * q + 4 * i);
;             v[4 * i] = (fkey(sv4.x) & ~127u) | (unsigned)ib; v[4 * i + 1] = (fkey(sv4.y) & ~127u) | (unsigned)(ib - 1);
;             v[4 * i + 2] = (fkey(sv4.z) & ~127u) | (unsigned)(ib - 2); v[4 * i + 3] = (fkey(sv4.w) & ~127u) | (unsigned)(ib - 3);
;         }
	s_nop 1
	v_bitop3_b32 v4, v0, s98, v7 bitop3:0x56
	ds_read_b128 v[0:3], v171 offset:17504
	v_and_b32_e32 v4, 0xffffff80, v4
	v_sub_u32_e32 v4, v4, v181
	v_add_u32_e32 v31, 0x7c, v4
	ds_read_b128 v[4:7], v171 offset:17520
	s_waitcnt lgkmcnt(1)
	v_ashrrev_i32_e32 v117, 31, v0


; DI unsigned fkey(float f) { const unsigned u = __float_as_uint(f); return (u & 0x80000000u) ? ~u : (u | 0x80000000u); }
; DI void topk_phase(unsigned char* smem_, const bf16_t* __restrict__ qp, const bf16_t* __restrict__ keys, int* __restrict__ eidx, float* __restrict__ gate) {
;     ...
;         for (int i = 0; i < 8; ++i) {
;             const f32x4 sv4 = *(const f32x4*)(S + row * LDS_ + 32 * q + 4 * i);
;             const int ib = 127 - (32 * q + 4 * i);
;             v[4 * i] = (fkey(sv4.x) & ~127u) | (unsigned)ib; v[4 * i + 1] = (fkey(sv4.y) & ~127u) | (unsigned)(ib - 1);
;             v[4 * i + 2] = (fkey(sv4.z) & ~127u) | (unsigned)(ib - 2); v[4 * i + 3] = (fkey(sv4.w) & ~127u) | (unsigned)(ib - 3);
;         }
	s_nop 1
	v_bitop3_b32 v0, v117, s98, v0 bitop3:0x56
	v_ashrrev_i32_e32 v117, 31, v1


; DI unsigned fkey(float f) { const unsigned u = __float_as_uint(f); return (u & 0x80000000u) ? ~u : (u | 0x80000000u); }
; DI void topk_phase(unsigned char* smem_, const bf16_t* __restrict__ qp, const bf16_t* __restrict__ keys, int* __restrict__ eidx, float* __restrict__ gate) {
;     ...
;         for (int i = 0; i < 8; ++i) {
;             const f32x4 sv4 = *(const f32x4*)(S + row * LDS_ + 32 * q + 4 * i);
;             const int ib = 127 - (32 * q + 4 * i);
;             v[4 * i] = (fkey(sv4.x) & ~127u) | (unsigned)ib; v[4 * i + 1] = (fkey(sv4.y) & ~127u) | (unsigned)(ib - 1);
;             v[4 * i + 2] = (fkey(sv4.z) & ~127u) | (unsigned)(ib - 2); v[4 * i + 3] = (fkey(sv4.w) & ~127u) | (unsigned)(ib - 3);
;         }
	v_and_b32_e32 v0, 0xffffff80, v0
	v_sub_u32_e32 v0, v0, v182
	v_bitop3_b32 v1, v117, s98, v1 bitop3:0x56
	v_ashrrev_i32_e32 v117, 31, v2


; DI unsigned fkey(float f) { const unsigned u = __float_as_uint(f); return (u & 0x80000000u) ? ~u : (u | 0x80000000u); }
; DI void topk_phase(unsigned char* smem_, const bf16_t* __restrict__ qp, const bf16_t* __restrict__ keys, int* __restrict__ eidx, float* __restrict__ gate) {
;     ...
;         for (int i = 0; i < 8; ++i) {
;             const f32x4 sv4 = *(const f32x4*)(S + row * LDS_ + 32 * q + 4 * i);
;             const int ib = 127 - (32 * q + 4 * i);
;             v[4 * i] = (fkey(sv4.x) & ~127u) | (unsigned)ib; v[4 * i + 1] = (fkey(sv4.y) & ~127u) | (unsigned)(ib - 1);
;             v[4 * i + 2] = (fkey(sv4.z) & ~127u) | (unsigned)(ib - 2); v[4 * i + 3] = (fkey(sv4.w) & ~127u) | (unsigned)(ib - 3);
;         }
	v_and_b32_e32 v1, 0xffffff80, v1
	v_sub_u32_e32 v1, v1, v182
	v_bitop3_b32 v2, v117, s98, v2 bitop3:0x56
	v_ashrrev_i32_e32 v117, 31, v3


; DI unsigned fkey(float f) { const unsigned u = __float_as_uint(f); return (u & 0x80000000u) ? ~u : (u | 0x80000000u); }
; DI void topk_phase(unsigned char* smem_, const bf16_t* __restrict__ qp, const bf16_t* __restrict__ keys, int* __restrict__ eidx, float* __restrict__ gate) {
;     ...
;         for (int i = 0; i < 8; ++i) {
;             const f32x4 sv4 = *(const f32x4*)(S + row * LDS_ + 32 * q + 4 * i);
;             const int ib = 127 - (32 * q + 4 * i);
;             v[4 * i] = (fkey(sv4.x) & ~127u) | (unsigned)ib; v[4 * i + 1] = (fkey(sv4.y) & ~127u) | (unsigned)(ib - 1);
;             v[4 * i + 2] = (fkey(sv4.z) & ~127u) | (unsigned)(ib - 2); v[4 * i + 3] = (fkey(sv4.w) & ~127u) | (unsigned)(ib - 3);
;         }
	v_and_b32_e32 v2, 0xffffff80, v2
	v_sub_u32_e32 v2, v2, v182
	v_bitop3_b32 v3, v117, s98, v3 bitop3:0x56
	s_waitcnt lgkmcnt(0)
	v_ashrrev_i32_e32 v117, 31, v4


; DI unsigned fkey(float f) { const unsigned u = __float_as_uint(f); return (u & 0x80000000u) ? ~u : (u | 0x80000000u); }
; DI void topk_phase(unsigned char* smem_, const bf16_t* __restrict__ qp, const bf16_t* __restrict__ keys, int* __restrict__ eidx, float* __restrict__ gate) {
;     ...
;         for (int i = 0; i < 8; ++i) {
;             const f32x4 sv4 = *(const f32x4*)(S + row * LDS_ + 32 * q + 4 * i);
;             const int ib = 127 - (32 * q + 4 * i);
;             v[4 * i] = (fkey(sv4.x) & ~127u) | (unsigned)ib; v[4 * i + 1] = (fkey(sv4.y) & ~127u) | (unsigned)(ib - 1);
;             v[4 * i + 2] = (fkey(sv4.z) & ~127u) | (unsigned)(ib - 2); v[4 * i + 3] = (fkey(sv4.w) & ~127u) | (unsigned)(ib - 3);
;         }
	v_and_b32_e32 v3, 0xffffff80, v3
	v_sub_u32_e32 v3, v3, v182
	v_bitop3_b32 v4, v117, s98, v4 bitop3:0x56
	v_ashrrev_i32_e32 v117, 31, v5


; DI unsigned fkey(float f) { const unsigned u = __float_as_uint(f); return (u & 0x80000000u) ? ~u : (u | 0x80000000u); }
; DI void topk_phase(unsigned char* smem_, const bf16_t* __restrict__ qp, const bf16_t* __restrict__ keys, int* __restrict__ eidx, float* __restrict__ gate) {
;     ...
;         for (int i = 0; i < 8; ++i) {
;             const f32x4 sv4 = *(const f32x4*)(S + row * LDS_ + 32 * q + 4 * i);
;             const int ib = 127 - (32 * q + 4 * i);
;             v[4 * i] = (fkey(sv4.x) & ~127u) | (unsigned)ib; v[4 * i + 1] = (fkey(sv4.y) & ~127u) | (unsigned)(ib - 1);
;             v[4 * i + 2] = (fkey(sv4.z) & ~127u) | (unsigned)(ib - 2); v[4 * i + 3] = (fkey(sv4.w) & ~127u) | (unsigned)(ib - 3);
;         }
	v_and_b32_e32 v4, 0xffffff80, v4
	v_sub_u32_e32 v4, v4, v183
	v_bitop3_b32 v5, v117, s98, v5 bitop3:0x56
	v_ashrrev_i32_e32 v117, 31, v6


; DI unsigned fkey(float f) { const unsigned u = __float_as_uint(f); return (u & 0x80000000u) ? ~u : (u | 0x80000000u); }
; DI void topk_phase(unsigned char* smem_, const bf16_t* __restrict__ qp, const bf16_t* __restrict__ keys, int* __restrict__ eidx, float* __restrict__ gate) {
;     ...
;         for (int i = 0; i < 8; ++i) {
;             const f32x4 sv4 = *(const f32x4*)(S + row * LDS_ + 32 * q + 4 * i);
;             const int ib = 127 - (32 * q + 4 * i);
;             v[4 * i] = (fkey(sv4.x) & ~127u) | (unsigned)ib; v[4 * i + 1] = (fkey(sv4.y) & ~127u) | (unsigned)(ib - 1);
;             v[4 * i + 2] = (fkey(sv4.z) & ~127u) | (unsigned)(ib - 2); v[4 * i + 3] = (fkey(sv4.w) & ~127u) | (unsigned)(ib - 3);
;         }
	v_and_b32_e32 v5, 0xffffff80, v5
	v_sub_u32_e32 v5, v5, v183
	v_bitop3_b32 v6, v117, s98, v6 bitop3:0x56
	v_ashrrev_i32_e32 v117, 31, v7


; DI unsigned fkey(float f) { const unsigned u = __float_as_uint(f); return (u & 0x80000000u) ? ~u : (u | 0x80000000u); }
; template <int N> DI void bitonic_sort_desc(unsigned (&v)[N]) {
; #pragma unroll
;     for (int k = 2; k <= N; k <<= 1)
; #pragma unroll
;         for (int j = k >> 1; j > 0; j >>= 1)
; #pragma unroll
;             for (int i = 0; i < N; ++i) { const int l = i ^ j; if (l > i) { if ((i & k) == 0) cswap(v[i], v[l]); else cswap(v[l], v[i]); } }
; DI void topk_phase(unsigned char* smem_, const bf16_t* __restrict__ qp, const bf16_t* __restrict__ keys, int* __restrict__ eidx, float* __restrict__ gate) {
;     ...
;         for (int i = 0; i < 8; ++i) {
;             const f32x4 sv4 = *(const f32x4*)(S + row * LDS_ + 32 * q + 4 * i);
;             const int ib = 127 - (32 * q + 4 * i);
;             v[4 * i] = (fkey(sv4.x) & ~127u) | (unsigned)ib; v[4 * i + 1] = (fkey(sv4.y) & ~127u) | (unsigned)(ib - 1);
;             v[4 * i + 2] = (fkey(sv4.z) & ~127u) | (unsigned)(ib - 2); v[4 * i + 3] = (fkey(sv4.w) & ~127u) | (unsigned)(ib - 3);
;         }
;         bitonic_sort_desc<32>(v);
	v_and_b32_e32 v6, 0xffffff80, v6
	v_sub_u32_e32 v6, v6, v183
	v_bitop3_b32 v7, v117, s98, v7 bitop3:0x56
	v_and_b32_e32 v7, 0xffffff80, v7
	v_sub_u32_e32 v7, v7, v183
	v_add_u32_e32 v0, 0x7f, v0
	v_add_u32_e32 v1, 0x7e, v1
	v_add_u32_e32 v2, 0x7d, v2
	v_add_u32_e32 v3, 0x7c, v3
	v_add_u32_e32 v4, 0x7f, v4
	v_add_u32_e32 v5, 0x7e, v5
	v_add_u32_e32 v6, 0x7d, v6
	v_add_u32_e32 v7, 0x7c, v7
	v_max_u32_e32 v117, v16, v17
	v_min_u32_e32 v16, v16, v17
	v_max_u32_e32 v17, v19, v18
	v_min_u32_e32 v18, v19, v18
	v_max_u32_e32 v19, v20, v21
	v_min_u32_e32 v20, v20, v21
	v_max_u32_e32 v21, v23, v22
	v_min_u32_e32 v22, v23, v22
	v_max_u32_e32 v23, v8, v9
	v_min_u32_e32 v8, v8, v9
	v_max_u32_e32 v9, v11, v10
	v_min_u32_e32 v10, v11, v10
	v_max_u32_e32 v11, v12, v13
	v_min_u32_e32 v12, v12, v13
	v_max_u32_e32 v13, v15, v14
	v_min_u32_e32 v14, v15, v14
	v_max_u32_e32 v15, v24, v25
	v_min_u32_e32 v24, v24, v25
	v_max_u32_e32 v25, v27, v26
	v_min_u32_e32 v26, v27, v26
	v_max_u32_e32 v27, v28, v29
	v_min_u32_e32 v28, v28, v29
	v_max_u32_e32 v29, v31, v30
	v_min_u32_e32 v30, v31, v30
	v_max_u32_e32 v31, v0, v1
	v_min_u32_e32 v0, v0, v1
	v_max_u32_e32 v1, v3, v2
	v_min_u32_e32 v2, v3, v2
	v_max_u32_e32 v3, v4, v5
	v_min_u32_e32 v4, v4, v5
	v_max_u32_e32 v5, v7, v6
	v_min_u32_e32 v6, v7, v6
	v_max_u32_e32 v7, v117, v18
	v_min_u32_e32 v18, v117, v18
	v_max_u32_e32 v117, v16, v17
	v_min_u32_e32 v16, v16, v17
	v_max_u32_e32 v17, v22, v19
	v_min_u32_e32 v19, v22, v19
	v_max_u32_e32 v22, v21, v20
	v_min_u32_e32 v20, v21, v20
	v_max_u32_e32 v21, v23, v10
	v_min_u32_e32 v10, v23, v10
	v_max_u32_e32 v23, v8, v9
	v_min_u32_e32 v8, v8, v9
	v_max_u32_e32 v9, v14, v11
	v_min_u32_e32 v11, v14, v11
	v_max_u32_e32 v14, v13, v12
	v_min_u32_e32 v12, v13, v12
	v_max_u32_e32 v13, v15, v26
	v_min_u32_e32 v15, v15, v26
	v_max_u32_e32 v26, v24, v25
	v_min_u32_e32 v24, v24, v25
	v_max_u32_e32 v25, v30, v27
	v_min_u32_e32 v27, v30, v27
	v_max_u32_e32 v30, v29, v28
	v_min_u32_e32 v28, v29, v28
	v_max_u32_e32 v29, v31, v2
	v_min_u32_e32 v2, v31, v2
	v_max_u32_e32 v31, v0, v1
	v_min_u32_e32 v0, v0, v1
	v_max_u32_e32 v1, v6, v3
	v_min_u32_e32 v3, v6, v3
	v_max_u32_e32 v6, v5, v4
	v_min_u32_e32 v4, v5, v4
	v_max_u32_e32 v5, v7, v117
	v_min_u32_e32 v7, v7, v117
	v_max_u32_e32 v117, v18, v16
	v_min_u32_e32 v16, v18, v16
	v_max_u32_e32 v18, v20, v19
	v_min_u32_e32 v19, v20, v19
	v_max_u32_e32 v20, v22, v17
	v_min_u32_e32 v17, v22, v17
	v_max_u32_e32 v22, v21, v23
	v_min_u32_e32 v21, v21, v23
	v_max_u32_e32 v23, v10, v8
	v_min_u32_e32 v8, v10, v8
	v_max_u32_e32 v10, v12, v11
	v_min_u32_e32 v11, v12, v11
	v_max_u32_e32 v12, v14, v9
	v_min_u32_e32 v9, v14, v9
	v_max_u32_e32 v14, v13, v26
	v_min_u32_e32 v13, v13, v26
	v_max_u32_e32 v26, v15, v24
	v_min_u32_e32 v15, v15, v24
	v_max_u32_e32 v24, v28, v27
	v_min_u32_e32 v27, v28, v27
	v_max_u32_e32 v28, v30, v25
	v_min_u32_e32 v25, v30, v25
	v_max_u32_e32 v30, v29, v31
	v_min_u32_e32 v29, v29, v31
	v_max_u32_e32 v31, v2, v0
	v_min_u32_e32 v0, v2, v0
	v_max_u32_e32 v2, v4, v3
	v_min_u32_e32 v3, v4, v3
	v_max_u32_e32 v4, v6, v1
	v_min_u32_e32 v1, v6, v1
	v_max_u32_e32 v6, v5, v19
	v_min_u32_e32 v5, v5, v19
	v_max_u32_e32 v19, v7, v18
	v_min_u32_e32 v7, v7, v18
	v_max_u32_e32 v18, v117, v17
	v_min_u32_e32 v17, v117, v17
	v_max_u32_e32 v117, v16, v20
	v_min_u32_e32 v16, v16, v20
	v_max_u32_e32 v20, v11, v22
	v_min_u32_e32 v11, v11, v22
	v_max_u32_e32 v22, v10, v21
	v_min_u32_e32 v10, v10, v21
	v_max_u32_e32 v21, v9, v23
	v_min_u32_e32 v9, v9, v23
	v_max_u32_e32 v23, v12, v8
	v_min_u32_e32 v8, v12, v8
	v_max_u32_e32 v12, v14, v27
	v_min_u32_e32 v14, v14, v27
	v_max_u32_e32 v27, v13, v24
	v_min_u32_e32 v13, v13, v24
	v_max_u32_e32 v24, v26, v25
	v_min_u32_e32 v25, v26, v25
	v_max_u32_e32 v26, v15, v28
	v_min_u32_e32 v15, v15, v28
	v_max_u32_e32 v28, v3, v30
	v_min_u32_e32 v3, v3, v30
	v_max_u32_e32 v30, v2, v29
	v_min_u32_e32 v2, v2, v29
	v_max_u32_e32 v29, v1, v31
	v_min_u32_e32 v1, v1, v31
	v_max_u32_e32 v31, v4, v0
	v_min_u32_e32 v0, v4, v0
	v_max_u32_e32 v4, v6, v18
	v_min_u32_e32 v6, v6, v18
	v_max_u32_e32 v18, v19, v117
	v_min_u32_e32 v19, v19, v117
	v_max_u32_e32 v117, v5, v17
	v_min_u32_e32 v5, v5, v17
	v_max_u32_e32 v17, v7, v16
	v_min_u32_e32 v7, v7, v16
	v_max_u32_e32 v16, v9, v11
	v_min_u32_e32 v9, v9, v11
	v_max_u32_e32 v11, v8, v10
	v_min_u32_e32 v8, v8, v10
	v_max_u32_e32 v10, v21, v20
	v_min_u32_e32 v20, v21, v20
	v_max_u32_e32 v21, v23, v22
	v_min_u32_e32 v22, v23, v22
	v_max_u32_e32 v23, v12, v24
	v_min_u32_e32 v12, v12, v24
	v_max_u32_e32 v24, v27, v26
	v_min_u32_e32 v26, v27, v26
	v_max_u32_e32 v27, v14, v25
	v_min_u32_e32 v14, v14, v25
	v_max_u32_e32 v25, v13, v15
	v_min_u32_e32 v13, v13, v15
	v_max_u32_e32 v15, v1, v3
	v_min_u32_e32 v1, v1, v3
	v_max_u32_e32 v3, v0, v2
	v_min_u32_e32 v0, v0, v2
	v_max_u32_e32 v2, v29, v28
	v_min_u32_e32 v28, v29, v28
	v_max_u32_e32 v29, v31, v30
	v_min_u32_e32 v30, v31, v30
	v_max_u32_e32 v31, v4, v18
	v_min_u32_e32 v4, v4, v18
	v_max_u32_e32 v18, v6, v19
	v_min_u32_e32 v6, v6, v19
	v_max_u32_e32 v19, v117, v17
	v_min_u32_e32 v17, v117, v17
	v_max_u32_e32 v117, v5, v7
	v_min_u32_e32 v5, v5, v7
	v_max_u32_e32 v7, v8, v9
	v_min_u32_e32 v8, v8, v9
	v_max_u32_e32 v9, v11, v16
	v_min_u32_e32 v11, v11, v16
	v_max_u32_e32 v16, v22, v20
	v_min_u32_e32 v20, v22, v20
	v_max_u32_e32 v22, v21, v10
	v_min_u32_e32 v10, v21, v10
	v_max_u32_e32 v21, v23, v24
	v_min_u32_e32 v23, v23, v24
	v_max_u32_e32 v24, v12, v26
	v_min_u32_e32 v12, v12, v26
	v_max_u32_e32 v26, v27, v25
	v_min_u32_e32 v25, v27, v25
	v_max_u32_e32 v27, v14, v13
	v_min_u32_e32 v13, v14, v13
	v_max_u32_e32 v14, v0, v1
	v_min_u32_e32 v0, v0, v1
; DI void merge_top16(unsigned (&v)[16], int st) {
;     unsigned x[16];
; #pragma unroll
;     for (int i = 0; i < 16; ++i) x[i] = (unsigned)__shfl_xor((int)v[15 - i], st);
; #pragma unroll
;     for (int i = 0; i < 16; ++i) v[i] = max(v[i], x[i]);
; #pragma unroll
;     for (int j = 8; j > 0; j >>= 1)
; #pragma unroll
;         for (int i = 0; i < 16; ++i) { const int l = i ^ j; if (l > i) cswap(v[i], v[l]); }
; }
; DI void topk_phase(unsigned char* smem_, const bf16_t* __restrict__ qp, const bf16_t* __restrict__ keys, int* __restrict__ eidx, float* __restrict__ gate) {
;     ...
;         bitonic_sort_desc<32>(v);
;         unsigned t16[16];
; #pragma unroll
;         for (int i = 0; i < 16; ++i) t16[i] = v[i];
;         merge_top16(t16, 1);
	v_max_u32_e32 v1, v3, v15
	v_min_u32_e32 v3, v3, v15
	v_max_u32_e32 v15, v30, v28
	v_min_u32_e32 v28, v30, v28
	v_max_u32_e32 v30, v29, v2
	v_min_u32_e32 v2, v29, v2
	v_max_u32_e32 v29, v31, v8
	v_min_u32_e32 v8, v31, v8
	v_max_u32_e32 v31, v4, v7
	v_min_u32_e32 v4, v4, v7
	v_max_u32_e32 v7, v18, v11
	v_min_u32_e32 v11, v18, v11
	v_max_u32_e32 v18, v6, v9
	v_min_u32_e32 v6, v6, v9
	v_max_u32_e32 v9, v19, v20
	v_min_u32_e32 v19, v19, v20
	v_max_u32_e32 v20, v17, v16
	v_min_u32_e32 v16, v17, v16
	v_max_u32_e32 v17, v117, v10
	v_min_u32_e32 v10, v117, v10
	v_max_u32_e32 v117, v5, v22
	v_min_u32_e32 v5, v5, v22
	v_max_u32_e32 v22, v0, v21
	v_min_u32_e32 v0, v0, v21
	v_max_u32_e32 v21, v14, v23
	v_min_u32_e32 v14, v14, v23
	v_max_u32_e32 v23, v3, v24
	v_min_u32_e32 v3, v3, v24
	v_max_u32_e32 v24, v1, v12
	v_min_u32_e32 v1, v1, v12
	v_max_u32_e32 v12, v28, v26
	v_min_u32_e32 v26, v28, v26
	v_max_u32_e32 v28, v15, v25
	v_min_u32_e32 v15, v15, v25
	v_max_u32_e32 v25, v2, v27
	v_min_u32_e32 v2, v2, v27
	v_max_u32_e32 v27, v30, v13
	v_min_u32_e32 v13, v30, v13
	v_max_u32_e32 v30, v29, v9
	v_min_u32_e32 v9, v29, v9
	v_max_u32_e32 v29, v31, v20
	v_min_u32_e32 v20, v31, v20
	v_max_u32_e32 v31, v7, v17
	v_min_u32_e32 v7, v7, v17
	v_max_u32_e32 v17, v18, v117
	v_min_u32_e32 v18, v18, v117
	v_max_u32_e32 v117, v8, v19
	v_min_u32_e32 v8, v8, v19
	v_max_u32_e32 v19, v4, v16
	v_min_u32_e32 v4, v4, v16
	v_max_u32_e32 v16, v11, v10
	v_min_u32_e32 v10, v11, v10
	v_max_u32_e32 v11, v6, v5
	v_min_u32_e32 v5, v6, v5
	v_max_u32_e32 v6, v26, v0
	v_min_u32_e32 v0, v26, v0
	v_max_u32_e32 v26, v15, v14
	v_min_u32_e32 v14, v15, v14
	v_max_u32_e32 v15, v2, v3
	v_min_u32_e32 v2, v2, v3
	v_max_u32_e32 v3, v13, v1
	v_min_u32_e32 v1, v13, v1
	v_max_u32_e32 v13, v12, v22
	v_min_u32_e32 v12, v12, v22
	v_max_u32_e32 v22, v28, v21
	v_min_u32_e32 v21, v28, v21
	v_max_u32_e32 v28, v25, v23
	v_min_u32_e32 v23, v25, v23
	v_max_u32_e32 v25, v27, v24
	v_min_u32_e32 v24, v27, v24
	v_max_u32_e32 v27, v30, v31
	v_min_u32_e32 v30, v30, v31
	v_max_u32_e32 v31, v29, v17
	v_min_u32_e32 v17, v29, v17
	v_max_u32_e32 v29, v9, v7
	v_min_u32_e32 v7, v9, v7
	v_max_u32_e32 v9, v20, v18
	v_min_u32_e32 v18, v20, v18
	v_max_u32_e32 v20, v117, v16
	v_min_u32_e32 v16, v117, v16
	v_max_u32_e32 v117, v19, v11
	v_min_u32_e32 v11, v19, v11
	v_max_u32_e32 v19, v8, v10
	v_min_u32_e32 v8, v8, v10
	v_max_u32_e32 v10, v4, v5
	v_min_u32_e32 v4, v4, v5
	v_max_u32_e32 v5, v2, v0
	v_min_u32_e32 v0, v2, v0
	v_max_u32_e32 v2, v1, v14
	v_min_u32_e32 v1, v1, v14
	v_max_u32_e32 v14, v15, v6
	v_min_u32_e32 v6, v15, v6
	v_max_u32_e32 v15, v3, v26
	v_min_u32_e32 v3, v3, v26
	v_max_u32_e32 v26, v23, v12
	v_min_u32_e32 v12, v23, v12
	v_max_u32_e32 v23, v24, v21
	v_min_u32_e32 v21, v24, v21
	v_max_u32_e32 v24, v28, v13
	v_min_u32_e32 v13, v28, v13
	v_max_u32_e32 v28, v25, v22
	v_min_u32_e32 v22, v25, v22
	v_min_u32_e32 v25, v27, v31
	v_min_u32_e32 v118, v30, v17
	v_min_u32_e32 v119, v29, v9
	v_min_u32_e32 v120, v7, v18
	v_min_u32_e32 v121, v20, v117
	v_min_u32_e32 v122, v16, v11
	v_min_u32_e32 v123, v19, v10
	v_min_u32_e32 v124, v8, v4
	v_min_u32_e32 v125, v1, v0
	v_min_u32_e32 v126, v2, v5
	v_min_u32_e32 v127, v3, v6
	v_min_u32_e32 v142, v15, v14
	v_min_u32_e32 v143, v21, v12
	v_min_u32_e32 v144, v23, v26
	v_min_u32_e32 v145, v22, v13
	v_min_u32_e32 v146, v28, v24
	v_max3_u32 v27, v27, v31, v125
	v_max3_u32 v0, v25, v1, v0
	v_max3_u32 v1, v30, v17, v126
	v_max3_u32 v2, v118, v2, v5
	v_max3_u32 v5, v29, v9, v127
	v_max3_u32 v3, v119, v3, v6
	v_max3_u32 v6, v7, v18, v142
	v_max3_u32 v7, v120, v15, v14
	v_max3_u32 v9, v20, v117, v143
	v_max3_u32 v12, v121, v21, v12
	v_max3_u32 v11, v16, v11, v144
	v_max3_u32 v14, v122, v23, v26
	v_max3_u32 v10, v19, v10, v145
	v_max3_u32 v13, v123, v22, v13
	v_max3_u32 v4, v8, v4, v146
	v_max3_u32 v8, v124, v28, v24
	v_max_u32_e32 v15, v27, v9
	v_min_u32_e32 v9, v27, v9
	v_max_u32_e32 v16, v0, v12
	v_min_u32_e32 v0, v0, v12
	v_max_u32_e32 v12, v1, v11
	v_min_u32_e32 v1, v1, v11
	v_max_u32_e32 v11, v2, v14
	v_min_u32_e32 v2, v2, v14
	v_max_u32_e32 v14, v5, v10
	v_min_u32_e32 v5, v5, v10
	v_max_u32_e32 v10, v3, v13
	v_min_u32_e32 v3, v3, v13
	v_max_u32_e32 v13, v6, v4
	v_min_u32_e32 v4, v6, v4
	v_max_u32_e32 v6, v7, v8
	v_min_u32_e32 v7, v7, v8
	v_max_u32_e32 v8, v15, v14
	v_min_u32_e32 v14, v15, v14
	v_max_u32_e32 v15, v16, v10
	v_min_u32_e32 v10, v16, v10
	v_max_u32_e32 v16, v12, v13
	v_min_u32_e32 v12, v12, v13
	v_max_u32_e32 v13, v11, v6
	v_min_u32_e32 v6, v11, v6
	v_max_u32_e32 v11, v9, v5
	v_min_u32_e32 v5, v9, v5
	v_max_u32_e32 v9, v0, v3
	v_min_u32_e32 v0, v0, v3
	v_max_u32_e32 v3, v1, v4
	v_min_u32_e32 v1, v1, v4
	v_max_u32_e32 v4, v2, v7
	v_min_u32_e32 v2, v2, v7
	v_max_u32_e32 v7, v8, v16
	v_min_u32_e32 v8, v8, v16
	v_max_u32_e32 v16, v15, v13
	v_min_u32_e32 v13, v15, v13
	v_max_u32_e32 v15, v14, v12
	v_min_u32_e32 v12, v14, v12
	v_max_u32_e32 v14, v10, v6
	v_min_u32_e32 v6, v10, v6
	v_max_u32_e32 v10, v11, v3
	v_min_u32_e32 v3, v11, v3
	v_max_u32_e32 v11, v9, v4
	v_min_u32_e32 v4, v9, v4
	v_max_u32_e32 v9, v5, v1
	v_min_u32_e32 v1, v5, v1
	v_max_u32_e32 v5, v0, v2
	v_min_u32_e32 v0, v0, v2
	v_max_u32_e32 v2, v7, v16
	v_min_u32_e32 v7, v7, v16
	v_max_u32_e32 v16, v8, v13
	v_min_u32_e32 v8, v8, v13
	v_max_u32_e32 v13, v15, v14
	v_min_u32_e32 v14, v15, v14
	v_max_u32_e32 v15, v12, v6
	v_min_u32_e32 v6, v12, v6
	v_max_u32_e32 v12, v10, v11
	v_min_u32_e32 v10, v10, v11
	v_max_u32_e32 v11, v3, v4
	v_min_u32_e32 v3, v3, v4
	v_max_u32_e32 v4, v9, v5
	v_min_u32_e32 v5, v9, v5
	v_max_u32_e32 v9, v1, v0
	v_min_u32_e32 v0, v1, v0
	s_nop 1
	v_mov_b32_dpp v1, v0 quad_perm:[1,0,3,2] row_mask:0xf bank_mask:0xf
	v_mov_b32_dpp v17, v9 quad_perm:[1,0,3,2] row_mask:0xf bank_mask:0xf
	v_mov_b32_dpp v18, v5 quad_perm:[1,0,3,2] row_mask:0xf bank_mask:0xf
	v_mov_b32_dpp v19, v4 quad_perm:[1,0,3,2] row_mask:0xf bank_mask:0xf
	v_mov_b32_dpp v20, v3 quad_perm:[1,0,3,2] row_mask:0xf bank_mask:0xf
	v_mov_b32_dpp v21, v11 quad_perm:[1,0,3,2] row_mask:0xf bank_mask:0xf
	v_mov_b32_dpp v22, v10 quad_perm:[1,0,3,2] row_mask:0xf bank_mask:0xf
	v_mov_b32_dpp v23, v12 quad_perm:[1,0,3,2] row_mask:0xf bank_mask:0xf
	v_mov_b32_dpp v24, v6 quad_perm:[1,0,3,2] row_mask:0xf bank_mask:0xf
	v_mov_b32_dpp v25, v15 quad_perm:[1,0,3,2] row_mask:0xf bank_mask:0xf
	v_mov_b32_dpp v26, v14 quad_perm:[1,0,3,2] row_mask:0xf bank_mask:0xf
	v_mov_b32_dpp v27, v13 quad_perm:[1,0,3,2] row_mask:0xf bank_mask:0xf
	v_mov_b32_dpp v28, v8 quad_perm:[1,0,3,2] row_mask:0xf bank_mask:0xf
	v_mov_b32_dpp v29, v16 quad_perm:[1,0,3,2] row_mask:0xf bank_mask:0xf
	v_mov_b32_dpp v30, v7 quad_perm:[1,0,3,2] row_mask:0xf bank_mask:0xf
	v_mov_b32_dpp v31, v2 quad_perm:[1,0,3,2] row_mask:0xf bank_mask:0xf
	s_waitcnt lgkmcnt(0)
; DI unsigned fkey(float f) { const unsigned u = __float_as_uint(f); return (u & 0x80000000u) ? ~u : (u | 0x80000000u); }
; DI void topk_phase(unsigned char* smem_, const bf16_t* __restrict__ qp, const bf16_t* __restrict__ keys, int* __restrict__ eidx, float* __restrict__ gate) {
;     ...
;         merge_top16(t16, 1);
;         merge_top16(t16, 2);
; #pragma unroll
;         for (int i = 0; i < 16; ++i) if ((i >> 2) == q) { const int idx = 127 - (int)(t16[i] & 127u); SI[row * 32 + 16 * p + i] = idx; SV[row * 32 + 16 * p + i] = S[row * LDS_ + idx]; }
;     }
;     __syncthreads();
;     constexpr unsigned KT[13] = {0x03020100u, 0x07060504u, 0x0b0a0908u, 0x0f0e0d0cu, 0x13121110u, 0x17161514u, 0x23222120u, 0x32313024u, 0x42414033u, 0x61605150u, 0x90807170u, 0xd0c0b0a0u, 0x0000f0e0u};
;     unsigned c16[16];
; #pragma unroll
;     for (int i = 0; i < 13; ++i) {
;         const unsigned ab = (KT[i] >> (8 * q)) & 255u;
;         const float c = SV[row * 32 + (ab >> 4)] + SV[row * 32 + 16 + (ab & 15u)];
;         c16[i] = (fkey(c) & ~255u) | (255u - ab);
	v_max_u32_e32 v1, v2, v1
	v_max_u32_e32 v2, v7, v17
	v_max_u32_e32 v7, v16, v18
	v_max_u32_e32 v8, v8, v19
	v_max_u32_e32 v13, v13, v20
	v_max_u32_e32 v14, v14, v21
	v_max_u32_e32 v15, v15, v22
	v_max_u32_e32 v6, v6, v23
	v_max_u32_e32 v12, v12, v24
	v_max_u32_e32 v10, v10, v25
	v_max_u32_e32 v11, v11, v26
	v_max_u32_e32 v3, v3, v27
	v_max_u32_e32 v4, v4, v28
	v_max_u32_e32 v5, v5, v29
	v_max_u32_e32 v9, v9, v30
	v_max_u32_e32 v0, v0, v31
	v_max_u32_e32 v16, v1, v12
	v_min_u32_e32 v1, v1, v12
	v_max_u32_e32 v12, v2, v10
	v_min_u32_e32 v2, v2, v10
	v_max_u32_e32 v10, v7, v11
	v_min_u32_e32 v7, v7, v11
	v_max_u32_e32 v11, v8, v3
	v_min_u32_e32 v3, v8, v3
	v_max_u32_e32 v8, v13, v4
	v_min_u32_e32 v4, v13, v4
	v_max_u32_e32 v13, v14, v5
	v_min_u32_e32 v5, v14, v5
	v_max_u32_e32 v14, v15, v9
	v_min_u32_e32 v9, v15, v9
	v_max_u32_e32 v15, v6, v0
	v_min_u32_e32 v0, v6, v0
	v_max_u32_e32 v6, v16, v8
	v_min_u32_e32 v8, v16, v8
	v_max_u32_e32 v16, v12, v13
	v_min_u32_e32 v12, v12, v13
	v_max_u32_e32 v13, v10, v14
	v_min_u32_e32 v10, v10, v14
	v_max_u32_e32 v14, v11, v15
	v_min_u32_e32 v11, v11, v15
	v_max_u32_e32 v15, v1, v4
	v_min_u32_e32 v1, v1, v4
	v_max_u32_e32 v4, v2, v5
	v_min_u32_e32 v2, v2, v5
	v_max_u32_e32 v5, v7, v9
	v_min_u32_e32 v7, v7, v9
	v_max_u32_e32 v9, v3, v0
	v_min_u32_e32 v0, v3, v0
	v_max_u32_e32 v3, v6, v13
	v_min_u32_e32 v6, v6, v13
	v_max_u32_e32 v13, v16, v14
	v_min_u32_e32 v14, v16, v14
	v_max_u32_e32 v16, v8, v10
	v_min_u32_e32 v8, v8, v10
	v_max_u32_e32 v10, v12, v11
	v_min_u32_e32 v11, v12, v11
	v_max_u32_e32 v12, v15, v5
	v_min_u32_e32 v5, v15, v5
	v_max_u32_e32 v15, v4, v9
	v_min_u32_e32 v4, v4, v9
	v_max_u32_e32 v9, v1, v7
	v_min_u32_e32 v1, v1, v7
	v_max_u32_e32 v7, v2, v0
	v_min_u32_e32 v0, v2, v0
	v_max_u32_e32 v2, v3, v13
	v_min_u32_e32 v3, v3, v13
	v_max_u32_e32 v13, v6, v14
	v_min_u32_e32 v6, v6, v14
	v_max_u32_e32 v14, v16, v10
	v_min_u32_e32 v10, v16, v10
	v_max_u32_e32 v16, v8, v11
	v_min_u32_e32 v8, v8, v11
	v_max_u32_e32 v11, v12, v15
	v_min_u32_e32 v12, v12, v15
	v_max_u32_e32 v15, v5, v4
	v_min_u32_e32 v17, v5, v4
	v_max_u32_e32 v18, v9, v7
	v_min_u32_e32 v19, v9, v7
	v_max_u32_e32 v20, v1, v0
	v_min_u32_e32 v21, v1, v0
	s_nop 1
	v_mov_b32_dpp v0, v21 quad_perm:[2,3,0,1] row_mask:0xf bank_mask:0xf
	v_mov_b32_dpp v1, v20 quad_perm:[2,3,0,1] row_mask:0xf bank_mask:0xf
	v_mov_b32_dpp v4, v19 quad_perm:[2,3,0,1] row_mask:0xf bank_mask:0xf
	v_mov_b32_dpp v5, v18 quad_perm:[2,3,0,1] row_mask:0xf bank_mask:0xf
	v_mov_b32_dpp v7, v17 quad_perm:[2,3,0,1] row_mask:0xf bank_mask:0xf
	v_mov_b32_dpp v9, v15 quad_perm:[2,3,0,1] row_mask:0xf bank_mask:0xf
	v_mov_b32_dpp v22, v12 quad_perm:[2,3,0,1] row_mask:0xf bank_mask:0xf
	v_mov_b32_dpp v23, v11 quad_perm:[2,3,0,1] row_mask:0xf bank_mask:0xf
	v_mov_b32_dpp v24, v8 quad_perm:[2,3,0,1] row_mask:0xf bank_mask:0xf
	v_mov_b32_dpp v25, v16 quad_perm:[2,3,0,1] row_mask:0xf bank_mask:0xf
	v_mov_b32_dpp v26, v10 quad_perm:[2,3,0,1] row_mask:0xf bank_mask:0xf
	v_mov_b32_dpp v27, v14 quad_perm:[2,3,0,1] row_mask:0xf bank_mask:0xf
	v_mov_b32_dpp v28, v6 quad_perm:[2,3,0,1] row_mask:0xf bank_mask:0xf
	v_mov_b32_dpp v29, v13 quad_perm:[2,3,0,1] row_mask:0xf bank_mask:0xf
	v_mov_b32_dpp v30, v3 quad_perm:[2,3,0,1] row_mask:0xf bank_mask:0xf
	v_mov_b32_dpp v31, v2 quad_perm:[2,3,0,1] row_mask:0xf bank_mask:0xf
	s_waitcnt lgkmcnt(0)
	v_max_u32_e32 v0, v2, v0
	v_max_u32_e32 v1, v3, v1
	v_max_u32_e32 v2, v13, v4
	v_max_u32_e32 v3, v6, v5
	v_max_u32_e32 v4, v14, v7
	v_max_u32_e32 v5, v10, v9
	v_max_u32_e32 v6, v16, v22
	v_max_u32_e32 v7, v8, v23
	v_max_u32_e32 v8, v11, v24
	v_max_u32_e32 v9, v12, v25
	v_max_u32_e32 v10, v15, v26
	v_max_u32_e32 v11, v17, v27
	v_max_u32_e32 v12, v18, v28
	v_max_u32_e32 v13, v19, v29
	v_max_u32_e32 v14, v20, v30
	v_max_u32_e32 v15, v21, v31
	v_max_u32_e32 v16, v0, v8
	v_max_u32_e32 v17, v1, v9
	v_max_u32_e32 v18, v2, v10
	v_max_u32_e32 v19, v3, v11
	v_max_u32_e32 v20, v4, v12
	v_max_u32_e32 v21, v5, v13
	v_max_u32_e32 v22, v6, v14
	v_max_u32_e32 v23, v7, v15
	s_or_b64 s[16:17], s[4:5], s[6:7]
	s_or_b64 vcc, s[6:7], s[10:11]
	v_min_u32_e32 v0, v0, v8
	v_min_u32_e32 v1, v1, v9
	v_min_u32_e32 v2, v2, v10
	v_min_u32_e32 v3, v3, v11
	v_min_u32_e32 v4, v4, v12
	v_min_u32_e32 v5, v5, v13
	v_min_u32_e32 v6, v6, v14
	v_min_u32_e32 v7, v7, v15
	v_cndmask_b32_e64 v0, v0, v16, s[16:17]
	v_cndmask_b32_e64 v1, v1, v17, s[16:17]
	v_cndmask_b32_e64 v2, v2, v18, s[16:17]
	v_cndmask_b32_e64 v3, v3, v19, s[16:17]
	v_cndmask_b32_e64 v4, v4, v20, s[16:17]
	v_cndmask_b32_e64 v5, v5, v21, s[16:17]
	v_cndmask_b32_e64 v6, v6, v22, s[16:17]
	v_cndmask_b32_e64 v7, v7, v23, s[16:17]
	v_max_u32_e32 v8, v0, v4
	v_max_u32_e32 v9, v1, v5
	v_max_u32_e32 v10, v2, v6
	v_max_u32_e32 v11, v3, v7
	v_min_u32_e32 v12, v0, v4
	v_min_u32_e32 v13, v1, v5
	v_min_u32_e32 v14, v2, v6
	v_min_u32_e32 v15, v3, v7
	v_cndmask_b32_e32 v0, v8, v12, vcc
	v_cndmask_b32_e32 v1, v9, v13, vcc
	v_cndmask_b32_e32 v2, v10, v14, vcc
	v_cndmask_b32_e32 v3, v11, v15, vcc
	v_max_u32_e32 v4, v0, v2
	v_min_u32_e32 v5, v0, v2
	v_max_u32_e32 v6, v1, v3
	v_min_u32_e32 v7, v1, v3
	v_max_u32_e32 v0, v4, v6
	v_min_u32_e32 v1, v4, v6
	v_max_u32_e32 v2, v5, v7
	v_min_u32_e32 v3, v5, v7
	v_xor_b32_e32 v0, -1, v0
	v_xor_b32_e32 v1, -1, v1
	v_xor_b32_e32 v2, -1, v2
	v_xor_b32_e32 v3, -1, v3
	v_and_b32_e32 v0, 0x7f, v0
	v_and_b32_e32 v1, 0x7f, v1
	v_and_b32_e32 v2, 0x7f, v2
	v_and_b32_e32 v3, 0x7f, v3
	v_lshl_add_u32 v4, v0, 2, v169
	v_lshl_add_u32 v5, v1, 2, v169
	v_lshl_add_u32 v6, v2, 2, v169
	v_lshl_add_u32 v7, v3, 2, v169
	ds_read_b32 v4, v4 offset:17408
	ds_read_b32 v5, v5 offset:17408
	ds_read_b32 v6, v6 offset:17408
	ds_read_b32 v7, v7 offset:17408
	ds_write_b128 v253, v[0:3] offset:61504
	s_waitcnt lgkmcnt(1)
	ds_write_b128 v253, v[4:7] offset:53312
	s_waitcnt lgkmcnt(0)
	s_barrier
	ds_read_b96 v[0:2], v175 offset:53248
	ds_read_b32 v5, v186 offset:53312
	ds_read_b32 v3, v188 offset:53312
	ds_read_b32 v4, v175 offset:53312
	s_mov_b32 s16, 0xff61b1e6
	s_waitcnt lgkmcnt(3)
	v_mov_b32_e32 v7, v2
	s_waitcnt lgkmcnt(2)
	v_add_f32_e32 v2, v0, v5
	v_ashrrev_i32_e32 v5, 31, v2


; DI unsigned fkey(float f) { const unsigned u = __float_as_uint(f); return (u & 0x80000000u) ? ~u : (u | 0x80000000u); }
; DI void topk_phase(unsigned char* smem_, const bf16_t* __restrict__ qp, const bf16_t* __restrict__ keys, int* __restrict__ eidx, float* __restrict__ gate) {
;     ...
;     for (int i = 0; i < 13; ++i) {
;         const unsigned ab = (KT[i] >> (8 * q)) & 255u;
;         const float c = SV[row * 32 + (ab >> 4)] + SV[row * 32 + 16 + (ab & 15u)];
;         c16[i] = (fkey(c) & ~255u) | (255u - ab);
;     }
;     if (q >= 2) c16[12] = 0u;
	v_mov_b32_e32 v6, v1
	v_or_b32_e32 v158, s24, v164
	v_bitop3_b32 v2, v5, s98, v2 bitop3:0x56
	v_and_b32_e32 v2, 0xffffff00, v2
	v_bitop3_b32 v5, v2, s71, v185 bitop3:0x36
	ds_read_b32 v2, v190 offset:53312
	ds_read_b32 v9, v211 offset:53312
	ds_read_b32 v8, v213 offset:53312
	ds_read_b32 v10, v215 offset:53312
	ds_read_b32 v11, v217 offset:53312
	ds_read_b32 v13, v219 offset:53248
	ds_read_b32 v15, v220 offset:53312
	ds_read_b32 v12, v222 offset:53248
	s_waitcnt lgkmcnt(7)
	v_pk_add_f32 v[2:3], v[0:1], v[2:3] op_sel_hi:[0,1]
	v_ashrrev_i32_e32 v14, 31, v3


; DI unsigned fkey(float f) { const unsigned u = __float_as_uint(f); return (u & 0x80000000u) ? ~u : (u | 0x80000000u); }
; DI void topk_phase(unsigned char* smem_, const bf16_t* __restrict__ qp, const bf16_t* __restrict__ keys, int* __restrict__ eidx, float* __restrict__ gate) {
;     ...
;     for (int i = 0; i < 13; ++i) {
;         const unsigned ab = (KT[i] >> (8 * q)) & 255u;
;         const float c = SV[row * 32 + (ab >> 4)] + SV[row * 32 + 16 + (ab & 15u)];
;         c16[i] = (fkey(c) & ~255u) | (255u - ab);
;     }
;     if (q >= 2) c16[12] = 0u;
	v_ashrrev_i32_e32 v159, 31, v158
	v_lshlrev_b64 v[158:159], 7, v[158:159]
	v_bitop3_b32 v3, v14, s98, v3 bitop3:0x56
	v_and_b32_e32 v3, 0xffffff00, v3
	v_bitop3_b32 v16, v3, s71, v187 bitop3:0x36
	v_ashrrev_i32_e32 v3, 31, v2


; DI unsigned fkey(float f) { const unsigned u = __float_as_uint(f); return (u & 0x80000000u) ? ~u : (u | 0x80000000u); }
; DI void topk_phase(unsigned char* smem_, const bf16_t* __restrict__ qp, const bf16_t* __restrict__ keys, int* __restrict__ eidx, float* __restrict__ gate) {
;     ...
;     for (int i = 0; i < 13; ++i) {
;         const unsigned ab = (KT[i] >> (8 * q)) & 255u;
;         const float c = SV[row * 32 + (ab >> 4)] + SV[row * 32 + 16 + (ab & 15u)];
;         c16[i] = (fkey(c) & ~255u) | (255u - ab);
;     }
;     if (q >= 2) c16[12] = 0u;
	v_lshl_or_b32 v158, s23, 4, v158
	v_lshlrev_b64 v[158:159], 2, v[158:159]
	v_bitop3_b32 v2, v3, s98, v2 bitop3:0x56
	v_and_b32_e32 v2, 0xffffff00, v2
	v_bitop3_b32 v17, v2, s71, v189 bitop3:0x36
	v_mov_b32_e32 v2, v1
	v_mov_b32_e32 v3, v0
	s_waitcnt lgkmcnt(5)
	v_pk_add_f32 v[0:1], v[2:3], v[8:9]
	s_nop 0
	v_ashrrev_i32_e32 v2, 31, v1


; DI unsigned fkey(float f) { const unsigned u = __float_as_uint(f); return (u & 0x80000000u) ? ~u : (u | 0x80000000u); }
; DI void topk_phase(unsigned char* smem_, const bf16_t* __restrict__ qp, const bf16_t* __restrict__ keys, int* __restrict__ eidx, float* __restrict__ gate) {
;     ...
;     for (int i = 0; i < 13; ++i) {
;         const unsigned ab = (KT[i] >> (8 * q)) & 255u;
;         const float c = SV[row * 32 + (ab >> 4)] + SV[row * 32 + 16 + (ab & 15u)];
;         c16[i] = (fkey(c) & ~255u) | (255u - ab);
;     }
;     if (q >= 2) c16[12] = 0u;
	s_nop 1
	v_bitop3_b32 v1, v2, s98, v1 bitop3:0x56
	v_and_b32_e32 v1, 0xffffff00, v1
	v_bitop3_b32 v18, v1, s71, v191 bitop3:0x36
	v_ashrrev_i32_e32 v1, 31, v0


; DI unsigned fkey(float f) { const unsigned u = __float_as_uint(f); return (u & 0x80000000u) ? ~u : (u | 0x80000000u); }
; DI void topk_phase(unsigned char* smem_, const bf16_t* __restrict__ qp, const bf16_t* __restrict__ keys, int* __restrict__ eidx, float* __restrict__ gate) {
;     ...
;     for (int i = 0; i < 13; ++i) {
;         const unsigned ab = (KT[i] >> (8 * q)) & 255u;
;         const float c = SV[row * 32 + (ab >> 4)] + SV[row * 32 + 16 + (ab & 15u)];
;         c16[i] = (fkey(c) & ~255u) | (255u - ab);
;     }
;     if (q >= 2) c16[12] = 0u;
	s_nop 1
	v_bitop3_b32 v0, v1, s98, v0 bitop3:0x56
	v_and_b32_e32 v0, 0xffffff00, v0
	v_bitop3_b32 v19, v0, s71, v212 bitop3:0x36
	s_waitcnt lgkmcnt(3)
	v_pk_add_f32 v[0:1], v[6:7], v[10:11]
	s_nop 0
	v_ashrrev_i32_e32 v2, 31, v0


; DI unsigned fkey(float f) { const unsigned u = __float_as_uint(f); return (u & 0x80000000u) ? ~u : (u | 0x80000000u); }
; DI void topk_phase(unsigned char* smem_, const bf16_t* __restrict__ qp, const bf16_t* __restrict__ keys, int* __restrict__ eidx, float* __restrict__ gate) {
;     ...
;     for (int i = 0; i < 13; ++i) {
;         const unsigned ab = (KT[i] >> (8 * q)) & 255u;
;         const float c = SV[row * 32 + (ab >> 4)] + SV[row * 32 + 16 + (ab & 15u)];
;         c16[i] = (fkey(c) & ~255u) | (255u - ab);
;     }
;     if (q >= 2) c16[12] = 0u;
	s_nop 1
	v_bitop3_b32 v0, v2, s98, v0 bitop3:0x56
	v_and_b32_e32 v0, 0xffffff00, v0
	v_bitop3_b32 v10, v0, s71, v214 bitop3:0x36
	v_ashrrev_i32_e32 v0, 31, v1


; DI unsigned fkey(float f) { const unsigned u = __float_as_uint(f); return (u & 0x80000000u) ? ~u : (u | 0x80000000u); }
; DI void topk_phase(unsigned char* smem_, const bf16_t* __restrict__ qp, const bf16_t* __restrict__ keys, int* __restrict__ eidx, float* __restrict__ gate) {
;     ...
;     for (int i = 0; i < 13; ++i) {
;         const unsigned ab = (KT[i] >> (8 * q)) & 255u;
;         const float c = SV[row * 32 + (ab >> 4)] + SV[row * 32 + 16 + (ab & 15u)];
;         c16[i] = (fkey(c) & ~255u) | (255u - ab);
;     }
;     if (q >= 2) c16[12] = 0u;
	s_nop 1
	v_bitop3_b32 v0, v0, s98, v1 bitop3:0x56
	v_and_b32_e32 v0, 0xffffff00, v0
	v_bitop3_b32 v11, v0, s71, v216 bitop3:0x36
	ds_read_b32 v14, v223 offset:53312
	ds_read_b32 v1, v225 offset:53248
	ds_read_b32 v3, v226 offset:53312
	ds_read_b32 v0, v228 offset:53248
	ds_read_b32 v2, v229 offset:53312
	ds_read_b32 v7, v232 offset:53248
	ds_read_b32 v6, v233 offset:53248
	s_waitcnt lgkmcnt(6)
	v_pk_add_f32 v[8:9], v[12:13], v[14:15]
	s_waitcnt lgkmcnt(2)
	v_pk_add_f32 v[0:1], v[0:1], v[2:3]
	v_ashrrev_i32_e32 v12, 31, v9


; DI unsigned fkey(float f) { const unsigned u = __float_as_uint(f); return (u & 0x80000000u) ? ~u : (u | 0x80000000u); }
; DI void topk_phase(unsigned char* smem_, const bf16_t* __restrict__ qp, const bf16_t* __restrict__ keys, int* __restrict__ eidx, float* __restrict__ gate) {
;     ...
;     for (int i = 0; i < 13; ++i) {
;         const unsigned ab = (KT[i] >> (8 * q)) & 255u;
;         const float c = SV[row * 32 + (ab >> 4)] + SV[row * 32 + 16 + (ab & 15u)];
;         c16[i] = (fkey(c) & ~255u) | (255u - ab);
;     }
;     if (q >= 2) c16[12] = 0u;
	v_ashrrev_i32_e32 v2, 31, v1

; DI unsigned fkey(float f) { const unsigned u = __float_as_uint(f); return (u & 0x80000000u) ? ~u : (u | 0x80000000u); }
; DI void topk_phase(unsigned char* smem_, const bf16_t* __restrict__ qp, const bf16_t* __restrict__ keys, int* __restrict__ eidx, float* __restrict__ gate) {
;     ...
;     for (int i = 0; i < 13; ++i) {
;         const unsigned ab = (KT[i] >> (8 * q)) & 255u;
;         const float c = SV[row * 32 + (ab >> 4)] + SV[row * 32 + 16 + (ab & 15u)];
;         c16[i] = (fkey(c) & ~255u) | (255u - ab);
;     }
;     if (q >= 2) c16[12] = 0u;
	v_bitop3_b32 v9, v12, s98, v9 bitop3:0x56
	v_ashrrev_i32_e32 v12, 31, v8


; DI unsigned fkey(float f) { const unsigned u = __float_as_uint(f); return (u & 0x80000000u) ? ~u : (u | 0x80000000u); }
; DI void topk_phase(unsigned char* smem_, const bf16_t* __restrict__ qp, const bf16_t* __restrict__ keys, int* __restrict__ eidx, float* __restrict__ gate) {
;     ...
;     for (int i = 0; i < 13; ++i) {
;         const unsigned ab = (KT[i] >> (8 * q)) & 255u;
;         const float c = SV[row * 32 + (ab >> 4)] + SV[row * 32 + 16 + (ab & 15u)];
;         c16[i] = (fkey(c) & ~255u) | (255u - ab);
;     }
;     if (q >= 2) c16[12] = 0u;
	v_and_b32_e32 v9, 0xffffff00, v9
	v_bitop3_b32 v9, v9, s71, v218 bitop3:0x36
	v_bitop3_b32 v8, v12, s98, v8 bitop3:0x56

; DI unsigned fkey(float f) { const unsigned u = __float_as_uint(f); return (u & 0x80000000u) ? ~u : (u | 0x80000000u); }
; DI void topk_phase(unsigned char* smem_, const bf16_t* __restrict__ qp, const bf16_t* __restrict__ keys, int* __restrict__ eidx, float* __restrict__ gate) {
;     ...
;     for (int i = 0; i < 13; ++i) {
;         const unsigned ab = (KT[i] >> (8 * q)) & 255u;
;         const float c = SV[row * 32 + (ab >> 4)] + SV[row * 32 + 16 + (ab & 15u)];
;         c16[i] = (fkey(c) & ~255u) | (255u - ab);
;     }
;     if (q >= 2) c16[12] = 0u;
	v_and_b32_e32 v8, 0xffffff00, v8
	v_bitop3_b32 v8, v8, s71, v221 bitop3:0x36
	v_bitop3_b32 v1, v2, s98, v1 bitop3:0x56
	v_and_b32_e32 v1, 0xffffff00, v1
	v_bitop3_b32 v2, v1, s71, v224 bitop3:0x36
	v_ashrrev_i32_e32 v1, 31, v0


; DI unsigned fkey(float f) { const unsigned u = __float_as_uint(f); return (u & 0x80000000u) ? ~u : (u | 0x80000000u); }
; template <int N> DI void bitonic_sort_desc(unsigned (&v)[N]) {
; #pragma unroll
;     for (int k = 2; k <= N; k <<= 1)
; #pragma unroll
;         for (int j = k >> 1; j > 0; j >>= 1)
; #pragma unroll
;             for (int i = 0; i < N; ++i) { const int l = i ^ j; if (l > i) { if ((i & k) == 0) cswap(v[i], v[l]); else cswap(v[l], v[i]); } }
; DI void topk_phase(unsigned char* smem_, const bf16_t* __restrict__ qp, const bf16_t* __restrict__ keys, int* __restrict__ eidx, float* __restrict__ gate) {
;     ...
;     for (int i = 0; i < 13; ++i) {
;         const unsigned ab = (KT[i] >> (8 * q)) & 255u;
;         const float c = SV[row * 32 + (ab >> 4)] + SV[row * 32 + 16 + (ab & 15u)];
;         c16[i] = (fkey(c) & ~255u) | (255u - ab);
;     }
;     if (q >= 2) c16[12] = 0u;
;     c16[13] = 0u; c16[14] = 0u; c16[15] = 0u;
;     bitonic_sort_desc<16>(c16);
	v_max_u32_e32 v12, v19, v10
	v_min_u32_e32 v10, v19, v10
	v_bitop3_b32 v0, v1, s98, v0 bitop3:0x56
	v_and_b32_e32 v0, 0xffffff00, v0
	v_bitop3_b32 v3, v0, s71, v227 bitop3:0x36
	s_waitcnt lgkmcnt(0)
	v_pk_add_f32 v[0:1], v[6:7], v[4:5] op_sel_hi:[1,0]
	v_min_u32_e32 v7, v18, v17
	v_ashrrev_i32_e32 v4, 31, v1


; DI unsigned fkey(float f) { const unsigned u = __float_as_uint(f); return (u & 0x80000000u) ? ~u : (u | 0x80000000u); }
; template <int N> DI void bitonic_sort_desc(unsigned (&v)[N]) {
; #pragma unroll
;     for (int k = 2; k <= N; k <<= 1)
; #pragma unroll
;         for (int j = k >> 1; j > 0; j >>= 1)
; #pragma unroll
;             for (int i = 0; i < N; ++i) { const int l = i ^ j; if (l > i) { if ((i & k) == 0) cswap(v[i], v[l]); else cswap(v[l], v[i]); } }
; DI void topk_phase(unsigned char* smem_, const bf16_t* __restrict__ qp, const bf16_t* __restrict__ keys, int* __restrict__ eidx, float* __restrict__ gate) {
;     ...
;     for (int i = 0; i < 13; ++i) {
;         const unsigned ab = (KT[i] >> (8 * q)) & 255u;
;         const float c = SV[row * 32 + (ab >> 4)] + SV[row * 32 + 16 + (ab & 15u)];
;         c16[i] = (fkey(c) & ~255u) | (255u - ab);
;     }
;     if (q >= 2) c16[12] = 0u;
;     c16[13] = 0u; c16[14] = 0u; c16[15] = 0u;
;     bitonic_sort_desc<16>(c16);
	v_max_u32_e32 v13, v9, v11
	v_min_u32_e32 v9, v9, v11
	v_bitop3_b32 v1, v4, s98, v1 bitop3:0x56
	v_and_b32_e32 v1, 0xffffff00, v1
	v_ashrrev_i32_e32 v4, 31, v0


; template <int N> DI void bitonic_sort_desc(unsigned (&v)[N]) {
; #pragma unroll
;     for (int k = 2; k <= N; k <<= 1)
; #pragma unroll
;         for (int j = k >> 1; j > 0; j >>= 1)
; #pragma unroll
;             for (int i = 0; i < N; ++i) { const int l = i ^ j; if (l > i) { if ((i & k) == 0) cswap(v[i], v[l]); else cswap(v[l], v[i]); } }
; }
; DI void merge_top16(unsigned (&v)[16], int st) {
;     unsigned x[16];
; #pragma unroll
;     for (int i = 0; i < 16; ++i) x[i] = (unsigned)__shfl_xor((int)v[15 - i], st);
; #pragma unroll
;     for (int i = 0; i < 16; ++i) v[i] = max(v[i], x[i]);
; #pragma unroll
;     for (int j = 8; j > 0; j >>= 1)
; #pragma unroll
;         for (int i = 0; i < 16; ++i) { const int l = i ^ j; if (l > i) cswap(v[i], v[l]); }
; }
; DI void topk_phase(unsigned char* smem_, const bf16_t* __restrict__ qp, const bf16_t* __restrict__ keys, int* __restrict__ eidx, float* __restrict__ gate) {
;     ...
;     if (q >= 2) c16[12] = 0u;
;     c16[13] = 0u; c16[14] = 0u; c16[15] = 0u;
;     bitonic_sort_desc<16>(c16);
;     merge_top16(c16, 1);
;     merge_top16(c16, 2);
	v_bitop3_b32 v1, v1, s71, v230 bitop3:0x36
	v_max_u32_e32 v11, v8, v2
	v_bitop3_b32 v0, v4, s98, v0 bitop3:0x56
	v_and_b32_e32 v0, 0xffffff00, v0
	v_max_u32_e32 v4, v5, v16
	v_min_u32_e32 v5, v5, v16
	v_max_u32_e32 v6, v18, v17
	v_min_u32_e32 v2, v8, v2
	v_max_u32_e32 v8, v1, v3
	v_min_u32_e32 v1, v1, v3
	v_bitop3_b32 v0, v0, s71, v231 bitop3:0x36
	v_max_u32_e32 v3, v4, v7
	v_min_u32_e32 v4, v4, v7
	v_max_u32_e32 v7, v5, v6
	v_min_u32_e32 v5, v5, v6
	v_max_u32_e32 v6, v9, v12
	v_min_u32_e32 v9, v9, v12
	v_max_u32_e32 v12, v13, v10
	v_min_u32_e32 v10, v13, v10
	v_max_u32_e32 v13, v11, v1
	v_min_u32_e32 v1, v11, v1
	v_max_u32_e32 v11, v2, v8
	v_min_u32_e32 v2, v2, v8
	v_cndmask_b32_e64 v0, v0, 0, s[2:3]
	v_max_u32_e32 v8, v3, v7
	v_min_u32_e32 v3, v3, v7
	v_max_u32_e32 v7, v4, v5
	v_min_u32_e32 v4, v4, v5
	v_max_u32_e32 v5, v10, v9
	v_min_u32_e32 v9, v10, v9
	v_max_u32_e32 v10, v12, v6
	v_min_u32_e32 v6, v12, v6
	v_max_u32_e32 v12, v13, v11
	v_min_u32_e32 v11, v13, v11
	v_max_u32_e32 v13, v1, v2
	v_min_u32_e32 v1, v1, v2
	v_max_u32_e32 v2, v8, v9
	v_min_u32_e32 v8, v8, v9
	v_max_u32_e32 v9, v3, v5
	v_min_u32_e32 v3, v3, v5
	v_max_u32_e32 v5, v7, v6
	v_min_u32_e32 v6, v7, v6
	v_max_u32_e32 v7, v4, v10
	v_min_u32_e32 v4, v4, v10
	v_max_u32_e32 v10, v0, v1
	v_min_u32_e32 v0, v0, v1
	v_max_u32_e32 v1, v2, v5
	v_min_u32_e32 v2, v2, v5
	v_max_u32_e32 v5, v9, v7
	v_min_u32_e32 v7, v9, v7
	v_max_u32_e32 v9, v8, v6
	v_min_u32_e32 v6, v8, v6
	v_max_u32_e32 v8, v3, v4
	v_min_u32_e32 v3, v3, v4
	v_max_u32_e32 v4, v13, v12
	v_min_u32_e32 v12, v13, v12
	v_max_u32_e32 v13, v10, v11
	v_min_u32_e32 v10, v10, v11
	v_max_u32_e32 v11, v1, v5
	v_min_u32_e32 v1, v1, v5
	v_max_u32_e32 v5, v2, v7
	v_min_u32_e32 v2, v2, v7
	v_max_u32_e32 v7, v9, v8
	v_min_u32_e32 v8, v9, v8
	v_max_u32_e32 v9, v6, v3
	v_min_u32_e32 v3, v6, v3
	v_max_u32_e32 v6, v10, v12
	v_min_u32_e32 v10, v10, v12
	v_max_u32_e32 v12, v13, v4
	v_min_u32_e32 v4, v13, v4
	v_max_u32_e32 v13, v2, v0
	v_min_u32_e32 v0, v2, v0
	v_max_u32_e32 v2, v7, v10
	v_min_u32_e32 v7, v7, v10
	v_max_u32_e32 v10, v8, v6
	v_min_u32_e32 v6, v8, v6
	v_max_u32_e32 v8, v9, v4
	v_min_u32_e32 v4, v9, v4
	v_max_u32_e32 v9, v3, v12
	v_min_u32_e32 v3, v3, v12
	v_max_u32_e32 v12, v11, v2
	v_min_u32_e32 v2, v11, v2
	v_max_u32_e32 v11, v1, v10
	v_min_u32_e32 v1, v1, v10
	v_max_u32_e32 v10, v5, v8
	v_min_u32_e32 v5, v5, v8
	v_max_u32_e32 v8, v13, v9
	v_min_u32_e32 v9, v13, v9
	v_max_u32_e32 v13, v0, v3
	v_min_u32_e32 v0, v0, v3
	v_max_u32_e32 v3, v12, v10
	v_min_u32_e32 v10, v12, v10
	v_max_u32_e32 v12, v11, v8
	v_min_u32_e32 v8, v11, v8
	v_max_u32_e32 v11, v2, v5
	v_min_u32_e32 v2, v2, v5
	v_max_u32_e32 v5, v1, v9
	v_min_u32_e32 v1, v1, v9
	v_max_u32_e32 v9, v7, v4
	v_min_u32_e32 v4, v7, v4
	v_max_u32_e32 v7, v6, v13
	v_min_u32_e32 v6, v6, v13
	v_max_u32_e32 v13, v3, v12
	v_min_u32_e32 v3, v3, v12
	v_max_u32_e32 v12, v10, v8
	v_min_u32_e32 v8, v10, v8
	v_max_u32_e32 v10, v11, v5
	v_min_u32_e32 v5, v11, v5
	v_max_u32_e32 v11, v2, v1
	v_min_u32_e32 v1, v2, v1
	v_max_u32_e32 v2, v9, v7
	v_min_u32_e32 v7, v9, v7
	v_max_u32_e32 v9, v4, v6
	v_min_u32_e32 v4, v4, v6
	s_nop 1
	v_mov_b32_dpp v6, v0 quad_perm:[1,0,3,2] row_mask:0xf bank_mask:0xf
	v_mov_b32_dpp v14, v4 quad_perm:[1,0,3,2] row_mask:0xf bank_mask:0xf
	v_mov_b32_dpp v15, v9 quad_perm:[1,0,3,2] row_mask:0xf bank_mask:0xf
	v_mov_b32_dpp v16, v7 quad_perm:[1,0,3,2] row_mask:0xf bank_mask:0xf
	v_mov_b32_dpp v17, v2 quad_perm:[1,0,3,2] row_mask:0xf bank_mask:0xf
	v_mov_b32_dpp v18, v1 quad_perm:[1,0,3,2] row_mask:0xf bank_mask:0xf
	v_mov_b32_dpp v19, v11 quad_perm:[1,0,3,2] row_mask:0xf bank_mask:0xf
	v_mov_b32_dpp v20, v5 quad_perm:[1,0,3,2] row_mask:0xf bank_mask:0xf
	v_mov_b32_dpp v21, v10 quad_perm:[1,0,3,2] row_mask:0xf bank_mask:0xf
	v_mov_b32_dpp v22, v8 quad_perm:[1,0,3,2] row_mask:0xf bank_mask:0xf
	v_mov_b32_dpp v23, v12 quad_perm:[1,0,3,2] row_mask:0xf bank_mask:0xf
	v_mov_b32_dpp v24, v3 quad_perm:[1,0,3,2] row_mask:0xf bank_mask:0xf
	v_mov_b32_dpp v25, v13 quad_perm:[1,0,3,2] row_mask:0xf bank_mask:0xf
	s_waitcnt lgkmcnt(0)
	v_max_u32_e32 v6, v8, v6
	v_max_u32_e32 v8, v10, v14
	v_max_u32_e32 v5, v5, v15
	v_max_u32_e32 v10, v11, v16
	v_max_u32_e32 v1, v1, v17
	v_max_u32_e32 v2, v2, v18
	v_max_u32_e32 v7, v7, v19
	v_max_u32_e32 v9, v9, v20
	v_max_u32_e32 v4, v4, v21
	v_max_u32_e32 v0, v0, v22
	v_max_u32_e32 v11, v13, v2
	v_min_u32_e32 v2, v13, v2
	v_max_u32_e32 v13, v3, v7
	v_min_u32_e32 v3, v3, v7
	v_max_u32_e32 v7, v12, v9
	v_min_u32_e32 v9, v12, v9
	v_max_u32_e32 v12, v6, v4
	v_min_u32_e32 v4, v6, v4
	v_max_u32_e32 v6, v8, v0
	v_min_u32_e32 v0, v8, v0
	v_max_u32_e32 v8, v5, v23
	v_min_u32_e32 v5, v5, v23
	v_max_u32_e32 v14, v10, v24
	v_min_u32_e32 v10, v10, v24
	v_max_u32_e32 v15, v1, v25
	v_min_u32_e32 v1, v1, v25
	v_max_u32_e32 v16, v11, v6
	v_min_u32_e32 v6, v11, v6
	v_max_u32_e32 v11, v13, v8
	v_min_u32_e32 v8, v13, v8
	v_max_u32_e32 v13, v7, v14
	v_min_u32_e32 v7, v7, v14
	v_max_u32_e32 v14, v12, v15
	v_min_u32_e32 v12, v12, v15
	v_max_u32_e32 v15, v2, v0
	v_min_u32_e32 v0, v2, v0
	v_max_u32_e32 v2, v3, v5
	v_min_u32_e32 v3, v3, v5
	v_max_u32_e32 v5, v9, v10
	v_min_u32_e32 v9, v9, v10
	v_max_u32_e32 v10, v4, v1
	v_min_u32_e32 v1, v4, v1
	v_max_u32_e32 v4, v16, v13
	v_min_u32_e32 v13, v16, v13
	v_max_u32_e32 v16, v11, v14
	v_min_u32_e32 v11, v11, v14
	v_max_u32_e32 v14, v6, v7
	v_min_u32_e32 v6, v6, v7
	v_max_u32_e32 v7, v8, v12
	v_min_u32_e32 v8, v8, v12
	v_max_u32_e32 v12, v15, v5
	v_min_u32_e32 v5, v15, v5
	v_max_u32_e32 v15, v2, v10
	v_min_u32_e32 v2, v2, v10
	v_max_u32_e32 v10, v0, v9
	v_min_u32_e32 v0, v0, v9
	v_max_u32_e32 v9, v3, v1
	v_min_u32_e32 v1, v3, v1
; DI void merge_top16(unsigned (&v)[16], int st) {
;     unsigned x[16];
; #pragma unroll
;     for (int i = 0; i < 16; ++i) x[i] = (unsigned)__shfl_xor((int)v[15 - i], st);
; #pragma unroll
;     for (int i = 0; i < 16; ++i) v[i] = max(v[i], x[i]);
; #pragma unroll
;     for (int j = 8; j > 0; j >>= 1)
; #pragma unroll
;         for (int i = 0; i < 16; ++i) { const int l = i ^ j; if (l > i) cswap(v[i], v[l]); }
; }
; DI void topk_phase(unsigned char* smem_, const bf16_t* __restrict__ qp, const bf16_t* __restrict__ keys, int* __restrict__ eidx, float* __restrict__ gate) {
;     ...
;     merge_top16(c16, 1);
;     merge_top16(c16, 2);
;     float bv[16]; int be[16]; float mx = -3.0e38f;
; #pragma unroll
;     for (int i = 0; i < 16; ++i) {
;         const int ab = 255 - (int)(c16[i] & 255u), a = ab >> 4, b = ab & 15;
;         bv[i] = SV[row * 32 + a] + SV[row * 32 + 16 + b];
;         be[i] = SI[row * 32 + a] * 128 + SI[row * 32 + 16 + b];
;         mx = fmaxf(mx, bv[i]);
	v_max_u32_e32 v3, v4, v16
	v_min_u32_e32 v4, v4, v16
	v_max_u32_e32 v16, v13, v11
	v_min_u32_e32 v11, v13, v11
	v_max_u32_e32 v13, v14, v7
	v_min_u32_e32 v7, v14, v7
	v_max_u32_e32 v14, v6, v8
	v_min_u32_e32 v6, v6, v8
	v_max_u32_e32 v8, v12, v15
	v_min_u32_e32 v12, v12, v15
	v_max_u32_e32 v15, v5, v2
	v_min_u32_e32 v2, v5, v2
	v_max_u32_e32 v5, v10, v9
	v_min_u32_e32 v9, v10, v9
	v_max_u32_e32 v10, v0, v1
	v_min_u32_e32 v0, v0, v1
	s_nop 1
	v_mov_b32_dpp v1, v0 quad_perm:[2,3,0,1] row_mask:0xf bank_mask:0xf
	v_mov_b32_dpp v17, v10 quad_perm:[2,3,0,1] row_mask:0xf bank_mask:0xf
	v_mov_b32_dpp v18, v9 quad_perm:[2,3,0,1] row_mask:0xf bank_mask:0xf
	v_mov_b32_dpp v19, v5 quad_perm:[2,3,0,1] row_mask:0xf bank_mask:0xf
	v_mov_b32_dpp v20, v2 quad_perm:[2,3,0,1] row_mask:0xf bank_mask:0xf
	v_mov_b32_dpp v21, v15 quad_perm:[2,3,0,1] row_mask:0xf bank_mask:0xf
	v_mov_b32_dpp v22, v12 quad_perm:[2,3,0,1] row_mask:0xf bank_mask:0xf
	v_mov_b32_dpp v23, v8 quad_perm:[2,3,0,1] row_mask:0xf bank_mask:0xf
	v_mov_b32_dpp v24, v6 quad_perm:[2,3,0,1] row_mask:0xf bank_mask:0xf
	v_mov_b32_dpp v25, v14 quad_perm:[2,3,0,1] row_mask:0xf bank_mask:0xf
	v_mov_b32_dpp v26, v7 quad_perm:[2,3,0,1] row_mask:0xf bank_mask:0xf
	v_mov_b32_dpp v27, v13 quad_perm:[2,3,0,1] row_mask:0xf bank_mask:0xf
	v_mov_b32_dpp v28, v11 quad_perm:[2,3,0,1] row_mask:0xf bank_mask:0xf
	v_mov_b32_dpp v29, v16 quad_perm:[2,3,0,1] row_mask:0xf bank_mask:0xf
	v_mov_b32_dpp v30, v4 quad_perm:[2,3,0,1] row_mask:0xf bank_mask:0xf
	v_mov_b32_dpp v31, v3 quad_perm:[2,3,0,1] row_mask:0xf bank_mask:0xf
	s_waitcnt lgkmcnt(0)
	v_max_u32_e32 v1, v3, v1
	v_max_u32_e32 v3, v4, v17
	v_max_u32_e32 v4, v16, v18
	v_max_u32_e32 v11, v11, v19
	v_max_u32_e32 v13, v13, v20
	v_max_u32_e32 v7, v7, v21
	v_max_u32_e32 v14, v14, v22
	v_max_u32_e32 v6, v6, v23
	v_max_u32_e32 v8, v8, v24
	v_max_u32_e32 v12, v12, v25
	v_max_u32_e32 v15, v15, v26
	v_max_u32_e32 v2, v2, v27
	v_max_u32_e32 v5, v5, v28
	v_max_u32_e32 v9, v9, v29
	v_max_u32_e32 v10, v10, v30
	v_max_u32_e32 v0, v0, v31
	v_max_u32_e32 v16, v1, v8
	v_min_u32_e32 v1, v1, v8
	v_max_u32_e32 v8, v3, v12
	v_min_u32_e32 v3, v3, v12
	v_max_u32_e32 v12, v4, v15
	v_min_u32_e32 v4, v4, v15
	v_max_u32_e32 v15, v11, v2
	v_min_u32_e32 v2, v11, v2
	v_max_u32_e32 v11, v13, v5
	v_min_u32_e32 v5, v13, v5
	v_max_u32_e32 v13, v7, v9
	v_min_u32_e32 v7, v7, v9
	v_max_u32_e32 v9, v14, v10
	v_min_u32_e32 v10, v14, v10
	v_max_u32_e32 v14, v6, v0
	v_min_u32_e32 v0, v6, v0
	v_max_u32_e32 v6, v16, v11
	v_min_u32_e32 v11, v16, v11
	v_max_u32_e32 v16, v8, v13
	v_min_u32_e32 v8, v8, v13
	v_max_u32_e32 v13, v12, v9
	v_min_u32_e32 v9, v12, v9
	v_max_u32_e32 v12, v15, v14
	v_min_u32_e32 v14, v15, v14
	v_max_u32_e32 v15, v1, v5
	v_min_u32_e32 v1, v1, v5
	v_max_u32_e32 v5, v3, v7
	v_min_u32_e32 v3, v3, v7
	v_max_u32_e32 v7, v4, v10
	v_min_u32_e32 v4, v4, v10
	v_max_u32_e32 v10, v2, v0
	v_min_u32_e32 v0, v2, v0
	v_max_u32_e32 v2, v6, v13
	v_min_u32_e32 v6, v6, v13
	v_max_u32_e32 v13, v16, v12
	v_min_u32_e32 v12, v16, v12
	v_max_u32_e32 v16, v11, v9
	v_min_u32_e32 v9, v11, v9
	v_max_u32_e32 v11, v8, v14
	v_min_u32_e32 v8, v8, v14
	v_max_u32_e32 v14, v15, v7
	v_min_u32_e32 v7, v15, v7
	v_max_u32_e32 v15, v5, v10
	v_min_u32_e32 v5, v5, v10
	v_max_u32_e32 v10, v1, v4
	v_min_u32_e32 v1, v1, v4
	v_max_u32_e32 v4, v3, v0
	v_min_u32_e32 v0, v3, v0
	v_max_u32_e32 v3, v2, v13
	v_not_b32_e32 v17, v3
	v_min_u32_e32 v2, v2, v13
	v_max_u32_e32 v142, v1, v0
	v_min_u32_e32 v144, v1, v0
	v_lshrrev_b32_e32 v0, 4, v17
	v_not_b32_e32 v13, v2
	v_and_or_b32 v0, v0, 15, v174
	v_max_u32_e32 v18, v6, v12
	v_lshl_add_u32 v237, v0, 2, s19
	v_lshrrev_b32_e32 v0, 4, v13
	v_not_b32_e32 v19, v18
	v_and_or_b32 v0, v0, 15, v174
	v_min_u32_e32 v6, v6, v12
	v_bitop3_b32 v1, v3, 15, v3 bitop3:0xc
	v_lshl_add_u32 v239, v0, 2, s19
	v_lshrrev_b32_e32 v0, 4, v19
	v_not_b32_e32 v12, v6
	v_lshl_add_u32 v238, v1, 2, v184
	v_bitop3_b32 v1, v2, 15, v2 bitop3:0xc
	v_and_or_b32 v0, v0, 15, v174
	v_lshl_add_u32 v240, v1, 2, v175
	v_bitop3_b32 v1, v18, 15, v18 bitop3:0xc
	v_lshl_add_u32 v241, v0, 2, s19
	v_lshrrev_b32_e32 v0, 4, v12
	v_lshl_add_u32 v242, v1, 2, v184
	v_bitop3_b32 v1, v6, 15, v6 bitop3:0xc
	v_and_or_b32 v0, v0, 15, v174
	v_max_u32_e32 v30, v7, v5
	v_min_u32_e32 v116, v7, v5
	v_max_u32_e32 v120, v10, v4
	v_min_u32_e32 v124, v10, v4
	v_lshl_add_u32 v243, v0, 2, s19
	v_lshl_add_u32 v244, v1, 2, v175
	ds_read_b32 v0, v237 offset:53248
	ds_read_b32 v1, v238 offset:53312
	ds_read_b32 v2, v239 offset:53248
	ds_read_b32 v3, v240 offset:53312
	ds_read_b32 v4, v241 offset:53248
	ds_read_b32 v5, v242 offset:53312
	ds_read_b32 v6, v243 offset:53248
	ds_read_b32 v7, v244 offset:53312
	v_max_u32_e32 v20, v16, v11
	v_min_u32_e32 v11, v16, v11
	v_not_b32_e32 v16, v11
	s_waitcnt lgkmcnt(2)
	v_add_f32_e32 v148, v4, v5
	v_lshrrev_b32_e32 v5, 4, v16
	v_and_or_b32 v5, v5, 15, v174
	v_bitop3_b32 v10, v11, 15, v11 bitop3:0xc
	v_lshl_add_u32 v5, v5, 2, s19
	v_max_u32_e32 v22, v9, v8
	s_waitcnt lgkmcnt(0)
; DI void topk_phase(unsigned char* smem_, const bf16_t* __restrict__ qp, const bf16_t* __restrict__ keys, int* __restrict__ eidx, float* __restrict__ gate) {
;     ...
;     float bv[16]; int be[16]; float mx = -3.0e38f;
; #pragma unroll
;     for (int i = 0; i < 16; ++i) {
;         const int ab = 255 - (int)(c16[i] & 255u), a = ab >> 4, b = ab & 15;
;         bv[i] = SV[row * 32 + a] + SV[row * 32 + 16 + b];
;         be[i] = SI[row * 32 + a] * 128 + SI[row * 32 + 16 + b];
;         mx = fmaxf(mx, bv[i]);
;     }
;     float sum = 0.f, ex[16];
; #pragma unroll
;     for (int i = 0; i < 16; ++i) { ex[i] = __expf(bv[i] - mx); sum += ex[i]; }
;     const float inv = 1.f / sum;
;     const size_t ob = (size_t)(tok0 + row) * 128 + h * 16;
; #pragma unroll
;     for (int i = 0; i < 16; ++i) if ((i >> 2) == q) { eidx[ob + i] = be[i]; gate[ob + i] = ex[i] * inv; }
	v_add_f32_e32 v149, v6, v7
	ds_read2st64_b32 v[6:7], v5 offset0:208 offset1:240
	v_lshl_add_u32 v5, v10, 2, v175
	v_not_b32_e32 v23, v22
	v_add_u32_e32 v5, 64, v5
	ds_read2st64_b32 v[10:11], v5 offset0:208 offset1:240
	v_lshrrev_b32_e32 v5, 4, v23
	v_and_or_b32 v5, v5, 15, v174
	v_bitop3_b32 v12, v22, 15, v22 bitop3:0xc
	v_lshl_add_u32 v5, v5, 2, s19
	v_min_u32_e32 v8, v9, v8
	v_max_u32_e32 v24, v14, v15
	v_min_u32_e32 v26, v14, v15
	v_add_f32_e32 v146, v0, v1
	v_add_f32_e32 v147, v2, v3
	ds_read2st64_b32 v[14:15], v5 offset0:208 offset1:240
	v_lshl_add_u32 v5, v12, 2, v184
	v_not_b32_e32 v21, v20
	v_not_b32_e32 v9, v8
	v_max3_f32 v0, v146, s16, v147
	v_add_u32_e32 v5, 64, v5
	v_max3_f32 v4, v0, v148, v149
	v_lshrrev_b32_e32 v0, 4, v21
	v_bitop3_b32 v2, v20, 15, v20 bitop3:0xc
	ds_read2st64_b32 v[20:21], v5 offset0:208 offset1:240
	v_lshrrev_b32_e32 v5, 4, v9
	v_and_or_b32 v0, v0, 15, v174
	v_lshl_add_u32 v2, v2, 2, v184
	v_and_or_b32 v5, v5, 15, v174
	v_lshl_add_u32 v0, v0, 2, s19
	v_add_u32_e32 v2, 64, v2
	v_bitop3_b32 v8, v8, 15, v8 bitop3:0xc
	v_lshl_add_u32 v5, v5, 2, s19
	ds_read2st64_b32 v[0:1], v0 offset0:208 offset1:240
	ds_read2st64_b32 v[2:3], v2 offset0:208 offset1:240
	ds_read2st64_b32 v[28:29], v5 offset0:208 offset1:240
	v_lshl_add_u32 v5, v8, 2, v175
	v_add_u32_e32 v5, 64, v5
	v_not_b32_e32 v27, v26
	ds_read2st64_b32 v[118:119], v5 offset0:208 offset1:240
	v_lshrrev_b32_e32 v13, 4, v27
	v_and_or_b32 v13, v13, 15, v174
	s_waitcnt lgkmcnt(2)
	v_add_f32_e32 v0, v0, v2
	v_add_f32_e32 v2, v6, v10
	v_add_f32_e32 v6, v14, v20
	v_bitop3_b32 v14, v26, 15, v26 bitop3:0xc
	v_lshl_add_u32 v13, v13, 2, s19
	ds_read2st64_b32 v[16:17], v13 offset0:208 offset1:240
	v_lshl_add_u32 v13, v14, 2, v175
	v_not_b32_e32 v25, v24
	v_not_b32_e32 v31, v30
	v_max3_f32 v4, v4, v0, v2
	s_waitcnt lgkmcnt(1)
	v_add_f32_e32 v10, v28, v118
	v_add_u32_e32 v13, 64, v13
	v_max3_f32 v12, v4, v6, v10
	v_lshrrev_b32_e32 v4, 4, v25
	v_bitop3_b32 v8, v24, 15, v24 bitop3:0xc
	ds_read2st64_b32 v[22:23], v13 offset0:208 offset1:240
	v_lshrrev_b32_e32 v13, 4, v31
	v_and_or_b32 v4, v4, 15, v174
	v_lshl_add_u32 v8, v8, 2, v184
	v_and_or_b32 v13, v13, 15, v174
	v_lshl_add_u32 v4, v4, 2, s19
	v_add_u32_e32 v8, 64, v8
	v_bitop3_b32 v14, v30, 15, v30 bitop3:0xc
	v_lshl_add_u32 v13, v13, 2, s19
	ds_read2st64_b32 v[4:5], v4 offset0:208 offset1:240
	ds_read2st64_b32 v[8:9], v8 offset0:208 offset1:240
	ds_read2st64_b32 v[24:25], v13 offset0:208 offset1:240
	v_lshl_add_u32 v13, v14, 2, v184
	v_not_b32_e32 v117, v116
	v_add_u32_e32 v13, 64, v13
	ds_read2st64_b32 v[30:31], v13 offset0:208 offset1:240
	v_lshrrev_b32_e32 v13, 4, v117
	v_and_or_b32 v13, v13, 15, v174
	v_not_b32_e32 v125, v124
	v_bitop3_b32 v14, v116, 15, v116 bitop3:0xc
	v_lshl_add_u32 v13, v13, 2, s19
	ds_read2st64_b32 v[122:123], v13 offset0:208 offset1:240
	v_lshl_add_u32 v13, v14, 2, v175
	s_waitcnt lgkmcnt(3)
	v_add_f32_e32 v4, v4, v8
	v_add_f32_e32 v8, v16, v22
	v_lshrrev_b32_e32 v22, 4, v125
	v_add_u32_e32 v13, 64, v13
	v_and_or_b32 v22, v22, 15, v174
	ds_read2st64_b32 v[126:127], v13 offset0:208 offset1:240
	s_waitcnt lgkmcnt(2)
	v_add_f32_e32 v14, v24, v30
	v_bitop3_b32 v24, v124, 15, v124 bitop3:0xc
	v_lshl_add_u32 v22, v22, 2, s19
	ds_read2st64_b32 v[26:27], v22 offset0:208 offset1:240
	v_lshl_add_u32 v22, v24, 2, v175
	v_not_b32_e32 v143, v142
	v_add_u32_e32 v22, 64, v22
	ds_read2st64_b32 v[116:117], v22 offset0:208 offset1:240
	v_lshrrev_b32_e32 v22, 4, v143
	v_and_or_b32 v22, v22, 15, v174
	v_not_b32_e32 v121, v120
	v_max3_f32 v12, v12, v4, v8
	s_waitcnt lgkmcnt(2)
	v_add_f32_e32 v16, v122, v126
	v_bitop3_b32 v24, v142, 15, v142 bitop3:0xc
	v_lshl_add_u32 v22, v22, 2, s19
	v_max3_f32 v20, v12, v14, v16
	v_lshrrev_b32_e32 v12, 4, v121
	v_bitop3_b32 v18, v120, 15, v120 bitop3:0xc
	ds_read2st64_b32 v[120:121], v22 offset0:208 offset1:240
	v_lshl_add_u32 v22, v24, 2, v184
	v_not_b32_e32 v145, v144
	v_add_u32_e32 v22, 64, v22
	ds_read2st64_b32 v[124:125], v22 offset0:208 offset1:240
	v_lshrrev_b32_e32 v22, 4, v145
	v_and_or_b32 v22, v22, 15, v174
	v_and_or_b32 v12, v12, 15, v174
	v_lshl_add_u32 v18, v18, 2, v184
	v_bitop3_b32 v24, v144, 15, v144 bitop3:0xc
	v_lshl_add_u32 v22, v22, 2, s19
	v_lshl_add_u32 v12, v12, 2, s19
	v_add_u32_e32 v18, 64, v18
	ds_read2st64_b32 v[142:143], v22 offset0:208 offset1:240
	v_lshl_add_u32 v22, v24, 2, v175
	ds_read2st64_b32 v[12:13], v12 offset0:208 offset1:240
	ds_read2st64_b32 v[18:19], v18 offset0:208 offset1:240
	v_add_u32_e32 v22, 64, v22
	ds_read2st64_b32 v[144:145], v22 offset0:208 offset1:240
	s_waitcnt lgkmcnt(4)
	v_add_f32_e32 v22, v120, v124
	s_waitcnt lgkmcnt(1)
	v_add_f32_e32 v12, v12, v18
	v_add_f32_e32 v18, v26, v116
	v_max3_f32 v20, v20, v12, v18
	s_waitcnt lgkmcnt(0)
	v_add_f32_e32 v24, v142, v144
	v_max3_f32 v20, v20, v22, v24
	v_sub_f32_e32 v26, v146, v20
	v_mul_f32_e32 v26, 0x3fb8aa3b, v26
	v_exp_f32_e32 v160, v26
	v_sub_f32_e32 v26, v147, v20
	v_sub_f32_e32 v0, v0, v20
	v_mul_f32_e32 v26, 0x3fb8aa3b, v26
	v_mul_f32_e32 v0, 0x3fb8aa3b, v0
	v_exp_f32_e32 v161, v26
	v_sub_f32_e32 v26, v148, v20
	v_exp_f32_e32 v154, v0
	v_sub_f32_e32 v0, v2, v20
	v_sub_f32_e32 v2, v4, v20
	v_mul_f32_e32 v26, 0x3fb8aa3b, v26
	v_mul_f32_e32 v2, 0x3fb8aa3b, v2
	v_exp_f32_e32 v162, v26
	v_sub_f32_e32 v26, v149, v20
	v_exp_f32_e32 v150, v2
	v_sub_f32_e32 v2, v8, v20
	v_mul_f32_e32 v26, 0x3fb8aa3b, v26
	v_mul_f32_e32 v0, 0x3fb8aa3b, v0
	v_mul_f32_e32 v2, 0x3fb8aa3b, v2
	v_exp_f32_e32 v163, v26
	v_exp_f32_e32 v155, v0
	v_sub_f32_e32 v0, v6, v20
	v_exp_f32_e32 v151, v2
	v_sub_f32_e32 v2, v14, v20
	v_add_f32_e32 v26, 0, v160
	v_mul_f32_e32 v0, 0x3fb8aa3b, v0
	v_mul_f32_e32 v2, 0x3fb8aa3b, v2
	v_add_f32_e32 v26, v161, v26
	v_exp_f32_e32 v156, v0
	v_sub_f32_e32 v0, v10, v20
	v_exp_f32_e32 v152, v2
	v_sub_f32_e32 v2, v16, v20
	v_add_f32_e32 v26, v162, v26
	v_mul_f32_e32 v0, 0x3fb8aa3b, v0
	v_mul_f32_e32 v2, 0x3fb8aa3b, v2
	v_add_f32_e32 v26, v163, v26
	v_exp_f32_e32 v157, v0
	v_exp_f32_e32 v153, v2
	v_sub_f32_e32 v2, v12, v20
	v_add_f32_e32 v0, v154, v26
	v_mul_f32_e32 v2, 0x3fb8aa3b, v2
	v_add_f32_e32 v0, v155, v0
	v_exp_f32_e32 v146, v2
	v_sub_f32_e32 v2, v18, v20
	v_add_f32_e32 v0, v156, v0
	v_mul_f32_e32 v2, 0x3fb8aa3b, v2
	v_add_f32_e32 v0, v157, v0
	v_exp_f32_e32 v147, v2
	v_sub_f32_e32 v2, v22, v20
	v_add_f32_e32 v0, v150, v0
	v_mul_f32_e32 v2, 0x3fb8aa3b, v2
	v_add_f32_e32 v0, v151, v0
	v_exp_f32_e32 v148, v2
	v_sub_f32_e32 v2, v24, v20
	v_add_f32_e32 v0, v152, v0
	v_mul_f32_e32 v2, 0x3fb8aa3b, v2
	v_add_f32_e32 v0, v153, v0
	v_exp_f32_e32 v149, v2
	v_add_f32_e32 v0, v146, v0
	v_add_f32_e32 v0, v147, v0
	v_add_f32_e32 v0, v148, v0
	v_add_f32_e32 v0, v149, v0
	v_div_scale_f32 v2, s[16:17], v0, v0, 1.0
	v_rcp_f32_e32 v4, v2
	s_nop 0
	v_fma_f32 v6, -v2, v4, 1.0
	v_fmac_f32_e32 v4, v6, v4
	v_div_scale_f32 v6, vcc, 1.0, v0, 1.0
	v_mul_f32_e32 v8, v6, v4
	v_fma_f32 v10, -v2, v8, v6
	v_fmac_f32_e32 v8, v10, v4
	v_fma_f32 v2, -v2, v8, v6
	v_div_fmas_f32 v2, v2, v4, v8
	v_div_fixup_f32 v0, v2, v0, 1.0
	s_and_saveexec_b64 s[16:17], s[4:5]
	s_cbranch_execnz .LBB0_79
; DI void topk_phase(unsigned char* smem_, const bf16_t* __restrict__ qp, const bf16_t* __restrict__ keys, int* __restrict__ eidx, float* __restrict__ gate) {
;     ...
;     const size_t ob = (size_t)(tok0 + row) * 128 + h * 16;
; #pragma unroll
;     for (int i = 0; i < 16; ++i) if ((i >> 2) == q) { eidx[ob + i] = be[i]; gate[ob + i] = ex[i] * inv; }
	s_or_b64 exec, exec, s[16:17]
	s_and_saveexec_b64 s[16:17], s[6:7]
	s_cbranch_execnz .LBB0_80

; DI unsigned xcc_id() { return (unsigned)__builtin_amdgcn_s_getreg((3 << 11) | 20) & 0xFu; }
; __global__ void __launch_bounds__(512) fwd_kernel(Params p) {
;     extern __shared__ __attribute__((aligned(16))) unsigned char smem[];
;     cg::grid_group grid = cg::this_grid();
;     unsigned nsync = 0, my_xcnt = 0, nxcd = 0;
;     unsigned* ctl = (unsigned*)(p.ws + OFF_CTL);
;     const unsigned xcd = __builtin_amdgcn_readfirstlane(xcc_id());
;     if (threadIdx.x == 0) __hip_atomic_fetch_add(ctl + 512 + 16 * xcd, 1u, __ATOMIC_RELAXED, __HIP_MEMORY_SCOPE_AGENT);
;     if (p.ph_hi - p.ph_lo > 1) {
;         if (p.ph_lo < 0) grid.sync();
;         __syncthreads();
;         if (threadIdx.x == 0) {
;             __hip_atomic_fetch_add(ctl + 32, 1u, __ATOMIC_RELAXED, __HIP_MEMORY_SCOPE_AGENT);
;             while (__hip_atomic_load(ctl + 32, __ATOMIC_RELAXED, __HIP_MEMORY_SCOPE_AGENT) < gridDim.x) __builtin_amdgcn_s_sleep(2);
;         }
;         __syncthreads();
;         my_xcnt = __hip_atomic_load(ctl + 512 + 16 * xcd, __ATOMIC_RELAXED, __HIP_MEMORY_SCOPE_AGENT);
;         for (int j = 0; j < 16; ++j) nxcd += (__hip_atomic_load(ctl + 512 + 16 * j, __ATOMIC_RELAXED, __HIP_MEMORY_SCOPE_AGENT) != 0u) ? 1u : 0u;
;     }
;     for (int ph = p.ph_lo; ph < p.ph_hi; ++ph) {
;         const int reps = ((EXP_MASK >> (ph & 7)) & 1) ? 2 : 1;
;         for (int rep = 0; rep < reps; ++rep) {
;             run_phase(smem, p, ph, rep, rep + 1 < reps);
;             if (rep + 1 < reps) { ++nsync; grid_barrier(ctl, nsync, xcd, my_xcnt, nxcd); }
;         }
;         if (ph + 1 < p.ph_hi) {
;             ++nsync; grid_barrier(ctl, nsync, xcd, my_xcnt, nxcd);
;         }
;     }
; }
	.amdhsa_kernel _Z10fwd_kernel6Params
		.amdhsa_group_segment_fixed_size 6144
		.amdhsa_private_segment_fixed_size 0
		.amdhsa_kernarg_size 424
		.amdhsa_user_sgpr_count 2
		.amdhsa_user_sgpr_dispatch_ptr 0
		.amdhsa_user_sgpr_queue_ptr 0
		.amdhsa_user_sgpr_kernarg_segment_ptr 1
		.amdhsa_user_sgpr_dispatch_id 0
		.amdhsa_user_sgpr_kernarg_preload_length 0
		.amdhsa_user_sgpr_kernarg_preload_offset 0
		.amdhsa_user_sgpr_private_segment_size 0
		.amdhsa_uses_dynamic_stack 0
		.amdhsa_enable_private_segment 0
		.amdhsa_system_sgpr_workgroup_id_x 1
		.amdhsa_system_sgpr_workgroup_id_y 0
		.amdhsa_system_sgpr_workgroup_id_z 0
		.amdhsa_system_sgpr_workgroup_info 0
		.amdhsa_system_vgpr_workitem_id 2
		.amdhsa_next_free_vgpr 254
		.amdhsa_next_free_sgpr 99
		.amdhsa_accum_offset 256
		.amdhsa_reserve_vcc 1
		.amdhsa_float_round_mode_32 0
		.amdhsa_float_round_mode_16_64 0
		.amdhsa_float_denorm_mode_32 3
		.amdhsa_float_denorm_mode_16_64 3
		.amdhsa_dx10_clamp 1
		.amdhsa_ieee_mode 1
		.amdhsa_fp16_overflow 0
		.amdhsa_tg_split 0
		.amdhsa_exception_fp_ieee_invalid_op 0
		.amdhsa_exception_fp_denorm_src 0
		.amdhsa_exception_fp_ieee_div_zero 0
		.amdhsa_exception_fp_ieee_overflow 0
		.amdhsa_exception_fp_ieee_underflow 0
		.amdhsa_exception_fp_ieee_inexact 0
		.amdhsa_exception_int_div_zero 0
	.end_amdhsa_kernel

; __global__ void __launch_bounds__(512) fwd_kernel(Params p) {
;     extern __shared__ __attribute__((aligned(16))) unsigned char smem[];
amdhsa.kernels:
  - .agpr_count:     0
    .args:
      - .offset:         0
        .size:           168
        .value_kind:     by_value
      - .offset:         168
        .size:           4
        .value_kind:     hidden_block_count_x
      - .offset:         172
        .size:           4
        .value_kind:     hidden_block_count_y
      - .offset:         176
        .size:           4
        .value_kind:     hidden_block_count_z
      - .offset:         180
        .size:           2
        .value_kind:     hidden_group_size_x
      - .offset:         182
        .size:           2
        .value_kind:     hidden_group_size_y
      - .offset:         184
        .size:           2
        .value_kind:     hidden_group_size_z
      - .offset:         186
        .size:           2
        .value_kind:     hidden_remainder_x
      - .offset:         188
        .size:           2
        .value_kind:     hidden_remainder_y
      - .offset:         190
        .size:           2
        .value_kind:     hidden_remainder_z
      - .offset:         208
        .size:           8
        .value_kind:     hidden_global_offset_x
      - .offset:         216
        .size:           8
        .value_kind:     hidden_global_offset_y
      - .offset:         224
        .size:           8
        .value_kind:     hidden_global_offset_z
      - .offset:         232
        .size:           2
        .value_kind:     hidden_grid_dims
      - .offset:         256
        .size:           8
        .value_kind:     hidden_multigrid_sync_arg
      - .offset:         288
        .size:           4
        .value_kind:     hidden_dynamic_lds_size
    .group_segment_fixed_size: 6144
    .kernarg_segment_align: 8
    .kernarg_segment_size: 424
    .language:       OpenCL C
    .language_version:
      - 2
      - 0
    .max_flat_workgroup_size: 512
    .name:           _Z10fwd_kernel6Params
    .private_segment_fixed_size: 0
    .sgpr_count:     105
    .sgpr_spill_count: 157
    .symbol:         _Z10fwd_kernel6Params.kd
    .uniform_work_group_size: 1
    .uses_dynamic_stack: false
    .vgpr_count:     254
    .vgpr_spill_count: 0
    .wavefront_size: 64
